# v29 + the 44 redundant s_waitcnt lgkmcnt(0) at GEMM MFMA-cluster heads removed (the same wait sits before the barrier)
# speedup vs baseline: 1.0101x; 1.0101x over previous
.LBB0_849:
	ds_read_b128 v[146:149], v155
	ds_read_b128 v[160:163], v155 offset:1024
	ds_read_b128 v[164:167], v155 offset:2048
	ds_read_b128 v[168:171], v155 offset:3072
	ds_read_b128 v[172:175], v156
	ds_read_b128 v[176:179], v156 offset:1024
	ds_read_b128 v[180:183], v156 offset:2048
	ds_read_b128 v[184:187], v156 offset:3072
	ds_read_b128 v[188:191], v157
	ds_read_b128 v[192:195], v157 offset:1024
	ds_read_b128 v[196:199], v157 offset:2048
	ds_read_b128 v[200:203], v157 offset:3072
	ds_read_b128 v[204:207], v157 offset:4096
	ds_read_b128 v[208:211], v157 offset:5120
	ds_read_b128 v[212:215], v157 offset:6144
	ds_read_b128 v[216:219], v157 offset:7168
	s_add_u32 s74, s72, 0xfff80080
	s_addc_u32 s75, s73, -1
	s_cmp_eq_u32 s85, 28
	s_cselect_b32 s77, s63, s75
	s_cselect_b32 s76, s69, s74
	s_cselect_b32 s75, s57, s84
	s_cselect_b32 s74, s71, s83
	v_lshl_add_u64 v[220:221], s[72:73], 0, v[138:139]
	s_add_i32 m0, s3, 0xc000
	s_nop 0
	global_load_lds_dwordx4 v[220:221], off
	v_lshl_add_u64 v[220:221], s[72:73], 0, v[140:141]
	s_add_i32 m0, s3, 0xe000
	s_nop 0
	global_load_lds_dwordx4 v[220:221], off
	s_waitcnt vmcnt(8)
	s_waitcnt lgkmcnt(0)
	s_barrier
	s_setprio 1
	v_mfma_f32_16x16x32_bf16 v[124:127], v[146:149], v[188:191], v[124:127]
	v_mfma_f32_16x16x32_bf16 v[120:123], v[164:167], v[188:191], v[120:123]
	v_mfma_f32_16x16x32_bf16 v[108:111], v[146:149], v[196:199], v[108:111]
	v_mfma_f32_16x16x32_bf16 v[104:107], v[164:167], v[196:199], v[104:107]
	v_mfma_f32_16x16x32_bf16 v[92:95], v[146:149], v[204:207], v[92:95]
	v_mfma_f32_16x16x32_bf16 v[88:91], v[164:167], v[204:207], v[88:91]
	v_mfma_f32_16x16x32_bf16 v[76:79], v[146:149], v[212:215], v[76:79]
	v_mfma_f32_16x16x32_bf16 v[72:75], v[164:167], v[212:215], v[72:75]
	v_mfma_f32_16x16x32_bf16 v[124:127], v[160:163], v[192:195], v[124:127]
	v_mfma_f32_16x16x32_bf16 v[120:123], v[168:171], v[192:195], v[120:123]
	v_mfma_f32_16x16x32_bf16 v[108:111], v[160:163], v[200:203], v[108:111]
	v_mfma_f32_16x16x32_bf16 v[104:107], v[168:171], v[200:203], v[104:107]
	v_mfma_f32_16x16x32_bf16 v[92:95], v[160:163], v[208:211], v[92:95]
	v_mfma_f32_16x16x32_bf16 v[88:91], v[168:171], v[208:211], v[88:91]
	v_mfma_f32_16x16x32_bf16 v[76:79], v[160:163], v[216:219], v[76:79]
	v_mfma_f32_16x16x32_bf16 v[72:75], v[168:171], v[216:219], v[72:75]
	v_mfma_f32_16x16x32_bf16 v[116:119], v[172:175], v[188:191], v[116:119]
	v_mfma_f32_16x16x32_bf16 v[112:115], v[180:183], v[188:191], v[112:115]
	v_mfma_f32_16x16x32_bf16 v[100:103], v[172:175], v[196:199], v[100:103]
	v_mfma_f32_16x16x32_bf16 v[96:99], v[180:183], v[196:199], v[96:99]
	v_mfma_f32_16x16x32_bf16 v[84:87], v[172:175], v[204:207], v[84:87]
	v_mfma_f32_16x16x32_bf16 v[80:83], v[180:183], v[204:207], v[80:83]
	v_mfma_f32_16x16x32_bf16 v[68:71], v[172:175], v[212:215], v[68:71]
	v_mfma_f32_16x16x32_bf16 v[64:67], v[180:183], v[212:215], v[64:67]
	v_mfma_f32_16x16x32_bf16 v[116:119], v[176:179], v[192:195], v[116:119]
	v_mfma_f32_16x16x32_bf16 v[112:115], v[184:187], v[192:195], v[112:115]
	v_mfma_f32_16x16x32_bf16 v[100:103], v[176:179], v[200:203], v[100:103]
	v_mfma_f32_16x16x32_bf16 v[96:99], v[184:187], v[200:203], v[96:99]
	v_mfma_f32_16x16x32_bf16 v[84:87], v[176:179], v[208:211], v[84:87]
	v_mfma_f32_16x16x32_bf16 v[80:83], v[184:187], v[208:211], v[80:83]
	v_mfma_f32_16x16x32_bf16 v[68:71], v[176:179], v[216:219], v[68:71]
	v_mfma_f32_16x16x32_bf16 v[64:67], v[184:187], v[216:219], v[64:67]
	s_barrier
	s_setprio 0
	ds_read_b128 v[188:191], v157 offset:16384
	ds_read_b128 v[192:195], v157 offset:17408
	ds_read_b128 v[196:199], v157 offset:18432
	ds_read_b128 v[200:203], v157 offset:19456
	ds_read_b128 v[204:207], v157 offset:20480
	ds_read_b128 v[208:211], v157 offset:21504
	ds_read_b128 v[212:215], v157 offset:22528
	ds_read_b128 v[216:219], v157 offset:23552
	s_add_i32 s86, s79, s94
	v_lshl_add_u64 v[220:221], s[74:75], 0, v[130:131]
	s_mov_b32 m0, s86
	s_nop 0
	global_load_lds_dwordx4 v[220:221], off
	s_add_i32 m0, s86, 0x2000
	s_add_u32 s86, s74, 0x80000
	v_lshl_add_u64 v[222:223], s[74:75], 0, v[134:135]
	s_addc_u32 s87, s75, 0
	s_add_i32 s88, s81, s94
	global_load_lds_dwordx4 v[222:223], off
	v_lshl_add_u64 v[224:225], s[86:87], 0, v[130:131]
	s_mov_b32 m0, s88
	v_lshl_add_u64 v[226:227], s[76:77], 0, v[132:133]
	global_load_lds_dwordx4 v[224:225], off
	v_lshl_add_u64 v[224:225], s[86:87], 0, v[134:135]
	s_add_i32 m0, s88, 0x2000
	s_nop 0
	global_load_lds_dwordx4 v[224:225], off
	v_lshl_add_u64 v[224:225], s[76:77], 0, v[128:129]
	s_mov_b32 m0, s3
	s_nop 0
	global_load_lds_dwordx4 v[224:225], off
	s_mov_b32 m0, s6
	s_nop 0
	global_load_lds_dwordx4 v[226:227], off
	s_waitcnt vmcnt(8)
	s_waitcnt lgkmcnt(0)
	s_barrier
	s_setprio 1
	v_mfma_f32_16x16x32_bf16 v[60:63], v[146:149], v[188:191], v[60:63]
	v_mfma_f32_16x16x32_bf16 v[56:59], v[164:167], v[188:191], v[56:59]
	v_mfma_f32_16x16x32_bf16 v[44:47], v[146:149], v[196:199], v[44:47]
	v_mfma_f32_16x16x32_bf16 v[40:43], v[164:167], v[196:199], v[40:43]
	v_mfma_f32_16x16x32_bf16 v[28:31], v[146:149], v[204:207], v[28:31]
	v_mfma_f32_16x16x32_bf16 v[24:27], v[164:167], v[204:207], v[24:27]
	v_mfma_f32_16x16x32_bf16 v[12:15], v[146:149], v[212:215], v[12:15]
	v_mfma_f32_16x16x32_bf16 v[8:11], v[164:167], v[212:215], v[8:11]
	v_mfma_f32_16x16x32_bf16 v[60:63], v[160:163], v[192:195], v[60:63]
	v_mfma_f32_16x16x32_bf16 v[56:59], v[168:171], v[192:195], v[56:59]
	v_mfma_f32_16x16x32_bf16 v[44:47], v[160:163], v[200:203], v[44:47]
	v_mfma_f32_16x16x32_bf16 v[40:43], v[168:171], v[200:203], v[40:43]
	v_mfma_f32_16x16x32_bf16 v[28:31], v[160:163], v[208:211], v[28:31]
	v_mfma_f32_16x16x32_bf16 v[24:27], v[168:171], v[208:211], v[24:27]
	v_mfma_f32_16x16x32_bf16 v[12:15], v[160:163], v[216:219], v[12:15]
	v_mfma_f32_16x16x32_bf16 v[8:11], v[168:171], v[216:219], v[8:11]
	v_mfma_f32_16x16x32_bf16 v[52:55], v[172:175], v[188:191], v[52:55]
	v_mfma_f32_16x16x32_bf16 v[48:51], v[180:183], v[188:191], v[48:51]
	v_mfma_f32_16x16x32_bf16 v[36:39], v[172:175], v[196:199], v[36:39]
	v_mfma_f32_16x16x32_bf16 v[32:35], v[180:183], v[196:199], v[32:35]
	v_mfma_f32_16x16x32_bf16 v[20:23], v[172:175], v[204:207], v[20:23]
	v_mfma_f32_16x16x32_bf16 v[16:19], v[180:183], v[204:207], v[16:19]
	v_mfma_f32_16x16x32_bf16 v[4:7], v[172:175], v[212:215], v[4:7]
	v_mfma_f32_16x16x32_bf16 v[0:3], v[180:183], v[212:215], v[0:3]
	v_mfma_f32_16x16x32_bf16 v[52:55], v[176:179], v[192:195], v[52:55]
	v_mfma_f32_16x16x32_bf16 v[48:51], v[184:187], v[192:195], v[48:51]
	v_mfma_f32_16x16x32_bf16 v[36:39], v[176:179], v[200:203], v[36:39]
	v_mfma_f32_16x16x32_bf16 v[32:35], v[184:187], v[200:203], v[32:35]
	v_mfma_f32_16x16x32_bf16 v[20:23], v[176:179], v[208:211], v[20:23]
	v_mfma_f32_16x16x32_bf16 v[16:19], v[184:187], v[208:211], v[16:19]
	v_mfma_f32_16x16x32_bf16 v[4:7], v[176:179], v[216:219], v[4:7]
	v_mfma_f32_16x16x32_bf16 v[0:3], v[184:187], v[216:219], v[0:3]
	s_barrier
	s_setprio 0
	s_add_i32 s86, 0, 0x18000
	v_add_u32_e32 v159, s86, v151
	ds_read_b128 v[146:149], v159
	ds_read_b128 v[160:163], v159 offset:1024
	ds_read_b128 v[164:167], v159 offset:2048
	ds_read_b128 v[168:171], v159 offset:3072
	s_add_i32 s87, 0, 0x1c000
	v_add_u32_e32 v159, s87, v151
	ds_read_b128 v[172:175], v159
	ds_read_b128 v[176:179], v159 offset:1024
	ds_read_b128 v[180:183], v159 offset:2048
	ds_read_b128 v[184:187], v159 offset:3072
	ds_read_b128 v[188:191], v157 offset:32768
	ds_read_b128 v[192:195], v157 offset:33792
	ds_read_b128 v[196:199], v157 offset:34816
	ds_read_b128 v[200:203], v157 offset:35840
	ds_read_b128 v[204:207], v157 offset:36864
	ds_read_b128 v[208:211], v157 offset:37888
	ds_read_b128 v[212:215], v157 offset:38912
	ds_read_b128 v[216:219], v157 offset:39936
	s_add_u32 s76, s76, 0x80000
	s_addc_u32 s77, s77, 0
	s_mov_b32 m0, s7
	v_lshl_add_u64 v[228:229], s[76:77], 0, v[128:129]
	global_load_lds_dwordx4 v[228:229], off
	v_lshl_add_u64 v[228:229], s[76:77], 0, v[132:133]
	s_mov_b32 m0, s29
	s_nop 0
	global_load_lds_dwordx4 v[228:229], off
	s_waitcnt vmcnt(8)
	s_waitcnt lgkmcnt(0)
	s_barrier
	s_setprio 1
	v_mfma_f32_16x16x32_bf16 v[124:127], v[146:149], v[188:191], v[124:127]
	v_mfma_f32_16x16x32_bf16 v[120:123], v[164:167], v[188:191], v[120:123]
	v_mfma_f32_16x16x32_bf16 v[108:111], v[146:149], v[196:199], v[108:111]
	v_mfma_f32_16x16x32_bf16 v[104:107], v[164:167], v[196:199], v[104:107]
	v_mfma_f32_16x16x32_bf16 v[92:95], v[146:149], v[204:207], v[92:95]
	v_mfma_f32_16x16x32_bf16 v[88:91], v[164:167], v[204:207], v[88:91]
	v_mfma_f32_16x16x32_bf16 v[76:79], v[146:149], v[212:215], v[76:79]
	v_mfma_f32_16x16x32_bf16 v[72:75], v[164:167], v[212:215], v[72:75]
	v_mfma_f32_16x16x32_bf16 v[124:127], v[160:163], v[192:195], v[124:127]
	v_mfma_f32_16x16x32_bf16 v[120:123], v[168:171], v[192:195], v[120:123]
	v_mfma_f32_16x16x32_bf16 v[108:111], v[160:163], v[200:203], v[108:111]
	v_mfma_f32_16x16x32_bf16 v[104:107], v[168:171], v[200:203], v[104:107]
	v_mfma_f32_16x16x32_bf16 v[92:95], v[160:163], v[208:211], v[92:95]
	v_mfma_f32_16x16x32_bf16 v[88:91], v[168:171], v[208:211], v[88:91]
	v_mfma_f32_16x16x32_bf16 v[76:79], v[160:163], v[216:219], v[76:79]
	v_mfma_f32_16x16x32_bf16 v[72:75], v[168:171], v[216:219], v[72:75]
	v_mfma_f32_16x16x32_bf16 v[116:119], v[172:175], v[188:191], v[116:119]
	v_mfma_f32_16x16x32_bf16 v[112:115], v[180:183], v[188:191], v[112:115]
	v_mfma_f32_16x16x32_bf16 v[100:103], v[172:175], v[196:199], v[100:103]
	v_mfma_f32_16x16x32_bf16 v[96:99], v[180:183], v[196:199], v[96:99]
	v_mfma_f32_16x16x32_bf16 v[84:87], v[172:175], v[204:207], v[84:87]
	v_mfma_f32_16x16x32_bf16 v[80:83], v[180:183], v[204:207], v[80:83]
	v_mfma_f32_16x16x32_bf16 v[68:71], v[172:175], v[212:215], v[68:71]
	v_mfma_f32_16x16x32_bf16 v[64:67], v[180:183], v[212:215], v[64:67]
	v_mfma_f32_16x16x32_bf16 v[116:119], v[176:179], v[192:195], v[116:119]
	v_mfma_f32_16x16x32_bf16 v[112:115], v[184:187], v[192:195], v[112:115]
	v_mfma_f32_16x16x32_bf16 v[100:103], v[176:179], v[200:203], v[100:103]
	v_mfma_f32_16x16x32_bf16 v[96:99], v[184:187], v[200:203], v[96:99]
	v_mfma_f32_16x16x32_bf16 v[84:87], v[176:179], v[208:211], v[84:87]
	v_mfma_f32_16x16x32_bf16 v[80:83], v[184:187], v[208:211], v[80:83]
	v_mfma_f32_16x16x32_bf16 v[68:71], v[176:179], v[216:219], v[68:71]
	v_mfma_f32_16x16x32_bf16 v[64:67], v[184:187], v[216:219], v[64:67]
	s_barrier
	s_setprio 0
	ds_read_b128 v[188:191], v157 offset:49152
	ds_read_b128 v[192:195], v157 offset:50176
	ds_read_b128 v[196:199], v157 offset:51200
	ds_read_b128 v[200:203], v157 offset:52224
	ds_read_b128 v[204:207], v157 offset:53248
	ds_read_b128 v[208:211], v157 offset:54272
	ds_read_b128 v[212:215], v157 offset:55296
	ds_read_b128 v[216:219], v157 offset:56320
	s_add_i32 s76, s86, s94
	v_lshl_add_u64 v[220:221], v[220:221], 0, s[18:19]
	s_mov_b32 m0, s76
	s_nop 0
	global_load_lds_dwordx4 v[220:221], off
	s_add_i32 m0, s76, 0x2000
	s_add_u32 s74, s74, 0x80080
	v_lshl_add_u64 v[220:221], v[222:223], 0, s[18:19]
	s_addc_u32 s75, s75, 0
	s_add_i32 s76, s87, s94
	global_load_lds_dwordx4 v[220:221], off
	v_lshl_add_u64 v[220:221], s[74:75], 0, v[130:131]
	s_mov_b32 m0, s76
	s_nop 0
	global_load_lds_dwordx4 v[220:221], off
	v_lshl_add_u64 v[220:221], s[74:75], 0, v[134:135]
	s_add_i32 m0, s76, 0x2000
	s_nop 0
	global_load_lds_dwordx4 v[220:221], off
	v_lshl_add_u64 v[220:221], v[224:225], 0, s[18:19]
	s_mov_b32 m0, s34
	s_nop 0
	global_load_lds_dwordx4 v[220:221], off
	v_lshl_add_u64 v[220:221], v[226:227], 0, s[18:19]
	s_mov_b32 m0, s35
	s_nop 0
	global_load_lds_dwordx4 v[220:221], off
	s_waitcnt vmcnt(8)
	s_waitcnt lgkmcnt(0)
	s_barrier
	s_setprio 1
	v_mfma_f32_16x16x32_bf16 v[60:63], v[146:149], v[188:191], v[60:63]
	v_mfma_f32_16x16x32_bf16 v[56:59], v[164:167], v[188:191], v[56:59]
	v_mfma_f32_16x16x32_bf16 v[44:47], v[146:149], v[196:199], v[44:47]
	v_mfma_f32_16x16x32_bf16 v[40:43], v[164:167], v[196:199], v[40:43]
	v_mfma_f32_16x16x32_bf16 v[28:31], v[146:149], v[204:207], v[28:31]
	v_mfma_f32_16x16x32_bf16 v[24:27], v[164:167], v[204:207], v[24:27]
	v_mfma_f32_16x16x32_bf16 v[12:15], v[146:149], v[212:215], v[12:15]
	v_mfma_f32_16x16x32_bf16 v[8:11], v[164:167], v[212:215], v[8:11]
	v_mfma_f32_16x16x32_bf16 v[60:63], v[160:163], v[192:195], v[60:63]
	v_mfma_f32_16x16x32_bf16 v[56:59], v[168:171], v[192:195], v[56:59]
	v_mfma_f32_16x16x32_bf16 v[44:47], v[160:163], v[200:203], v[44:47]
	v_mfma_f32_16x16x32_bf16 v[40:43], v[168:171], v[200:203], v[40:43]
	v_mfma_f32_16x16x32_bf16 v[28:31], v[160:163], v[208:211], v[28:31]
	v_mfma_f32_16x16x32_bf16 v[24:27], v[168:171], v[208:211], v[24:27]
	v_mfma_f32_16x16x32_bf16 v[12:15], v[160:163], v[216:219], v[12:15]
	v_mfma_f32_16x16x32_bf16 v[8:11], v[168:171], v[216:219], v[8:11]
	v_mfma_f32_16x16x32_bf16 v[52:55], v[172:175], v[188:191], v[52:55]
	v_mfma_f32_16x16x32_bf16 v[48:51], v[180:183], v[188:191], v[48:51]
	v_mfma_f32_16x16x32_bf16 v[36:39], v[172:175], v[196:199], v[36:39]
	v_mfma_f32_16x16x32_bf16 v[32:35], v[180:183], v[196:199], v[32:35]
	v_mfma_f32_16x16x32_bf16 v[20:23], v[172:175], v[204:207], v[20:23]
	v_mfma_f32_16x16x32_bf16 v[16:19], v[180:183], v[204:207], v[16:19]
	v_mfma_f32_16x16x32_bf16 v[4:7], v[172:175], v[212:215], v[4:7]
	v_mfma_f32_16x16x32_bf16 v[0:3], v[180:183], v[212:215], v[0:3]
	v_mfma_f32_16x16x32_bf16 v[52:55], v[176:179], v[192:195], v[52:55]
	v_mfma_f32_16x16x32_bf16 v[48:51], v[184:187], v[192:195], v[48:51]
	v_mfma_f32_16x16x32_bf16 v[36:39], v[176:179], v[200:203], v[36:39]
	v_mfma_f32_16x16x32_bf16 v[32:35], v[184:187], v[200:203], v[32:35]
	v_mfma_f32_16x16x32_bf16 v[20:23], v[176:179], v[208:211], v[20:23]
	v_mfma_f32_16x16x32_bf16 v[16:19], v[184:187], v[208:211], v[16:19]
	v_mfma_f32_16x16x32_bf16 v[4:7], v[176:179], v[216:219], v[4:7]
	v_mfma_f32_16x16x32_bf16 v[0:3], v[184:187], v[216:219], v[0:3]
	s_barrier
	s_setprio 0
	s_add_i32 s85, s85, 2
	s_add_u32 s72, s72, 0x100
	s_addc_u32 s73, s73, 0
	s_add_u32 s83, s83, 0x100
	s_addc_u32 s84, s84, 0
	s_cmp_gt_u32 s85, 29
	s_cbranch_scc0 .LBB0_849
	s_and_b64 vcc, exec, s[20:21]
	s_cbranch_vccz .LBB0_852
	s_barrier

.LBB0_946:
	ds_read_b128 v[148:151], v143
	ds_read_b128 v[152:155], v143 offset:1024
	ds_read_b128 v[156:159], v143 offset:2048
	ds_read_b128 v[160:163], v143 offset:3072
	ds_read_b128 v[164:167], v144
	ds_read_b128 v[168:171], v144 offset:1024
	ds_read_b128 v[172:175], v144 offset:2048
	ds_read_b128 v[176:179], v144 offset:3072
	ds_read_b128 v[180:183], v145
	ds_read_b128 v[184:187], v145 offset:1024
	ds_read_b128 v[188:191], v145 offset:2048
	ds_read_b128 v[192:195], v145 offset:3072
	ds_read_b128 v[196:199], v145 offset:4096
	ds_read_b128 v[200:203], v145 offset:5120
	ds_read_b128 v[204:207], v145 offset:6144
	ds_read_b128 v[208:211], v145 offset:7168
	s_add_u32 s18, s14, s16
	s_addc_u32 s19, s15, s17
	s_add_u32 s18, s18, 0x7498100
	s_addc_u32 s19, s19, 0
	s_add_u32 s20, s24, s16
	s_addc_u32 s21, s25, s17
	s_add_u32 s69, s20, 0x1308100
	s_addc_u32 s70, s21, 0
	s_cmpk_eq_i32 s16, 0xf00
	s_cselect_b32 s21, s11, s19
	s_cselect_b32 s20, s10, s18
	s_cselect_b32 s19, s9, s70
	s_cselect_b32 s18, s8, s69
	s_mov_b32 m0, s46
	v_lshl_add_u64 v[212:213], v[136:137], 0, s[16:17]
	global_load_lds_dwordx4 v[212:213], off
	v_lshl_add_u64 v[212:213], v[138:139], 0, s[16:17]
	s_mov_b32 m0, s56
	s_nop 0
	global_load_lds_dwordx4 v[212:213], off
	s_waitcnt vmcnt(8)
	s_waitcnt lgkmcnt(0)
	s_barrier
	s_setprio 1
	v_mfma_f32_16x16x32_bf16 v[124:127], v[148:151], v[180:183], v[124:127]
	v_mfma_f32_16x16x32_bf16 v[120:123], v[156:159], v[180:183], v[120:123]
	v_mfma_f32_16x16x32_bf16 v[108:111], v[148:151], v[188:191], v[108:111]
	v_mfma_f32_16x16x32_bf16 v[104:107], v[156:159], v[188:191], v[104:107]
	v_mfma_f32_16x16x32_bf16 v[92:95], v[148:151], v[196:199], v[92:95]
	v_mfma_f32_16x16x32_bf16 v[88:91], v[156:159], v[196:199], v[88:91]
	v_mfma_f32_16x16x32_bf16 v[76:79], v[148:151], v[204:207], v[76:79]
	v_mfma_f32_16x16x32_bf16 v[72:75], v[156:159], v[204:207], v[72:75]
	v_mfma_f32_16x16x32_bf16 v[124:127], v[152:155], v[184:187], v[124:127]
	v_mfma_f32_16x16x32_bf16 v[120:123], v[160:163], v[184:187], v[120:123]
	v_mfma_f32_16x16x32_bf16 v[108:111], v[152:155], v[192:195], v[108:111]
	v_mfma_f32_16x16x32_bf16 v[104:107], v[160:163], v[192:195], v[104:107]
	v_mfma_f32_16x16x32_bf16 v[92:95], v[152:155], v[200:203], v[92:95]
	v_mfma_f32_16x16x32_bf16 v[88:91], v[160:163], v[200:203], v[88:91]
	v_mfma_f32_16x16x32_bf16 v[76:79], v[152:155], v[208:211], v[76:79]
	v_mfma_f32_16x16x32_bf16 v[72:75], v[160:163], v[208:211], v[72:75]
	v_mfma_f32_16x16x32_bf16 v[116:119], v[164:167], v[180:183], v[116:119]
	v_mfma_f32_16x16x32_bf16 v[112:115], v[172:175], v[180:183], v[112:115]
	v_mfma_f32_16x16x32_bf16 v[100:103], v[164:167], v[188:191], v[100:103]
	v_mfma_f32_16x16x32_bf16 v[96:99], v[172:175], v[188:191], v[96:99]
	v_mfma_f32_16x16x32_bf16 v[84:87], v[164:167], v[196:199], v[84:87]
	v_mfma_f32_16x16x32_bf16 v[80:83], v[172:175], v[196:199], v[80:83]
	v_mfma_f32_16x16x32_bf16 v[68:71], v[164:167], v[204:207], v[68:71]
	v_mfma_f32_16x16x32_bf16 v[64:67], v[172:175], v[204:207], v[64:67]
	v_mfma_f32_16x16x32_bf16 v[116:119], v[168:171], v[184:187], v[116:119]
	v_mfma_f32_16x16x32_bf16 v[112:115], v[176:179], v[184:187], v[112:115]
	v_mfma_f32_16x16x32_bf16 v[100:103], v[168:171], v[192:195], v[100:103]
	v_mfma_f32_16x16x32_bf16 v[96:99], v[176:179], v[192:195], v[96:99]
	v_mfma_f32_16x16x32_bf16 v[84:87], v[168:171], v[200:203], v[84:87]
	v_mfma_f32_16x16x32_bf16 v[80:83], v[176:179], v[200:203], v[80:83]
	v_mfma_f32_16x16x32_bf16 v[68:71], v[168:171], v[208:211], v[68:71]
	v_mfma_f32_16x16x32_bf16 v[64:67], v[176:179], v[208:211], v[64:67]
	s_barrier
	s_setprio 0
	ds_read_b128 v[180:183], v145 offset:16384
	ds_read_b128 v[184:187], v145 offset:17408
	ds_read_b128 v[188:191], v145 offset:18432
	ds_read_b128 v[192:195], v145 offset:19456
	ds_read_b128 v[196:199], v145 offset:20480
	ds_read_b128 v[200:203], v145 offset:21504
	ds_read_b128 v[204:207], v145 offset:22528
	ds_read_b128 v[208:211], v145 offset:23552
	s_mov_b32 m0, s57
	v_lshl_add_u64 v[212:213], s[18:19], 0, v[132:133]
	s_add_u32 s70, s18, 0x80000
	global_load_lds_dwordx4 v[212:213], off
	v_lshl_add_u64 v[214:215], s[18:19], 0, v[128:129]
	s_mov_b32 m0, s62
	s_addc_u32 s71, s19, 0
	global_load_lds_dwordx4 v[214:215], off
	v_lshl_add_u64 v[216:217], s[70:71], 0, v[132:133]
	s_mov_b32 m0, s63
	v_lshl_add_u64 v[218:219], s[20:21], 0, v[130:131]
	global_load_lds_dwordx4 v[216:217], off
	v_lshl_add_u64 v[216:217], s[70:71], 0, v[128:129]
	s_mov_b32 m0, s64
	s_nop 0
	global_load_lds_dwordx4 v[216:217], off
	v_lshl_add_u64 v[216:217], s[20:21], 0, v[134:135]
	s_mov_b32 m0, s3
	s_nop 0
	global_load_lds_dwordx4 v[216:217], off
	s_mov_b32 m0, s6
	s_nop 0
	global_load_lds_dwordx4 v[218:219], off
	s_waitcnt vmcnt(8)
	s_waitcnt lgkmcnt(0)
	s_barrier
	s_setprio 1
	v_mfma_f32_16x16x32_bf16 v[60:63], v[148:151], v[180:183], v[60:63]
	v_mfma_f32_16x16x32_bf16 v[56:59], v[156:159], v[180:183], v[56:59]
	v_mfma_f32_16x16x32_bf16 v[44:47], v[148:151], v[188:191], v[44:47]
	v_mfma_f32_16x16x32_bf16 v[40:43], v[156:159], v[188:191], v[40:43]
	v_mfma_f32_16x16x32_bf16 v[28:31], v[148:151], v[196:199], v[28:31]
	v_mfma_f32_16x16x32_bf16 v[24:27], v[156:159], v[196:199], v[24:27]
	v_mfma_f32_16x16x32_bf16 v[12:15], v[148:151], v[204:207], v[12:15]
	v_mfma_f32_16x16x32_bf16 v[8:11], v[156:159], v[204:207], v[8:11]
	v_mfma_f32_16x16x32_bf16 v[60:63], v[152:155], v[184:187], v[60:63]
	v_mfma_f32_16x16x32_bf16 v[56:59], v[160:163], v[184:187], v[56:59]
	v_mfma_f32_16x16x32_bf16 v[44:47], v[152:155], v[192:195], v[44:47]
	v_mfma_f32_16x16x32_bf16 v[40:43], v[160:163], v[192:195], v[40:43]
	v_mfma_f32_16x16x32_bf16 v[28:31], v[152:155], v[200:203], v[28:31]
	v_mfma_f32_16x16x32_bf16 v[24:27], v[160:163], v[200:203], v[24:27]
	v_mfma_f32_16x16x32_bf16 v[12:15], v[152:155], v[208:211], v[12:15]
	v_mfma_f32_16x16x32_bf16 v[8:11], v[160:163], v[208:211], v[8:11]
	v_mfma_f32_16x16x32_bf16 v[52:55], v[164:167], v[180:183], v[52:55]
	v_mfma_f32_16x16x32_bf16 v[48:51], v[172:175], v[180:183], v[48:51]
	v_mfma_f32_16x16x32_bf16 v[36:39], v[164:167], v[188:191], v[36:39]
	v_mfma_f32_16x16x32_bf16 v[32:35], v[172:175], v[188:191], v[32:35]
	v_mfma_f32_16x16x32_bf16 v[20:23], v[164:167], v[196:199], v[20:23]
	v_mfma_f32_16x16x32_bf16 v[16:19], v[172:175], v[196:199], v[16:19]
	v_mfma_f32_16x16x32_bf16 v[4:7], v[164:167], v[204:207], v[4:7]
	v_mfma_f32_16x16x32_bf16 v[0:3], v[172:175], v[204:207], v[0:3]
	v_mfma_f32_16x16x32_bf16 v[52:55], v[168:171], v[184:187], v[52:55]
	v_mfma_f32_16x16x32_bf16 v[48:51], v[176:179], v[184:187], v[48:51]
	v_mfma_f32_16x16x32_bf16 v[36:39], v[168:171], v[192:195], v[36:39]
	v_mfma_f32_16x16x32_bf16 v[32:35], v[176:179], v[192:195], v[32:35]
	v_mfma_f32_16x16x32_bf16 v[20:23], v[168:171], v[200:203], v[20:23]
	v_mfma_f32_16x16x32_bf16 v[16:19], v[176:179], v[200:203], v[16:19]
	v_mfma_f32_16x16x32_bf16 v[4:7], v[168:171], v[208:211], v[4:7]
	v_mfma_f32_16x16x32_bf16 v[0:3], v[176:179], v[208:211], v[0:3]
	s_barrier
	s_setprio 0
	ds_read_b128 v[148:151], v146
	ds_read_b128 v[152:155], v146 offset:1024
	ds_read_b128 v[156:159], v146 offset:2048
	ds_read_b128 v[160:163], v146 offset:3072
	ds_read_b128 v[164:167], v147
	ds_read_b128 v[168:171], v147 offset:1024
	ds_read_b128 v[172:175], v147 offset:2048
	ds_read_b128 v[176:179], v147 offset:3072
	ds_read_b128 v[180:183], v145 offset:32768
	ds_read_b128 v[184:187], v145 offset:33792
	ds_read_b128 v[188:191], v145 offset:34816
	ds_read_b128 v[192:195], v145 offset:35840
	ds_read_b128 v[196:199], v145 offset:36864
	ds_read_b128 v[200:203], v145 offset:37888
	ds_read_b128 v[204:207], v145 offset:38912
	ds_read_b128 v[208:211], v145 offset:39936
	s_add_u32 s20, s20, 0x80000
	s_addc_u32 s21, s21, 0
	s_mov_b32 m0, s7
	v_lshl_add_u64 v[220:221], s[20:21], 0, v[134:135]
	global_load_lds_dwordx4 v[220:221], off
	v_lshl_add_u64 v[220:221], s[20:21], 0, v[130:131]
	s_mov_b32 m0, s29
	s_nop 0
	global_load_lds_dwordx4 v[220:221], off
	s_waitcnt vmcnt(8)
	s_waitcnt lgkmcnt(0)
	s_barrier
	s_setprio 1
	v_mfma_f32_16x16x32_bf16 v[124:127], v[148:151], v[180:183], v[124:127]
	v_mfma_f32_16x16x32_bf16 v[120:123], v[156:159], v[180:183], v[120:123]
	v_mfma_f32_16x16x32_bf16 v[108:111], v[148:151], v[188:191], v[108:111]
	v_mfma_f32_16x16x32_bf16 v[104:107], v[156:159], v[188:191], v[104:107]
	v_mfma_f32_16x16x32_bf16 v[92:95], v[148:151], v[196:199], v[92:95]
	v_mfma_f32_16x16x32_bf16 v[88:91], v[156:159], v[196:199], v[88:91]
	v_mfma_f32_16x16x32_bf16 v[76:79], v[148:151], v[204:207], v[76:79]
	v_mfma_f32_16x16x32_bf16 v[72:75], v[156:159], v[204:207], v[72:75]
	v_mfma_f32_16x16x32_bf16 v[124:127], v[152:155], v[184:187], v[124:127]
	v_mfma_f32_16x16x32_bf16 v[120:123], v[160:163], v[184:187], v[120:123]
	v_mfma_f32_16x16x32_bf16 v[108:111], v[152:155], v[192:195], v[108:111]
	v_mfma_f32_16x16x32_bf16 v[104:107], v[160:163], v[192:195], v[104:107]
	v_mfma_f32_16x16x32_bf16 v[92:95], v[152:155], v[200:203], v[92:95]
	v_mfma_f32_16x16x32_bf16 v[88:91], v[160:163], v[200:203], v[88:91]
	v_mfma_f32_16x16x32_bf16 v[76:79], v[152:155], v[208:211], v[76:79]
	v_mfma_f32_16x16x32_bf16 v[72:75], v[160:163], v[208:211], v[72:75]
	v_mfma_f32_16x16x32_bf16 v[116:119], v[164:167], v[180:183], v[116:119]
	v_mfma_f32_16x16x32_bf16 v[112:115], v[172:175], v[180:183], v[112:115]
	v_mfma_f32_16x16x32_bf16 v[100:103], v[164:167], v[188:191], v[100:103]
	v_mfma_f32_16x16x32_bf16 v[96:99], v[172:175], v[188:191], v[96:99]
	v_mfma_f32_16x16x32_bf16 v[84:87], v[164:167], v[196:199], v[84:87]
	v_mfma_f32_16x16x32_bf16 v[80:83], v[172:175], v[196:199], v[80:83]
	v_mfma_f32_16x16x32_bf16 v[68:71], v[164:167], v[204:207], v[68:71]
	v_mfma_f32_16x16x32_bf16 v[64:67], v[172:175], v[204:207], v[64:67]
	v_mfma_f32_16x16x32_bf16 v[116:119], v[168:171], v[184:187], v[116:119]
	v_mfma_f32_16x16x32_bf16 v[112:115], v[176:179], v[184:187], v[112:115]
	v_mfma_f32_16x16x32_bf16 v[100:103], v[168:171], v[192:195], v[100:103]
	v_mfma_f32_16x16x32_bf16 v[96:99], v[176:179], v[192:195], v[96:99]
	v_mfma_f32_16x16x32_bf16 v[84:87], v[168:171], v[200:203], v[84:87]
	v_mfma_f32_16x16x32_bf16 v[80:83], v[176:179], v[200:203], v[80:83]
	v_mfma_f32_16x16x32_bf16 v[68:71], v[168:171], v[208:211], v[68:71]
	v_mfma_f32_16x16x32_bf16 v[64:67], v[176:179], v[208:211], v[64:67]
	s_barrier
	s_setprio 0
	ds_read_b128 v[180:183], v145 offset:49152
	ds_read_b128 v[184:187], v145 offset:50176
	ds_read_b128 v[188:191], v145 offset:51200
	ds_read_b128 v[192:195], v145 offset:52224
	ds_read_b128 v[196:199], v145 offset:53248
	ds_read_b128 v[200:203], v145 offset:54272
	ds_read_b128 v[204:207], v145 offset:55296
	ds_read_b128 v[208:211], v145 offset:56320
	s_mov_b32 m0, s65
	v_lshl_add_u64 v[212:213], v[212:213], 0, s[12:13]
	s_add_u32 s18, s18, 0x80080
	global_load_lds_dwordx4 v[212:213], off
	v_lshl_add_u64 v[212:213], v[214:215], 0, s[12:13]
	s_mov_b32 m0, s66
	s_addc_u32 s19, s19, 0
	global_load_lds_dwordx4 v[212:213], off
	v_lshl_add_u64 v[212:213], s[18:19], 0, v[132:133]
	s_mov_b32 m0, s67
	s_nop 0
	global_load_lds_dwordx4 v[212:213], off
	v_lshl_add_u64 v[212:213], s[18:19], 0, v[128:129]
	s_mov_b32 m0, s68
	s_nop 0
	global_load_lds_dwordx4 v[212:213], off
	v_lshl_add_u64 v[212:213], v[216:217], 0, s[12:13]
	s_mov_b32 m0, s30
	s_nop 0
	global_load_lds_dwordx4 v[212:213], off
	v_lshl_add_u64 v[212:213], v[218:219], 0, s[12:13]
	s_mov_b32 m0, s34
	s_nop 0
	global_load_lds_dwordx4 v[212:213], off
	s_waitcnt vmcnt(8)
	s_waitcnt lgkmcnt(0)
	s_barrier
	s_setprio 1
	v_mfma_f32_16x16x32_bf16 v[60:63], v[148:151], v[180:183], v[60:63]
	v_mfma_f32_16x16x32_bf16 v[56:59], v[156:159], v[180:183], v[56:59]
	v_mfma_f32_16x16x32_bf16 v[44:47], v[148:151], v[188:191], v[44:47]
	v_mfma_f32_16x16x32_bf16 v[40:43], v[156:159], v[188:191], v[40:43]
	v_mfma_f32_16x16x32_bf16 v[28:31], v[148:151], v[196:199], v[28:31]
	v_mfma_f32_16x16x32_bf16 v[24:27], v[156:159], v[196:199], v[24:27]
	v_mfma_f32_16x16x32_bf16 v[12:15], v[148:151], v[204:207], v[12:15]
	v_mfma_f32_16x16x32_bf16 v[8:11], v[156:159], v[204:207], v[8:11]
	v_mfma_f32_16x16x32_bf16 v[60:63], v[152:155], v[184:187], v[60:63]
	v_mfma_f32_16x16x32_bf16 v[56:59], v[160:163], v[184:187], v[56:59]
	v_mfma_f32_16x16x32_bf16 v[44:47], v[152:155], v[192:195], v[44:47]
	v_mfma_f32_16x16x32_bf16 v[40:43], v[160:163], v[192:195], v[40:43]
	v_mfma_f32_16x16x32_bf16 v[28:31], v[152:155], v[200:203], v[28:31]
	v_mfma_f32_16x16x32_bf16 v[24:27], v[160:163], v[200:203], v[24:27]
	v_mfma_f32_16x16x32_bf16 v[12:15], v[152:155], v[208:211], v[12:15]
	v_mfma_f32_16x16x32_bf16 v[8:11], v[160:163], v[208:211], v[8:11]
	v_mfma_f32_16x16x32_bf16 v[52:55], v[164:167], v[180:183], v[52:55]
	v_mfma_f32_16x16x32_bf16 v[48:51], v[172:175], v[180:183], v[48:51]
	v_mfma_f32_16x16x32_bf16 v[36:39], v[164:167], v[188:191], v[36:39]
	v_mfma_f32_16x16x32_bf16 v[32:35], v[172:175], v[188:191], v[32:35]
	v_mfma_f32_16x16x32_bf16 v[20:23], v[164:167], v[196:199], v[20:23]
	v_mfma_f32_16x16x32_bf16 v[16:19], v[172:175], v[196:199], v[16:19]
	v_mfma_f32_16x16x32_bf16 v[4:7], v[164:167], v[204:207], v[4:7]
	v_mfma_f32_16x16x32_bf16 v[0:3], v[172:175], v[204:207], v[0:3]
	v_mfma_f32_16x16x32_bf16 v[52:55], v[168:171], v[184:187], v[52:55]
	v_mfma_f32_16x16x32_bf16 v[48:51], v[176:179], v[184:187], v[48:51]
	v_mfma_f32_16x16x32_bf16 v[36:39], v[168:171], v[192:195], v[36:39]
	v_mfma_f32_16x16x32_bf16 v[32:35], v[176:179], v[192:195], v[32:35]
	v_mfma_f32_16x16x32_bf16 v[20:23], v[168:171], v[200:203], v[20:23]
	v_mfma_f32_16x16x32_bf16 v[16:19], v[176:179], v[200:203], v[16:19]
	v_mfma_f32_16x16x32_bf16 v[4:7], v[168:171], v[208:211], v[4:7]
	v_mfma_f32_16x16x32_bf16 v[0:3], v[176:179], v[208:211], v[0:3]
	s_barrier
	s_setprio 0
	s_add_i32 s35, s35, 2
	s_add_u32 s16, s16, 0x100
	s_addc_u32 s17, s17, 0
	s_cmp_gt_u32 s35, 29
	s_cbranch_scc0 .LBB0_946
	s_cmpk_lt_u32 s80, 0x100
	s_cbranch_scc0 .LBB0_949
	s_barrier

.LBB0_1693:
	ds_read_b128 v[140:143], v149
	ds_read_b128 v[152:155], v149 offset:1024
	ds_read_b128 v[156:159], v149 offset:2048
	ds_read_b128 v[160:163], v149 offset:3072
	ds_read_b128 v[164:167], v150
	ds_read_b128 v[168:171], v150 offset:1024
	ds_read_b128 v[172:175], v150 offset:2048
	ds_read_b128 v[176:179], v150 offset:3072
	ds_read_b128 v[180:183], v151
	ds_read_b128 v[184:187], v151 offset:1024
	ds_read_b128 v[188:191], v151 offset:2048
	ds_read_b128 v[192:195], v151 offset:3072
	ds_read_b128 v[196:199], v151 offset:4096
	ds_read_b128 v[200:203], v151 offset:5120
	ds_read_b128 v[204:207], v151 offset:6144
	ds_read_b128 v[208:211], v151 offset:7168
	s_add_u32 s76, s74, 0xfff80080
	s_addc_u32 s77, s75, -1
	s_cmp_eq_u32 s86, 28
	s_cselect_b32 s79, s67, s77
	s_cselect_b32 s78, s73, s76
	s_cselect_b32 s77, s65, s85
	s_cselect_b32 s76, s83, s84
	v_lshl_add_u64 v[212:213], s[74:75], 0, v[132:133]
	s_add_i32 m0, s6, 0xc000
	s_nop 0
	global_load_lds_dwordx4 v[212:213], off
	v_lshl_add_u64 v[212:213], s[74:75], 0, v[134:135]
	s_add_i32 m0, s6, 0xe000
	s_nop 0
	global_load_lds_dwordx4 v[212:213], off
	s_waitcnt vmcnt(8)
	s_waitcnt lgkmcnt(0)
	s_barrier
	s_setprio 1
	v_mfma_f32_16x16x32_bf16 v[124:127], v[140:143], v[180:183], v[124:127]
	v_mfma_f32_16x16x32_bf16 v[120:123], v[156:159], v[180:183], v[120:123]
	v_mfma_f32_16x16x32_bf16 v[108:111], v[140:143], v[188:191], v[108:111]
	v_mfma_f32_16x16x32_bf16 v[104:107], v[156:159], v[188:191], v[104:107]
	v_mfma_f32_16x16x32_bf16 v[92:95], v[140:143], v[196:199], v[92:95]
	v_mfma_f32_16x16x32_bf16 v[88:91], v[156:159], v[196:199], v[88:91]
	v_mfma_f32_16x16x32_bf16 v[76:79], v[140:143], v[204:207], v[76:79]
	v_mfma_f32_16x16x32_bf16 v[72:75], v[156:159], v[204:207], v[72:75]
	v_mfma_f32_16x16x32_bf16 v[124:127], v[152:155], v[184:187], v[124:127]
	v_mfma_f32_16x16x32_bf16 v[120:123], v[160:163], v[184:187], v[120:123]
	v_mfma_f32_16x16x32_bf16 v[108:111], v[152:155], v[192:195], v[108:111]
	v_mfma_f32_16x16x32_bf16 v[104:107], v[160:163], v[192:195], v[104:107]
	v_mfma_f32_16x16x32_bf16 v[92:95], v[152:155], v[200:203], v[92:95]
	v_mfma_f32_16x16x32_bf16 v[88:91], v[160:163], v[200:203], v[88:91]
	v_mfma_f32_16x16x32_bf16 v[76:79], v[152:155], v[208:211], v[76:79]
	v_mfma_f32_16x16x32_bf16 v[72:75], v[160:163], v[208:211], v[72:75]
	v_mfma_f32_16x16x32_bf16 v[116:119], v[164:167], v[180:183], v[116:119]
	v_mfma_f32_16x16x32_bf16 v[112:115], v[172:175], v[180:183], v[112:115]
	v_mfma_f32_16x16x32_bf16 v[100:103], v[164:167], v[188:191], v[100:103]
	v_mfma_f32_16x16x32_bf16 v[96:99], v[172:175], v[188:191], v[96:99]
	v_mfma_f32_16x16x32_bf16 v[84:87], v[164:167], v[196:199], v[84:87]
	v_mfma_f32_16x16x32_bf16 v[80:83], v[172:175], v[196:199], v[80:83]
	v_mfma_f32_16x16x32_bf16 v[68:71], v[164:167], v[204:207], v[68:71]
	v_mfma_f32_16x16x32_bf16 v[64:67], v[172:175], v[204:207], v[64:67]
	v_mfma_f32_16x16x32_bf16 v[116:119], v[168:171], v[184:187], v[116:119]
	v_mfma_f32_16x16x32_bf16 v[112:115], v[176:179], v[184:187], v[112:115]
	v_mfma_f32_16x16x32_bf16 v[100:103], v[168:171], v[192:195], v[100:103]
	v_mfma_f32_16x16x32_bf16 v[96:99], v[176:179], v[192:195], v[96:99]
	v_mfma_f32_16x16x32_bf16 v[84:87], v[168:171], v[200:203], v[84:87]
	v_mfma_f32_16x16x32_bf16 v[80:83], v[176:179], v[200:203], v[80:83]
	v_mfma_f32_16x16x32_bf16 v[68:71], v[168:171], v[208:211], v[68:71]
	v_mfma_f32_16x16x32_bf16 v[64:67], v[176:179], v[208:211], v[64:67]
	s_barrier
	s_setprio 0
	ds_read_b128 v[180:183], v151 offset:16384
	ds_read_b128 v[184:187], v151 offset:17408
	ds_read_b128 v[188:191], v151 offset:18432
	ds_read_b128 v[192:195], v151 offset:19456
	ds_read_b128 v[196:199], v151 offset:20480
	ds_read_b128 v[200:203], v151 offset:21504
	ds_read_b128 v[204:207], v151 offset:22528
	ds_read_b128 v[208:211], v151 offset:23552
	s_add_i32 s87, s57, s94
	v_lshl_add_u64 v[212:213], s[76:77], 0, v[128:129]
	s_mov_b32 m0, s87
	s_nop 0
	global_load_lds_dwordx4 v[212:213], off
	s_add_i32 m0, s87, 0x2000
	s_add_u32 s88, s76, 0x80000
	v_lshl_add_u64 v[214:215], s[76:77], 0, v[130:131]
	s_addc_u32 s89, s77, 0
	s_add_i32 s87, s81, s94
	global_load_lds_dwordx4 v[214:215], off
	v_lshl_add_u64 v[216:217], s[88:89], 0, v[128:129]
	s_mov_b32 m0, s87
	v_lshl_add_u64 v[218:219], s[78:79], 0, v[130:131]
	global_load_lds_dwordx4 v[216:217], off
	v_lshl_add_u64 v[216:217], s[88:89], 0, v[130:131]
	s_add_i32 m0, s87, 0x2000
	s_nop 0
	global_load_lds_dwordx4 v[216:217], off
	v_lshl_add_u64 v[216:217], s[78:79], 0, v[128:129]
	s_mov_b32 m0, s6
	s_nop 0
	global_load_lds_dwordx4 v[216:217], off
	s_mov_b32 m0, s7
	s_nop 0
	global_load_lds_dwordx4 v[218:219], off
	s_waitcnt vmcnt(8)
	s_waitcnt lgkmcnt(0)
	s_barrier
	s_setprio 1
	v_mfma_f32_16x16x32_bf16 v[60:63], v[140:143], v[180:183], v[60:63]
	v_mfma_f32_16x16x32_bf16 v[56:59], v[156:159], v[180:183], v[56:59]
	v_mfma_f32_16x16x32_bf16 v[44:47], v[140:143], v[188:191], v[44:47]
	v_mfma_f32_16x16x32_bf16 v[40:43], v[156:159], v[188:191], v[40:43]
	v_mfma_f32_16x16x32_bf16 v[28:31], v[140:143], v[196:199], v[28:31]
	v_mfma_f32_16x16x32_bf16 v[24:27], v[156:159], v[196:199], v[24:27]
	v_mfma_f32_16x16x32_bf16 v[12:15], v[140:143], v[204:207], v[12:15]
	v_mfma_f32_16x16x32_bf16 v[8:11], v[156:159], v[204:207], v[8:11]
	v_mfma_f32_16x16x32_bf16 v[60:63], v[152:155], v[184:187], v[60:63]
	v_mfma_f32_16x16x32_bf16 v[56:59], v[160:163], v[184:187], v[56:59]
	v_mfma_f32_16x16x32_bf16 v[44:47], v[152:155], v[192:195], v[44:47]
	v_mfma_f32_16x16x32_bf16 v[40:43], v[160:163], v[192:195], v[40:43]
	v_mfma_f32_16x16x32_bf16 v[28:31], v[152:155], v[200:203], v[28:31]
	v_mfma_f32_16x16x32_bf16 v[24:27], v[160:163], v[200:203], v[24:27]
	v_mfma_f32_16x16x32_bf16 v[12:15], v[152:155], v[208:211], v[12:15]
	v_mfma_f32_16x16x32_bf16 v[8:11], v[160:163], v[208:211], v[8:11]
	v_mfma_f32_16x16x32_bf16 v[52:55], v[164:167], v[180:183], v[52:55]
	v_mfma_f32_16x16x32_bf16 v[48:51], v[172:175], v[180:183], v[48:51]
	v_mfma_f32_16x16x32_bf16 v[36:39], v[164:167], v[188:191], v[36:39]
	v_mfma_f32_16x16x32_bf16 v[32:35], v[172:175], v[188:191], v[32:35]
	v_mfma_f32_16x16x32_bf16 v[20:23], v[164:167], v[196:199], v[20:23]
	v_mfma_f32_16x16x32_bf16 v[16:19], v[172:175], v[196:199], v[16:19]
	v_mfma_f32_16x16x32_bf16 v[4:7], v[164:167], v[204:207], v[4:7]
	v_mfma_f32_16x16x32_bf16 v[0:3], v[172:175], v[204:207], v[0:3]
	v_mfma_f32_16x16x32_bf16 v[52:55], v[168:171], v[184:187], v[52:55]
	v_mfma_f32_16x16x32_bf16 v[48:51], v[176:179], v[184:187], v[48:51]
	v_mfma_f32_16x16x32_bf16 v[36:39], v[168:171], v[192:195], v[36:39]
	v_mfma_f32_16x16x32_bf16 v[32:35], v[176:179], v[192:195], v[32:35]
	v_mfma_f32_16x16x32_bf16 v[20:23], v[168:171], v[200:203], v[20:23]
	v_mfma_f32_16x16x32_bf16 v[16:19], v[176:179], v[200:203], v[16:19]
	v_mfma_f32_16x16x32_bf16 v[4:7], v[168:171], v[208:211], v[4:7]
	v_mfma_f32_16x16x32_bf16 v[0:3], v[176:179], v[208:211], v[0:3]
	s_barrier
	s_setprio 0
	s_add_i32 s87, 0, 0x18000
	s_add_i32 s88, 0, 0x1c000
	v_add_u32_e32 v160, s87, v145
	ds_read_b128 v[140:143], v160
	ds_read_b128 v[152:155], v160 offset:1024
	ds_read_b128 v[156:159], v160 offset:2048
	ds_read_b128 v[160:163], v160 offset:3072
	v_add_u32_e32 v176, s88, v145
	ds_read_b128 v[164:167], v176
	ds_read_b128 v[168:171], v176 offset:1024
	ds_read_b128 v[172:175], v176 offset:2048
	ds_read_b128 v[176:179], v176 offset:3072
	ds_read_b128 v[180:183], v151 offset:32768
	ds_read_b128 v[184:187], v151 offset:33792
	ds_read_b128 v[188:191], v151 offset:34816
	ds_read_b128 v[192:195], v151 offset:35840
	ds_read_b128 v[196:199], v151 offset:36864
	ds_read_b128 v[200:203], v151 offset:37888
	ds_read_b128 v[204:207], v151 offset:38912
	ds_read_b128 v[208:211], v151 offset:39936
	s_add_u32 s78, s78, 0x80000
	s_addc_u32 s79, s79, 0
	s_mov_b32 m0, s29
	v_lshl_add_u64 v[220:221], s[78:79], 0, v[128:129]
	global_load_lds_dwordx4 v[220:221], off
	v_lshl_add_u64 v[220:221], s[78:79], 0, v[130:131]
	s_mov_b32 m0, s30
	s_nop 0
	global_load_lds_dwordx4 v[220:221], off
	s_waitcnt vmcnt(8)
	s_waitcnt lgkmcnt(0)
	s_barrier
	s_setprio 1
	v_mfma_f32_16x16x32_bf16 v[124:127], v[140:143], v[180:183], v[124:127]
	v_mfma_f32_16x16x32_bf16 v[120:123], v[156:159], v[180:183], v[120:123]
	v_mfma_f32_16x16x32_bf16 v[108:111], v[140:143], v[188:191], v[108:111]
	v_mfma_f32_16x16x32_bf16 v[104:107], v[156:159], v[188:191], v[104:107]
	v_mfma_f32_16x16x32_bf16 v[92:95], v[140:143], v[196:199], v[92:95]
	v_mfma_f32_16x16x32_bf16 v[88:91], v[156:159], v[196:199], v[88:91]
	v_mfma_f32_16x16x32_bf16 v[76:79], v[140:143], v[204:207], v[76:79]
	v_mfma_f32_16x16x32_bf16 v[72:75], v[156:159], v[204:207], v[72:75]
	v_mfma_f32_16x16x32_bf16 v[124:127], v[152:155], v[184:187], v[124:127]
	v_mfma_f32_16x16x32_bf16 v[120:123], v[160:163], v[184:187], v[120:123]
	v_mfma_f32_16x16x32_bf16 v[108:111], v[152:155], v[192:195], v[108:111]
	v_mfma_f32_16x16x32_bf16 v[104:107], v[160:163], v[192:195], v[104:107]
	v_mfma_f32_16x16x32_bf16 v[92:95], v[152:155], v[200:203], v[92:95]
	v_mfma_f32_16x16x32_bf16 v[88:91], v[160:163], v[200:203], v[88:91]
	v_mfma_f32_16x16x32_bf16 v[76:79], v[152:155], v[208:211], v[76:79]
	v_mfma_f32_16x16x32_bf16 v[72:75], v[160:163], v[208:211], v[72:75]
	v_mfma_f32_16x16x32_bf16 v[116:119], v[164:167], v[180:183], v[116:119]
	v_mfma_f32_16x16x32_bf16 v[112:115], v[172:175], v[180:183], v[112:115]
	v_mfma_f32_16x16x32_bf16 v[100:103], v[164:167], v[188:191], v[100:103]
	v_mfma_f32_16x16x32_bf16 v[96:99], v[172:175], v[188:191], v[96:99]
	v_mfma_f32_16x16x32_bf16 v[84:87], v[164:167], v[196:199], v[84:87]
	v_mfma_f32_16x16x32_bf16 v[80:83], v[172:175], v[196:199], v[80:83]
	v_mfma_f32_16x16x32_bf16 v[68:71], v[164:167], v[204:207], v[68:71]
	v_mfma_f32_16x16x32_bf16 v[64:67], v[172:175], v[204:207], v[64:67]
	v_mfma_f32_16x16x32_bf16 v[116:119], v[168:171], v[184:187], v[116:119]
	v_mfma_f32_16x16x32_bf16 v[112:115], v[176:179], v[184:187], v[112:115]
	v_mfma_f32_16x16x32_bf16 v[100:103], v[168:171], v[192:195], v[100:103]
	v_mfma_f32_16x16x32_bf16 v[96:99], v[176:179], v[192:195], v[96:99]
	v_mfma_f32_16x16x32_bf16 v[84:87], v[168:171], v[200:203], v[84:87]
	v_mfma_f32_16x16x32_bf16 v[80:83], v[176:179], v[200:203], v[80:83]
	v_mfma_f32_16x16x32_bf16 v[68:71], v[168:171], v[208:211], v[68:71]
	v_mfma_f32_16x16x32_bf16 v[64:67], v[176:179], v[208:211], v[64:67]
	s_barrier
	s_setprio 0
	ds_read_b128 v[180:183], v151 offset:49152
	ds_read_b128 v[184:187], v151 offset:50176
	ds_read_b128 v[188:191], v151 offset:51200
	ds_read_b128 v[192:195], v151 offset:52224
	ds_read_b128 v[196:199], v151 offset:53248
	ds_read_b128 v[200:203], v151 offset:54272
	ds_read_b128 v[204:207], v151 offset:55296
	ds_read_b128 v[208:211], v151 offset:56320
	s_add_i32 s78, s87, s94
	v_lshl_add_u64 v[212:213], v[212:213], 0, s[58:59]
	s_mov_b32 m0, s78
	s_nop 0
	global_load_lds_dwordx4 v[212:213], off
	s_add_i32 m0, s78, 0x2000
	s_add_u32 s76, s76, 0x80080
	v_lshl_add_u64 v[212:213], v[214:215], 0, s[58:59]
	s_addc_u32 s77, s77, 0
	s_add_i32 s78, s88, s94
	global_load_lds_dwordx4 v[212:213], off
	v_lshl_add_u64 v[212:213], s[76:77], 0, v[128:129]
	s_mov_b32 m0, s78
	s_nop 0
	global_load_lds_dwordx4 v[212:213], off
	v_lshl_add_u64 v[212:213], s[76:77], 0, v[130:131]
	s_add_i32 m0, s78, 0x2000
	s_nop 0
	global_load_lds_dwordx4 v[212:213], off
	v_lshl_add_u64 v[212:213], v[216:217], 0, s[58:59]
	s_mov_b32 m0, s34
	s_nop 0
	global_load_lds_dwordx4 v[212:213], off
	v_lshl_add_u64 v[212:213], v[218:219], 0, s[58:59]
	s_mov_b32 m0, s35
	s_nop 0
	global_load_lds_dwordx4 v[212:213], off
	s_waitcnt vmcnt(8)
	s_waitcnt lgkmcnt(0)
	s_barrier
	s_setprio 1
	v_mfma_f32_16x16x32_bf16 v[60:63], v[140:143], v[180:183], v[60:63]
	v_mfma_f32_16x16x32_bf16 v[56:59], v[156:159], v[180:183], v[56:59]
	v_mfma_f32_16x16x32_bf16 v[44:47], v[140:143], v[188:191], v[44:47]
	v_mfma_f32_16x16x32_bf16 v[40:43], v[156:159], v[188:191], v[40:43]
	v_mfma_f32_16x16x32_bf16 v[28:31], v[140:143], v[196:199], v[28:31]
	v_mfma_f32_16x16x32_bf16 v[24:27], v[156:159], v[196:199], v[24:27]
	v_mfma_f32_16x16x32_bf16 v[12:15], v[140:143], v[204:207], v[12:15]
	v_mfma_f32_16x16x32_bf16 v[8:11], v[156:159], v[204:207], v[8:11]
	v_mfma_f32_16x16x32_bf16 v[60:63], v[152:155], v[184:187], v[60:63]
	v_mfma_f32_16x16x32_bf16 v[56:59], v[160:163], v[184:187], v[56:59]
	v_mfma_f32_16x16x32_bf16 v[44:47], v[152:155], v[192:195], v[44:47]
	v_mfma_f32_16x16x32_bf16 v[40:43], v[160:163], v[192:195], v[40:43]
	v_mfma_f32_16x16x32_bf16 v[28:31], v[152:155], v[200:203], v[28:31]
	v_mfma_f32_16x16x32_bf16 v[24:27], v[160:163], v[200:203], v[24:27]
	v_mfma_f32_16x16x32_bf16 v[12:15], v[152:155], v[208:211], v[12:15]
	v_mfma_f32_16x16x32_bf16 v[8:11], v[160:163], v[208:211], v[8:11]
	v_mfma_f32_16x16x32_bf16 v[52:55], v[164:167], v[180:183], v[52:55]
	v_mfma_f32_16x16x32_bf16 v[48:51], v[172:175], v[180:183], v[48:51]
	v_mfma_f32_16x16x32_bf16 v[36:39], v[164:167], v[188:191], v[36:39]
	v_mfma_f32_16x16x32_bf16 v[32:35], v[172:175], v[188:191], v[32:35]
	v_mfma_f32_16x16x32_bf16 v[20:23], v[164:167], v[196:199], v[20:23]
	v_mfma_f32_16x16x32_bf16 v[16:19], v[172:175], v[196:199], v[16:19]
	v_mfma_f32_16x16x32_bf16 v[4:7], v[164:167], v[204:207], v[4:7]
	v_mfma_f32_16x16x32_bf16 v[0:3], v[172:175], v[204:207], v[0:3]
	v_mfma_f32_16x16x32_bf16 v[52:55], v[168:171], v[184:187], v[52:55]
	v_mfma_f32_16x16x32_bf16 v[48:51], v[176:179], v[184:187], v[48:51]
	v_mfma_f32_16x16x32_bf16 v[36:39], v[168:171], v[192:195], v[36:39]
	v_mfma_f32_16x16x32_bf16 v[32:35], v[176:179], v[192:195], v[32:35]
	v_mfma_f32_16x16x32_bf16 v[20:23], v[168:171], v[200:203], v[20:23]
	v_mfma_f32_16x16x32_bf16 v[16:19], v[176:179], v[200:203], v[16:19]
	v_mfma_f32_16x16x32_bf16 v[4:7], v[168:171], v[208:211], v[4:7]
	v_mfma_f32_16x16x32_bf16 v[0:3], v[176:179], v[208:211], v[0:3]
	s_barrier
	s_setprio 0
	s_add_i32 s86, s86, 2
	s_add_u32 s74, s74, 0x100
	s_addc_u32 s75, s75, 0
	s_add_u32 s84, s84, 0x100
	s_addc_u32 s85, s85, 0
	s_cmp_gt_u32 s86, 29
	s_cbranch_scc0 .LBB0_1693
	s_and_b64 vcc, exec, s[60:61]
	s_cbranch_vccz .LBB0_1696
	s_barrier

.LBB0_1785:
	ds_read_b128 v[146:149], v155
	ds_read_b128 v[160:163], v155 offset:1024
	ds_read_b128 v[164:167], v155 offset:2048
	ds_read_b128 v[168:171], v155 offset:3072
	ds_read_b128 v[172:175], v156
	ds_read_b128 v[176:179], v156 offset:1024
	ds_read_b128 v[180:183], v156 offset:2048
	ds_read_b128 v[184:187], v156 offset:3072
	ds_read_b128 v[188:191], v157
	ds_read_b128 v[192:195], v157 offset:1024
	ds_read_b128 v[196:199], v157 offset:2048
	ds_read_b128 v[200:203], v157 offset:3072
	ds_read_b128 v[204:207], v157 offset:4096
	ds_read_b128 v[208:211], v157 offset:5120
	ds_read_b128 v[212:215], v157 offset:6144
	ds_read_b128 v[216:219], v157 offset:7168
	s_add_u32 s60, s72, 0xfff80080
	s_addc_u32 s61, s73, -1
	s_cmp_eq_u32 s78, 28
	s_cselect_b32 s77, s56, s61
	s_cselect_b32 s76, s57, s60
	s_cselect_b32 s75, s23, s71
	s_cselect_b32 s74, s63, s69
	v_lshl_add_u64 v[220:221], s[72:73], 0, v[138:139]
	s_add_i32 m0, s6, 0xc000
	s_nop 0
	global_load_lds_dwordx4 v[220:221], off
	v_lshl_add_u64 v[220:221], s[72:73], 0, v[140:141]
	s_add_i32 m0, s6, 0xe000
	s_nop 0
	global_load_lds_dwordx4 v[220:221], off
	s_waitcnt vmcnt(8)
	s_waitcnt lgkmcnt(0)
	s_barrier
	s_setprio 1
	v_mfma_f32_16x16x32_bf16 v[124:127], v[146:149], v[188:191], v[124:127]
	v_mfma_f32_16x16x32_bf16 v[120:123], v[164:167], v[188:191], v[120:123]
	v_mfma_f32_16x16x32_bf16 v[108:111], v[146:149], v[196:199], v[108:111]
	v_mfma_f32_16x16x32_bf16 v[104:107], v[164:167], v[196:199], v[104:107]
	v_mfma_f32_16x16x32_bf16 v[92:95], v[146:149], v[204:207], v[92:95]
	v_mfma_f32_16x16x32_bf16 v[88:91], v[164:167], v[204:207], v[88:91]
	v_mfma_f32_16x16x32_bf16 v[76:79], v[146:149], v[212:215], v[76:79]
	v_mfma_f32_16x16x32_bf16 v[72:75], v[164:167], v[212:215], v[72:75]
	v_mfma_f32_16x16x32_bf16 v[124:127], v[160:163], v[192:195], v[124:127]
	v_mfma_f32_16x16x32_bf16 v[120:123], v[168:171], v[192:195], v[120:123]
	v_mfma_f32_16x16x32_bf16 v[108:111], v[160:163], v[200:203], v[108:111]
	v_mfma_f32_16x16x32_bf16 v[104:107], v[168:171], v[200:203], v[104:107]
	v_mfma_f32_16x16x32_bf16 v[92:95], v[160:163], v[208:211], v[92:95]
	v_mfma_f32_16x16x32_bf16 v[88:91], v[168:171], v[208:211], v[88:91]
	v_mfma_f32_16x16x32_bf16 v[76:79], v[160:163], v[216:219], v[76:79]
	v_mfma_f32_16x16x32_bf16 v[72:75], v[168:171], v[216:219], v[72:75]
	v_mfma_f32_16x16x32_bf16 v[116:119], v[172:175], v[188:191], v[116:119]
	v_mfma_f32_16x16x32_bf16 v[112:115], v[180:183], v[188:191], v[112:115]
	v_mfma_f32_16x16x32_bf16 v[100:103], v[172:175], v[196:199], v[100:103]
	v_mfma_f32_16x16x32_bf16 v[96:99], v[180:183], v[196:199], v[96:99]
	v_mfma_f32_16x16x32_bf16 v[84:87], v[172:175], v[204:207], v[84:87]
	v_mfma_f32_16x16x32_bf16 v[80:83], v[180:183], v[204:207], v[80:83]
	v_mfma_f32_16x16x32_bf16 v[68:71], v[172:175], v[212:215], v[68:71]
	v_mfma_f32_16x16x32_bf16 v[64:67], v[180:183], v[212:215], v[64:67]
	v_mfma_f32_16x16x32_bf16 v[116:119], v[176:179], v[192:195], v[116:119]
	v_mfma_f32_16x16x32_bf16 v[112:115], v[184:187], v[192:195], v[112:115]
	v_mfma_f32_16x16x32_bf16 v[100:103], v[176:179], v[200:203], v[100:103]
	v_mfma_f32_16x16x32_bf16 v[96:99], v[184:187], v[200:203], v[96:99]
	v_mfma_f32_16x16x32_bf16 v[84:87], v[176:179], v[208:211], v[84:87]
	v_mfma_f32_16x16x32_bf16 v[80:83], v[184:187], v[208:211], v[80:83]
	v_mfma_f32_16x16x32_bf16 v[68:71], v[176:179], v[216:219], v[68:71]
	v_mfma_f32_16x16x32_bf16 v[64:67], v[184:187], v[216:219], v[64:67]
	s_barrier
	s_setprio 0
	ds_read_b128 v[188:191], v157 offset:16384
	ds_read_b128 v[192:195], v157 offset:17408
	ds_read_b128 v[196:199], v157 offset:18432
	ds_read_b128 v[200:203], v157 offset:19456
	ds_read_b128 v[204:207], v157 offset:20480
	ds_read_b128 v[208:211], v157 offset:21504
	ds_read_b128 v[212:215], v157 offset:22528
	ds_read_b128 v[216:219], v157 offset:23552
	s_add_i32 s60, s35, s94
	v_lshl_add_u64 v[220:221], s[74:75], 0, v[130:131]
	s_mov_b32 m0, s60
	s_nop 0
	global_load_lds_dwordx4 v[220:221], off
	s_add_i32 m0, s60, 0x2000
	s_add_u32 s80, s74, 0x80000
	v_lshl_add_u64 v[222:223], s[74:75], 0, v[134:135]
	s_addc_u32 s81, s75, 0
	s_add_i32 s60, s46, s94
	global_load_lds_dwordx4 v[222:223], off
	v_lshl_add_u64 v[224:225], s[80:81], 0, v[130:131]
	s_mov_b32 m0, s60
	v_lshl_add_u64 v[226:227], s[76:77], 0, v[132:133]
	global_load_lds_dwordx4 v[224:225], off
	v_lshl_add_u64 v[224:225], s[80:81], 0, v[134:135]
	s_add_i32 m0, s60, 0x2000
	s_nop 0
	global_load_lds_dwordx4 v[224:225], off
	v_lshl_add_u64 v[224:225], s[76:77], 0, v[128:129]
	s_mov_b32 m0, s6
	s_nop 0
	global_load_lds_dwordx4 v[224:225], off
	s_mov_b32 m0, s7
	s_nop 0
	global_load_lds_dwordx4 v[226:227], off
	s_waitcnt vmcnt(8)
	s_waitcnt lgkmcnt(0)
	s_barrier
	s_setprio 1
	v_mfma_f32_16x16x32_bf16 v[60:63], v[146:149], v[188:191], v[60:63]
	v_mfma_f32_16x16x32_bf16 v[56:59], v[164:167], v[188:191], v[56:59]
	v_mfma_f32_16x16x32_bf16 v[44:47], v[146:149], v[196:199], v[44:47]
	v_mfma_f32_16x16x32_bf16 v[40:43], v[164:167], v[196:199], v[40:43]
	v_mfma_f32_16x16x32_bf16 v[28:31], v[146:149], v[204:207], v[28:31]
	v_mfma_f32_16x16x32_bf16 v[24:27], v[164:167], v[204:207], v[24:27]
	v_mfma_f32_16x16x32_bf16 v[12:15], v[146:149], v[212:215], v[12:15]
	v_mfma_f32_16x16x32_bf16 v[8:11], v[164:167], v[212:215], v[8:11]
	v_mfma_f32_16x16x32_bf16 v[60:63], v[160:163], v[192:195], v[60:63]
	v_mfma_f32_16x16x32_bf16 v[56:59], v[168:171], v[192:195], v[56:59]
	v_mfma_f32_16x16x32_bf16 v[44:47], v[160:163], v[200:203], v[44:47]
	v_mfma_f32_16x16x32_bf16 v[40:43], v[168:171], v[200:203], v[40:43]
	v_mfma_f32_16x16x32_bf16 v[28:31], v[160:163], v[208:211], v[28:31]
	v_mfma_f32_16x16x32_bf16 v[24:27], v[168:171], v[208:211], v[24:27]
	v_mfma_f32_16x16x32_bf16 v[12:15], v[160:163], v[216:219], v[12:15]
	v_mfma_f32_16x16x32_bf16 v[8:11], v[168:171], v[216:219], v[8:11]
	v_mfma_f32_16x16x32_bf16 v[52:55], v[172:175], v[188:191], v[52:55]
	v_mfma_f32_16x16x32_bf16 v[48:51], v[180:183], v[188:191], v[48:51]
	v_mfma_f32_16x16x32_bf16 v[36:39], v[172:175], v[196:199], v[36:39]
	v_mfma_f32_16x16x32_bf16 v[32:35], v[180:183], v[196:199], v[32:35]
	v_mfma_f32_16x16x32_bf16 v[20:23], v[172:175], v[204:207], v[20:23]
	v_mfma_f32_16x16x32_bf16 v[16:19], v[180:183], v[204:207], v[16:19]
	v_mfma_f32_16x16x32_bf16 v[4:7], v[172:175], v[212:215], v[4:7]
	v_mfma_f32_16x16x32_bf16 v[0:3], v[180:183], v[212:215], v[0:3]
	v_mfma_f32_16x16x32_bf16 v[52:55], v[176:179], v[192:195], v[52:55]
	v_mfma_f32_16x16x32_bf16 v[48:51], v[184:187], v[192:195], v[48:51]
	v_mfma_f32_16x16x32_bf16 v[36:39], v[176:179], v[200:203], v[36:39]
	v_mfma_f32_16x16x32_bf16 v[32:35], v[184:187], v[200:203], v[32:35]
	v_mfma_f32_16x16x32_bf16 v[20:23], v[176:179], v[208:211], v[20:23]
	v_mfma_f32_16x16x32_bf16 v[16:19], v[184:187], v[208:211], v[16:19]
	v_mfma_f32_16x16x32_bf16 v[4:7], v[176:179], v[216:219], v[4:7]
	v_mfma_f32_16x16x32_bf16 v[0:3], v[184:187], v[216:219], v[0:3]
	s_barrier
	s_setprio 0
	s_add_i32 s60, 0, 0x18000
	v_add_u32_e32 v159, s60, v151
	ds_read_b128 v[146:149], v159
	ds_read_b128 v[160:163], v159 offset:1024
	ds_read_b128 v[164:167], v159 offset:2048
	ds_read_b128 v[168:171], v159 offset:3072
	s_add_i32 s61, 0, 0x1c000
	v_add_u32_e32 v159, s61, v151
	ds_read_b128 v[172:175], v159
	ds_read_b128 v[176:179], v159 offset:1024
	ds_read_b128 v[180:183], v159 offset:2048
	ds_read_b128 v[184:187], v159 offset:3072
	ds_read_b128 v[188:191], v157 offset:32768
	ds_read_b128 v[192:195], v157 offset:33792
	ds_read_b128 v[196:199], v157 offset:34816
	ds_read_b128 v[200:203], v157 offset:35840
	ds_read_b128 v[204:207], v157 offset:36864
	ds_read_b128 v[208:211], v157 offset:37888
	ds_read_b128 v[212:215], v157 offset:38912
	ds_read_b128 v[216:219], v157 offset:39936
	s_add_u32 s76, s76, 0x80000
	s_addc_u32 s77, s77, 0
	s_mov_b32 m0, s12
	v_lshl_add_u64 v[228:229], s[76:77], 0, v[128:129]
	global_load_lds_dwordx4 v[228:229], off
	v_lshl_add_u64 v[228:229], s[76:77], 0, v[132:133]
	s_mov_b32 m0, s13
	s_nop 0
	global_load_lds_dwordx4 v[228:229], off
	s_waitcnt vmcnt(8)
	s_waitcnt lgkmcnt(0)
	s_barrier
	s_setprio 1
	v_mfma_f32_16x16x32_bf16 v[124:127], v[146:149], v[188:191], v[124:127]
	v_mfma_f32_16x16x32_bf16 v[120:123], v[164:167], v[188:191], v[120:123]
	v_mfma_f32_16x16x32_bf16 v[108:111], v[146:149], v[196:199], v[108:111]
	v_mfma_f32_16x16x32_bf16 v[104:107], v[164:167], v[196:199], v[104:107]
	v_mfma_f32_16x16x32_bf16 v[92:95], v[146:149], v[204:207], v[92:95]
	v_mfma_f32_16x16x32_bf16 v[88:91], v[164:167], v[204:207], v[88:91]
	v_mfma_f32_16x16x32_bf16 v[76:79], v[146:149], v[212:215], v[76:79]
	v_mfma_f32_16x16x32_bf16 v[72:75], v[164:167], v[212:215], v[72:75]
	v_mfma_f32_16x16x32_bf16 v[124:127], v[160:163], v[192:195], v[124:127]
	v_mfma_f32_16x16x32_bf16 v[120:123], v[168:171], v[192:195], v[120:123]
	v_mfma_f32_16x16x32_bf16 v[108:111], v[160:163], v[200:203], v[108:111]
	v_mfma_f32_16x16x32_bf16 v[104:107], v[168:171], v[200:203], v[104:107]
	v_mfma_f32_16x16x32_bf16 v[92:95], v[160:163], v[208:211], v[92:95]
	v_mfma_f32_16x16x32_bf16 v[88:91], v[168:171], v[208:211], v[88:91]
	v_mfma_f32_16x16x32_bf16 v[76:79], v[160:163], v[216:219], v[76:79]
	v_mfma_f32_16x16x32_bf16 v[72:75], v[168:171], v[216:219], v[72:75]
	v_mfma_f32_16x16x32_bf16 v[116:119], v[172:175], v[188:191], v[116:119]
	v_mfma_f32_16x16x32_bf16 v[112:115], v[180:183], v[188:191], v[112:115]
	v_mfma_f32_16x16x32_bf16 v[100:103], v[172:175], v[196:199], v[100:103]
	v_mfma_f32_16x16x32_bf16 v[96:99], v[180:183], v[196:199], v[96:99]
	v_mfma_f32_16x16x32_bf16 v[84:87], v[172:175], v[204:207], v[84:87]
	v_mfma_f32_16x16x32_bf16 v[80:83], v[180:183], v[204:207], v[80:83]
	v_mfma_f32_16x16x32_bf16 v[68:71], v[172:175], v[212:215], v[68:71]
	v_mfma_f32_16x16x32_bf16 v[64:67], v[180:183], v[212:215], v[64:67]
	v_mfma_f32_16x16x32_bf16 v[116:119], v[176:179], v[192:195], v[116:119]
	v_mfma_f32_16x16x32_bf16 v[112:115], v[184:187], v[192:195], v[112:115]
	v_mfma_f32_16x16x32_bf16 v[100:103], v[176:179], v[200:203], v[100:103]
	v_mfma_f32_16x16x32_bf16 v[96:99], v[184:187], v[200:203], v[96:99]
	v_mfma_f32_16x16x32_bf16 v[84:87], v[176:179], v[208:211], v[84:87]
	v_mfma_f32_16x16x32_bf16 v[80:83], v[184:187], v[208:211], v[80:83]
	v_mfma_f32_16x16x32_bf16 v[68:71], v[176:179], v[216:219], v[68:71]
	v_mfma_f32_16x16x32_bf16 v[64:67], v[184:187], v[216:219], v[64:67]
	s_barrier
	s_setprio 0
	ds_read_b128 v[188:191], v157 offset:49152
	ds_read_b128 v[192:195], v157 offset:50176
	ds_read_b128 v[196:199], v157 offset:51200
	ds_read_b128 v[200:203], v157 offset:52224
	ds_read_b128 v[204:207], v157 offset:53248
	ds_read_b128 v[208:211], v157 offset:54272
	ds_read_b128 v[212:215], v157 offset:55296
	ds_read_b128 v[216:219], v157 offset:56320
	s_add_i32 s60, s60, s94
	v_lshl_add_u64 v[220:221], v[220:221], 0, s[20:21]
	s_mov_b32 m0, s60
	s_nop 0
	global_load_lds_dwordx4 v[220:221], off
	s_add_i32 m0, s60, 0x2000
	s_add_u32 s74, s74, 0x80080
	v_lshl_add_u64 v[220:221], v[222:223], 0, s[20:21]
	s_addc_u32 s75, s75, 0
	s_add_i32 s60, s61, s94
	global_load_lds_dwordx4 v[220:221], off
	v_lshl_add_u64 v[220:221], s[74:75], 0, v[130:131]
	s_mov_b32 m0, s60
	s_nop 0
	global_load_lds_dwordx4 v[220:221], off
	v_lshl_add_u64 v[220:221], s[74:75], 0, v[134:135]
	s_add_i32 m0, s60, 0x2000
	s_nop 0
	global_load_lds_dwordx4 v[220:221], off
	v_lshl_add_u64 v[220:221], v[224:225], 0, s[20:21]
	s_mov_b32 m0, s30
	s_nop 0
	global_load_lds_dwordx4 v[220:221], off
	v_lshl_add_u64 v[220:221], v[226:227], 0, s[20:21]
	s_mov_b32 m0, s34
	s_nop 0
	global_load_lds_dwordx4 v[220:221], off
	s_waitcnt vmcnt(8)
	s_waitcnt lgkmcnt(0)
	s_barrier
	s_setprio 1
	v_mfma_f32_16x16x32_bf16 v[60:63], v[146:149], v[188:191], v[60:63]
	v_mfma_f32_16x16x32_bf16 v[56:59], v[164:167], v[188:191], v[56:59]
	v_mfma_f32_16x16x32_bf16 v[44:47], v[146:149], v[196:199], v[44:47]
	v_mfma_f32_16x16x32_bf16 v[40:43], v[164:167], v[196:199], v[40:43]
	v_mfma_f32_16x16x32_bf16 v[28:31], v[146:149], v[204:207], v[28:31]
	v_mfma_f32_16x16x32_bf16 v[24:27], v[164:167], v[204:207], v[24:27]
	v_mfma_f32_16x16x32_bf16 v[12:15], v[146:149], v[212:215], v[12:15]
	v_mfma_f32_16x16x32_bf16 v[8:11], v[164:167], v[212:215], v[8:11]
	v_mfma_f32_16x16x32_bf16 v[60:63], v[160:163], v[192:195], v[60:63]
	v_mfma_f32_16x16x32_bf16 v[56:59], v[168:171], v[192:195], v[56:59]
	v_mfma_f32_16x16x32_bf16 v[44:47], v[160:163], v[200:203], v[44:47]
	v_mfma_f32_16x16x32_bf16 v[40:43], v[168:171], v[200:203], v[40:43]
	v_mfma_f32_16x16x32_bf16 v[28:31], v[160:163], v[208:211], v[28:31]
	v_mfma_f32_16x16x32_bf16 v[24:27], v[168:171], v[208:211], v[24:27]
	v_mfma_f32_16x16x32_bf16 v[12:15], v[160:163], v[216:219], v[12:15]
	v_mfma_f32_16x16x32_bf16 v[8:11], v[168:171], v[216:219], v[8:11]
	v_mfma_f32_16x16x32_bf16 v[52:55], v[172:175], v[188:191], v[52:55]
	v_mfma_f32_16x16x32_bf16 v[48:51], v[180:183], v[188:191], v[48:51]
	v_mfma_f32_16x16x32_bf16 v[36:39], v[172:175], v[196:199], v[36:39]
	v_mfma_f32_16x16x32_bf16 v[32:35], v[180:183], v[196:199], v[32:35]
	v_mfma_f32_16x16x32_bf16 v[20:23], v[172:175], v[204:207], v[20:23]
	v_mfma_f32_16x16x32_bf16 v[16:19], v[180:183], v[204:207], v[16:19]
	v_mfma_f32_16x16x32_bf16 v[4:7], v[172:175], v[212:215], v[4:7]
	v_mfma_f32_16x16x32_bf16 v[0:3], v[180:183], v[212:215], v[0:3]
	v_mfma_f32_16x16x32_bf16 v[52:55], v[176:179], v[192:195], v[52:55]
	v_mfma_f32_16x16x32_bf16 v[48:51], v[184:187], v[192:195], v[48:51]
	v_mfma_f32_16x16x32_bf16 v[36:39], v[176:179], v[200:203], v[36:39]
	v_mfma_f32_16x16x32_bf16 v[32:35], v[184:187], v[200:203], v[32:35]
	v_mfma_f32_16x16x32_bf16 v[20:23], v[176:179], v[208:211], v[20:23]
	v_mfma_f32_16x16x32_bf16 v[16:19], v[184:187], v[208:211], v[16:19]
	v_mfma_f32_16x16x32_bf16 v[4:7], v[176:179], v[216:219], v[4:7]
	v_mfma_f32_16x16x32_bf16 v[0:3], v[184:187], v[216:219], v[0:3]
	s_barrier
	s_setprio 0
	s_add_i32 s78, s78, 2
	s_add_u32 s72, s72, 0x100
	s_addc_u32 s73, s73, 0
	s_add_u32 s69, s69, 0x100
	s_addc_u32 s71, s71, 0
	s_cmp_gt_u32 s78, 29
	s_cbranch_scc0 .LBB0_1785
	s_and_b64 vcc, exec, s[58:59]
	s_cbranch_vccz .LBB0_1788
	s_barrier

.LBB0_1897:
	ds_read_b128 v[140:143], v149
	ds_read_b128 v[152:155], v149 offset:1024
	ds_read_b128 v[156:159], v149 offset:2048
	ds_read_b128 v[160:163], v149 offset:3072
	ds_read_b128 v[164:167], v150
	ds_read_b128 v[168:171], v150 offset:1024
	ds_read_b128 v[172:175], v150 offset:2048
	ds_read_b128 v[176:179], v150 offset:3072
	ds_read_b128 v[180:183], v151
	ds_read_b128 v[184:187], v151 offset:1024
	ds_read_b128 v[188:191], v151 offset:2048
	ds_read_b128 v[192:195], v151 offset:3072
	ds_read_b128 v[196:199], v151 offset:4096
	ds_read_b128 v[200:203], v151 offset:5120
	ds_read_b128 v[204:207], v151 offset:6144
	ds_read_b128 v[208:211], v151 offset:7168
	s_add_u32 s60, s72, 0xffe00080
	s_addc_u32 s61, s73, -1
	s_cmpk_eq_i32 s79, 0x7c
	s_cselect_b32 s77, s56, s61
	s_cselect_b32 s76, s57, s60
	s_cselect_b32 s75, s63, s78
	s_cselect_b32 s74, s65, s71
	v_lshl_add_u64 v[212:213], s[72:73], 0, v[132:133]
	s_add_i32 m0, s6, 0xc000
	s_nop 0
	global_load_lds_dwordx4 v[212:213], off
	v_lshl_add_u64 v[212:213], s[72:73], 0, v[134:135]
	s_add_i32 m0, s6, 0xe000
	s_nop 0
	global_load_lds_dwordx4 v[212:213], off
	s_waitcnt vmcnt(8)
	s_waitcnt lgkmcnt(0)
	s_barrier
	s_setprio 1
	v_mfma_f32_16x16x32_bf16 v[124:127], v[140:143], v[180:183], v[124:127]
	v_mfma_f32_16x16x32_bf16 v[120:123], v[156:159], v[180:183], v[120:123]
	v_mfma_f32_16x16x32_bf16 v[108:111], v[140:143], v[188:191], v[108:111]
	v_mfma_f32_16x16x32_bf16 v[104:107], v[156:159], v[188:191], v[104:107]
	v_mfma_f32_16x16x32_bf16 v[92:95], v[140:143], v[196:199], v[92:95]
	v_mfma_f32_16x16x32_bf16 v[88:91], v[156:159], v[196:199], v[88:91]
	v_mfma_f32_16x16x32_bf16 v[76:79], v[140:143], v[204:207], v[76:79]
	v_mfma_f32_16x16x32_bf16 v[72:75], v[156:159], v[204:207], v[72:75]
	v_mfma_f32_16x16x32_bf16 v[124:127], v[152:155], v[184:187], v[124:127]
	v_mfma_f32_16x16x32_bf16 v[120:123], v[160:163], v[184:187], v[120:123]
	v_mfma_f32_16x16x32_bf16 v[108:111], v[152:155], v[192:195], v[108:111]
	v_mfma_f32_16x16x32_bf16 v[104:107], v[160:163], v[192:195], v[104:107]
	v_mfma_f32_16x16x32_bf16 v[92:95], v[152:155], v[200:203], v[92:95]
	v_mfma_f32_16x16x32_bf16 v[88:91], v[160:163], v[200:203], v[88:91]
	v_mfma_f32_16x16x32_bf16 v[76:79], v[152:155], v[208:211], v[76:79]
	v_mfma_f32_16x16x32_bf16 v[72:75], v[160:163], v[208:211], v[72:75]
	v_mfma_f32_16x16x32_bf16 v[116:119], v[164:167], v[180:183], v[116:119]
	v_mfma_f32_16x16x32_bf16 v[112:115], v[172:175], v[180:183], v[112:115]
	v_mfma_f32_16x16x32_bf16 v[100:103], v[164:167], v[188:191], v[100:103]
	v_mfma_f32_16x16x32_bf16 v[96:99], v[172:175], v[188:191], v[96:99]
	v_mfma_f32_16x16x32_bf16 v[84:87], v[164:167], v[196:199], v[84:87]
	v_mfma_f32_16x16x32_bf16 v[80:83], v[172:175], v[196:199], v[80:83]
	v_mfma_f32_16x16x32_bf16 v[68:71], v[164:167], v[204:207], v[68:71]
	v_mfma_f32_16x16x32_bf16 v[64:67], v[172:175], v[204:207], v[64:67]
	v_mfma_f32_16x16x32_bf16 v[116:119], v[168:171], v[184:187], v[116:119]
	v_mfma_f32_16x16x32_bf16 v[112:115], v[176:179], v[184:187], v[112:115]
	v_mfma_f32_16x16x32_bf16 v[100:103], v[168:171], v[192:195], v[100:103]
	v_mfma_f32_16x16x32_bf16 v[96:99], v[176:179], v[192:195], v[96:99]
	v_mfma_f32_16x16x32_bf16 v[84:87], v[168:171], v[200:203], v[84:87]
	v_mfma_f32_16x16x32_bf16 v[80:83], v[176:179], v[200:203], v[80:83]
	v_mfma_f32_16x16x32_bf16 v[68:71], v[168:171], v[208:211], v[68:71]
	v_mfma_f32_16x16x32_bf16 v[64:67], v[176:179], v[208:211], v[64:67]
	s_barrier
	s_setprio 0
	ds_read_b128 v[180:183], v151 offset:16384
	ds_read_b128 v[184:187], v151 offset:17408
	ds_read_b128 v[188:191], v151 offset:18432
	ds_read_b128 v[192:195], v151 offset:19456
	ds_read_b128 v[196:199], v151 offset:20480
	ds_read_b128 v[200:203], v151 offset:21504
	ds_read_b128 v[204:207], v151 offset:22528
	ds_read_b128 v[208:211], v151 offset:23552
	s_add_i32 s60, s34, s94
	v_lshl_add_u64 v[212:213], s[74:75], 0, v[128:129]
	s_mov_b32 m0, s60
	s_nop 0
	global_load_lds_dwordx4 v[212:213], off
	s_add_i32 m0, s60, 0x2000
	s_add_u32 s80, s74, 0x200000
	v_lshl_add_u64 v[214:215], s[74:75], 0, v[130:131]
	s_addc_u32 s81, s75, 0
	s_add_i32 s60, s35, s94
	global_load_lds_dwordx4 v[214:215], off
	v_lshl_add_u64 v[216:217], s[80:81], 0, v[128:129]
	s_mov_b32 m0, s60
	v_lshl_add_u64 v[218:219], s[76:77], 0, v[130:131]
	global_load_lds_dwordx4 v[216:217], off
	v_lshl_add_u64 v[216:217], s[80:81], 0, v[130:131]
	s_add_i32 m0, s60, 0x2000
	s_nop 0
	global_load_lds_dwordx4 v[216:217], off
	v_lshl_add_u64 v[216:217], s[76:77], 0, v[128:129]
	s_mov_b32 m0, s6
	s_nop 0
	global_load_lds_dwordx4 v[216:217], off
	s_mov_b32 m0, s7
	s_nop 0
	global_load_lds_dwordx4 v[218:219], off
	s_waitcnt vmcnt(8)
	s_waitcnt lgkmcnt(0)
	s_barrier
	s_setprio 1
	v_mfma_f32_16x16x32_bf16 v[60:63], v[140:143], v[180:183], v[60:63]
	v_mfma_f32_16x16x32_bf16 v[56:59], v[156:159], v[180:183], v[56:59]
	v_mfma_f32_16x16x32_bf16 v[44:47], v[140:143], v[188:191], v[44:47]
	v_mfma_f32_16x16x32_bf16 v[40:43], v[156:159], v[188:191], v[40:43]
	v_mfma_f32_16x16x32_bf16 v[28:31], v[140:143], v[196:199], v[28:31]
	v_mfma_f32_16x16x32_bf16 v[24:27], v[156:159], v[196:199], v[24:27]
	v_mfma_f32_16x16x32_bf16 v[12:15], v[140:143], v[204:207], v[12:15]
	v_mfma_f32_16x16x32_bf16 v[8:11], v[156:159], v[204:207], v[8:11]
	v_mfma_f32_16x16x32_bf16 v[60:63], v[152:155], v[184:187], v[60:63]
	v_mfma_f32_16x16x32_bf16 v[56:59], v[160:163], v[184:187], v[56:59]
	v_mfma_f32_16x16x32_bf16 v[44:47], v[152:155], v[192:195], v[44:47]
	v_mfma_f32_16x16x32_bf16 v[40:43], v[160:163], v[192:195], v[40:43]
	v_mfma_f32_16x16x32_bf16 v[28:31], v[152:155], v[200:203], v[28:31]
	v_mfma_f32_16x16x32_bf16 v[24:27], v[160:163], v[200:203], v[24:27]
	v_mfma_f32_16x16x32_bf16 v[12:15], v[152:155], v[208:211], v[12:15]
	v_mfma_f32_16x16x32_bf16 v[8:11], v[160:163], v[208:211], v[8:11]
	v_mfma_f32_16x16x32_bf16 v[52:55], v[164:167], v[180:183], v[52:55]
	v_mfma_f32_16x16x32_bf16 v[48:51], v[172:175], v[180:183], v[48:51]
	v_mfma_f32_16x16x32_bf16 v[36:39], v[164:167], v[188:191], v[36:39]
	v_mfma_f32_16x16x32_bf16 v[32:35], v[172:175], v[188:191], v[32:35]
	v_mfma_f32_16x16x32_bf16 v[20:23], v[164:167], v[196:199], v[20:23]
	v_mfma_f32_16x16x32_bf16 v[16:19], v[172:175], v[196:199], v[16:19]
	v_mfma_f32_16x16x32_bf16 v[4:7], v[164:167], v[204:207], v[4:7]
	v_mfma_f32_16x16x32_bf16 v[0:3], v[172:175], v[204:207], v[0:3]
	v_mfma_f32_16x16x32_bf16 v[52:55], v[168:171], v[184:187], v[52:55]
	v_mfma_f32_16x16x32_bf16 v[48:51], v[176:179], v[184:187], v[48:51]
	v_mfma_f32_16x16x32_bf16 v[36:39], v[168:171], v[192:195], v[36:39]
	v_mfma_f32_16x16x32_bf16 v[32:35], v[176:179], v[192:195], v[32:35]
	v_mfma_f32_16x16x32_bf16 v[20:23], v[168:171], v[200:203], v[20:23]
	v_mfma_f32_16x16x32_bf16 v[16:19], v[176:179], v[200:203], v[16:19]
	v_mfma_f32_16x16x32_bf16 v[4:7], v[168:171], v[208:211], v[4:7]
	v_mfma_f32_16x16x32_bf16 v[0:3], v[176:179], v[208:211], v[0:3]
	s_barrier
	s_setprio 0
	s_add_i32 s60, 0, 0x18000
	s_add_i32 s61, 0, 0x1c000
	v_add_u32_e32 v160, s60, v145
	ds_read_b128 v[140:143], v160
	ds_read_b128 v[152:155], v160 offset:1024
	ds_read_b128 v[156:159], v160 offset:2048
	ds_read_b128 v[160:163], v160 offset:3072
	v_add_u32_e32 v176, s61, v145
	ds_read_b128 v[164:167], v176
	ds_read_b128 v[168:171], v176 offset:1024
	ds_read_b128 v[172:175], v176 offset:2048
	ds_read_b128 v[176:179], v176 offset:3072
	ds_read_b128 v[180:183], v151 offset:32768
	ds_read_b128 v[184:187], v151 offset:33792
	ds_read_b128 v[188:191], v151 offset:34816
	ds_read_b128 v[192:195], v151 offset:35840
	ds_read_b128 v[196:199], v151 offset:36864
	ds_read_b128 v[200:203], v151 offset:37888
	ds_read_b128 v[204:207], v151 offset:38912
	ds_read_b128 v[208:211], v151 offset:39936
	s_add_u32 s76, s76, 0x200000
	s_addc_u32 s77, s77, 0
	s_mov_b32 m0, s12
	v_lshl_add_u64 v[220:221], s[76:77], 0, v[128:129]
	global_load_lds_dwordx4 v[220:221], off
	v_lshl_add_u64 v[220:221], s[76:77], 0, v[130:131]
	s_mov_b32 m0, s13
	s_nop 0
	global_load_lds_dwordx4 v[220:221], off
	s_waitcnt vmcnt(8)
	s_waitcnt lgkmcnt(0)
	s_barrier
	s_setprio 1
	v_mfma_f32_16x16x32_bf16 v[124:127], v[140:143], v[180:183], v[124:127]
	v_mfma_f32_16x16x32_bf16 v[120:123], v[156:159], v[180:183], v[120:123]
	v_mfma_f32_16x16x32_bf16 v[108:111], v[140:143], v[188:191], v[108:111]
	v_mfma_f32_16x16x32_bf16 v[104:107], v[156:159], v[188:191], v[104:107]
	v_mfma_f32_16x16x32_bf16 v[92:95], v[140:143], v[196:199], v[92:95]
	v_mfma_f32_16x16x32_bf16 v[88:91], v[156:159], v[196:199], v[88:91]
	v_mfma_f32_16x16x32_bf16 v[76:79], v[140:143], v[204:207], v[76:79]
	v_mfma_f32_16x16x32_bf16 v[72:75], v[156:159], v[204:207], v[72:75]
	v_mfma_f32_16x16x32_bf16 v[124:127], v[152:155], v[184:187], v[124:127]
	v_mfma_f32_16x16x32_bf16 v[120:123], v[160:163], v[184:187], v[120:123]
	v_mfma_f32_16x16x32_bf16 v[108:111], v[152:155], v[192:195], v[108:111]
	v_mfma_f32_16x16x32_bf16 v[104:107], v[160:163], v[192:195], v[104:107]
	v_mfma_f32_16x16x32_bf16 v[92:95], v[152:155], v[200:203], v[92:95]
	v_mfma_f32_16x16x32_bf16 v[88:91], v[160:163], v[200:203], v[88:91]
	v_mfma_f32_16x16x32_bf16 v[76:79], v[152:155], v[208:211], v[76:79]
	v_mfma_f32_16x16x32_bf16 v[72:75], v[160:163], v[208:211], v[72:75]
	v_mfma_f32_16x16x32_bf16 v[116:119], v[164:167], v[180:183], v[116:119]
	v_mfma_f32_16x16x32_bf16 v[112:115], v[172:175], v[180:183], v[112:115]
	v_mfma_f32_16x16x32_bf16 v[100:103], v[164:167], v[188:191], v[100:103]
	v_mfma_f32_16x16x32_bf16 v[96:99], v[172:175], v[188:191], v[96:99]
	v_mfma_f32_16x16x32_bf16 v[84:87], v[164:167], v[196:199], v[84:87]
	v_mfma_f32_16x16x32_bf16 v[80:83], v[172:175], v[196:199], v[80:83]
	v_mfma_f32_16x16x32_bf16 v[68:71], v[164:167], v[204:207], v[68:71]
	v_mfma_f32_16x16x32_bf16 v[64:67], v[172:175], v[204:207], v[64:67]
	v_mfma_f32_16x16x32_bf16 v[116:119], v[168:171], v[184:187], v[116:119]
	v_mfma_f32_16x16x32_bf16 v[112:115], v[176:179], v[184:187], v[112:115]
	v_mfma_f32_16x16x32_bf16 v[100:103], v[168:171], v[192:195], v[100:103]
	v_mfma_f32_16x16x32_bf16 v[96:99], v[176:179], v[192:195], v[96:99]
	v_mfma_f32_16x16x32_bf16 v[84:87], v[168:171], v[200:203], v[84:87]
	v_mfma_f32_16x16x32_bf16 v[80:83], v[176:179], v[200:203], v[80:83]
	v_mfma_f32_16x16x32_bf16 v[68:71], v[168:171], v[208:211], v[68:71]
	v_mfma_f32_16x16x32_bf16 v[64:67], v[176:179], v[208:211], v[64:67]
	s_barrier
	s_setprio 0
	ds_read_b128 v[180:183], v151 offset:49152
	ds_read_b128 v[184:187], v151 offset:50176
	ds_read_b128 v[188:191], v151 offset:51200
	ds_read_b128 v[192:195], v151 offset:52224
	ds_read_b128 v[196:199], v151 offset:53248
	ds_read_b128 v[200:203], v151 offset:54272
	ds_read_b128 v[204:207], v151 offset:55296
	ds_read_b128 v[208:211], v151 offset:56320
	s_add_i32 s60, s60, s94
	v_lshl_add_u64 v[212:213], v[212:213], 0, s[22:23]
	s_mov_b32 m0, s60
	s_nop 0
	global_load_lds_dwordx4 v[212:213], off
	s_add_i32 m0, s60, 0x2000
	s_add_u32 s74, s74, 0x200080
	v_lshl_add_u64 v[212:213], v[214:215], 0, s[22:23]
	s_addc_u32 s75, s75, 0
	s_add_i32 s60, s61, s94
	global_load_lds_dwordx4 v[212:213], off
	v_lshl_add_u64 v[212:213], s[74:75], 0, v[128:129]
	s_mov_b32 m0, s60
	s_nop 0
	global_load_lds_dwordx4 v[212:213], off
	v_lshl_add_u64 v[212:213], s[74:75], 0, v[130:131]
	s_add_i32 m0, s60, 0x2000
	s_nop 0
	global_load_lds_dwordx4 v[212:213], off
	v_lshl_add_u64 v[212:213], v[216:217], 0, s[22:23]
	s_mov_b32 m0, s29
	s_nop 0
	global_load_lds_dwordx4 v[212:213], off
	v_lshl_add_u64 v[212:213], v[218:219], 0, s[22:23]
	s_mov_b32 m0, s30
	s_nop 0
	global_load_lds_dwordx4 v[212:213], off
	s_waitcnt vmcnt(8)
	s_waitcnt lgkmcnt(0)
	s_barrier
	s_setprio 1
	v_mfma_f32_16x16x32_bf16 v[60:63], v[140:143], v[180:183], v[60:63]
	v_mfma_f32_16x16x32_bf16 v[56:59], v[156:159], v[180:183], v[56:59]
	v_mfma_f32_16x16x32_bf16 v[44:47], v[140:143], v[188:191], v[44:47]
	v_mfma_f32_16x16x32_bf16 v[40:43], v[156:159], v[188:191], v[40:43]
	v_mfma_f32_16x16x32_bf16 v[28:31], v[140:143], v[196:199], v[28:31]
	v_mfma_f32_16x16x32_bf16 v[24:27], v[156:159], v[196:199], v[24:27]
	v_mfma_f32_16x16x32_bf16 v[12:15], v[140:143], v[204:207], v[12:15]
	v_mfma_f32_16x16x32_bf16 v[8:11], v[156:159], v[204:207], v[8:11]
	v_mfma_f32_16x16x32_bf16 v[60:63], v[152:155], v[184:187], v[60:63]
	v_mfma_f32_16x16x32_bf16 v[56:59], v[160:163], v[184:187], v[56:59]
	v_mfma_f32_16x16x32_bf16 v[44:47], v[152:155], v[192:195], v[44:47]
	v_mfma_f32_16x16x32_bf16 v[40:43], v[160:163], v[192:195], v[40:43]
	v_mfma_f32_16x16x32_bf16 v[28:31], v[152:155], v[200:203], v[28:31]
	v_mfma_f32_16x16x32_bf16 v[24:27], v[160:163], v[200:203], v[24:27]
	v_mfma_f32_16x16x32_bf16 v[12:15], v[152:155], v[208:211], v[12:15]
	v_mfma_f32_16x16x32_bf16 v[8:11], v[160:163], v[208:211], v[8:11]
	v_mfma_f32_16x16x32_bf16 v[52:55], v[164:167], v[180:183], v[52:55]
	v_mfma_f32_16x16x32_bf16 v[48:51], v[172:175], v[180:183], v[48:51]
	v_mfma_f32_16x16x32_bf16 v[36:39], v[164:167], v[188:191], v[36:39]
	v_mfma_f32_16x16x32_bf16 v[32:35], v[172:175], v[188:191], v[32:35]
	v_mfma_f32_16x16x32_bf16 v[20:23], v[164:167], v[196:199], v[20:23]
	v_mfma_f32_16x16x32_bf16 v[16:19], v[172:175], v[196:199], v[16:19]
	v_mfma_f32_16x16x32_bf16 v[4:7], v[164:167], v[204:207], v[4:7]
	v_mfma_f32_16x16x32_bf16 v[0:3], v[172:175], v[204:207], v[0:3]
	v_mfma_f32_16x16x32_bf16 v[52:55], v[168:171], v[184:187], v[52:55]
	v_mfma_f32_16x16x32_bf16 v[48:51], v[176:179], v[184:187], v[48:51]
	v_mfma_f32_16x16x32_bf16 v[36:39], v[168:171], v[192:195], v[36:39]
	v_mfma_f32_16x16x32_bf16 v[32:35], v[176:179], v[192:195], v[32:35]
	v_mfma_f32_16x16x32_bf16 v[20:23], v[168:171], v[200:203], v[20:23]
	v_mfma_f32_16x16x32_bf16 v[16:19], v[176:179], v[200:203], v[16:19]
	v_mfma_f32_16x16x32_bf16 v[4:7], v[168:171], v[208:211], v[4:7]
	v_mfma_f32_16x16x32_bf16 v[0:3], v[176:179], v[208:211], v[0:3]
	s_barrier
	s_setprio 0
	s_add_i32 s79, s79, 2
	s_add_u32 s72, s72, 0x100
	s_addc_u32 s73, s73, 0
	s_add_u32 s71, s71, 0x100
	s_addc_u32 s78, s78, 0
	s_cmpk_gt_u32 s79, 0x7d
	s_cbranch_scc0 .LBB0_1897
	s_and_b64 vcc, exec, s[58:59]
	s_cbranch_vccz .LBB0_1900
	s_barrier

.LBB0_2128:
	ds_read_b128 v[148:151], v179
	ds_read_b128 v[152:155], v179 offset:1024
	ds_read_b128 v[156:159], v179 offset:2048
	ds_read_b128 v[160:163], v179 offset:3072
	ds_read_b128 v[164:167], v180
	ds_read_b128 v[168:171], v180 offset:1024
	ds_read_b128 v[184:187], v180 offset:2048
	ds_read_b128 v[188:191], v180 offset:3072
	ds_read_b128 v[192:195], v181
	ds_read_b128 v[196:199], v181 offset:1024
	ds_read_b128 v[200:203], v181 offset:2048
	ds_read_b128 v[204:207], v181 offset:3072
	ds_read_b128 v[208:211], v181 offset:4096
	ds_read_b128 v[212:215], v181 offset:5120
	ds_read_b128 v[216:219], v181 offset:6144
	ds_read_b128 v[220:223], v181 offset:7168
	s_add_u32 s60, s84, 0xfff80080
	s_addc_u32 s61, s85, -1
	s_cmp_eq_u32 s95, 28
	s_cselect_b32 s89, s23, s61
	s_cselect_b32 s88, s79, s60
	s_cselect_b32 s87, s77, s97
	s_cselect_b32 s86, vcc_lo, vcc_hi
	v_lshl_add_u64 v[172:173], s[84:85], 0, v[140:141]
	s_add_i32 m0, s6, 0xc000
	s_nop 0
	global_load_lds_dwordx4 v[172:173], off
	v_lshl_add_u64 v[172:173], s[84:85], 0, v[142:143]
	s_add_i32 m0, s6, 0xe000
	s_nop 0
	global_load_lds_dwordx4 v[172:173], off
	s_waitcnt vmcnt(8)
	s_waitcnt lgkmcnt(0)
	s_barrier
	s_setprio 1
	v_mfma_f32_16x16x32_bf16 v[124:127], v[148:151], v[192:195], v[124:127]
	v_mfma_f32_16x16x32_bf16 v[120:123], v[156:159], v[192:195], v[120:123]
	v_mfma_f32_16x16x32_bf16 v[108:111], v[148:151], v[200:203], v[108:111]
	v_mfma_f32_16x16x32_bf16 v[104:107], v[156:159], v[200:203], v[104:107]
	v_mfma_f32_16x16x32_bf16 v[92:95], v[148:151], v[208:211], v[92:95]
	v_mfma_f32_16x16x32_bf16 v[88:91], v[156:159], v[208:211], v[88:91]
	v_mfma_f32_16x16x32_bf16 v[76:79], v[148:151], v[216:219], v[76:79]
	v_mfma_f32_16x16x32_bf16 v[72:75], v[156:159], v[216:219], v[72:75]
	v_mfma_f32_16x16x32_bf16 v[124:127], v[152:155], v[196:199], v[124:127]
	v_mfma_f32_16x16x32_bf16 v[120:123], v[160:163], v[196:199], v[120:123]
	v_mfma_f32_16x16x32_bf16 v[108:111], v[152:155], v[204:207], v[108:111]
	v_mfma_f32_16x16x32_bf16 v[104:107], v[160:163], v[204:207], v[104:107]
	v_mfma_f32_16x16x32_bf16 v[92:95], v[152:155], v[212:215], v[92:95]
	v_mfma_f32_16x16x32_bf16 v[88:91], v[160:163], v[212:215], v[88:91]
	v_mfma_f32_16x16x32_bf16 v[76:79], v[152:155], v[220:223], v[76:79]
	v_mfma_f32_16x16x32_bf16 v[72:75], v[160:163], v[220:223], v[72:75]
	v_mfma_f32_16x16x32_bf16 v[116:119], v[164:167], v[192:195], v[116:119]
	v_mfma_f32_16x16x32_bf16 v[112:115], v[184:187], v[192:195], v[112:115]
	v_mfma_f32_16x16x32_bf16 v[100:103], v[164:167], v[200:203], v[100:103]
	v_mfma_f32_16x16x32_bf16 v[96:99], v[184:187], v[200:203], v[96:99]
	v_mfma_f32_16x16x32_bf16 v[84:87], v[164:167], v[208:211], v[84:87]
	v_mfma_f32_16x16x32_bf16 v[80:83], v[184:187], v[208:211], v[80:83]
	v_mfma_f32_16x16x32_bf16 v[68:71], v[164:167], v[216:219], v[68:71]
	v_mfma_f32_16x16x32_bf16 v[64:67], v[184:187], v[216:219], v[64:67]
	v_mfma_f32_16x16x32_bf16 v[116:119], v[168:171], v[196:199], v[116:119]
	v_mfma_f32_16x16x32_bf16 v[112:115], v[188:191], v[196:199], v[112:115]
	v_mfma_f32_16x16x32_bf16 v[100:103], v[168:171], v[204:207], v[100:103]
	v_mfma_f32_16x16x32_bf16 v[96:99], v[188:191], v[204:207], v[96:99]
	v_mfma_f32_16x16x32_bf16 v[84:87], v[168:171], v[212:215], v[84:87]
	v_mfma_f32_16x16x32_bf16 v[80:83], v[188:191], v[212:215], v[80:83]
	v_mfma_f32_16x16x32_bf16 v[68:71], v[168:171], v[220:223], v[68:71]
	v_mfma_f32_16x16x32_bf16 v[64:67], v[188:191], v[220:223], v[64:67]
	s_barrier
	s_setprio 0
	ds_read_b128 v[192:195], v181 offset:16384
	ds_read_b128 v[196:199], v181 offset:17408
	ds_read_b128 v[200:203], v181 offset:18432
	ds_read_b128 v[204:207], v181 offset:19456
	ds_read_b128 v[208:211], v181 offset:20480
	ds_read_b128 v[212:215], v181 offset:21504
	ds_read_b128 v[216:219], v181 offset:22528
	ds_read_b128 v[220:223], v181 offset:23552
	s_add_i32 s60, s12, s94
	v_lshl_add_u64 v[172:173], s[86:87], 0, v[130:131]
	s_mov_b32 m0, s60
	s_nop 0
	global_load_lds_dwordx4 v[172:173], off
	s_add_i32 m0, s60, 0x2000
	s_add_u32 s60, s86, 0x80000
	v_lshl_add_u64 v[224:225], s[86:87], 0, v[134:135]
	s_addc_u32 s61, s87, 0
	s_add_i32 s96, s13, s94
	global_load_lds_dwordx4 v[224:225], off
	v_lshl_add_u64 v[226:227], s[60:61], 0, v[130:131]
	s_mov_b32 m0, s96
	v_lshl_add_u64 v[228:229], s[88:89], 0, v[132:133]
	global_load_lds_dwordx4 v[226:227], off
	v_lshl_add_u64 v[226:227], s[60:61], 0, v[134:135]
	s_add_i32 m0, s96, 0x2000
	s_nop 0
	global_load_lds_dwordx4 v[226:227], off
	v_lshl_add_u64 v[226:227], s[88:89], 0, v[128:129]
	s_mov_b32 m0, s6
	s_nop 0
	global_load_lds_dwordx4 v[226:227], off
	s_mov_b32 m0, s7
	s_nop 0
	global_load_lds_dwordx4 v[228:229], off
	s_waitcnt vmcnt(8)
	s_waitcnt lgkmcnt(0)
	s_barrier
	s_setprio 1
	v_mfma_f32_16x16x32_bf16 v[60:63], v[148:151], v[192:195], v[60:63]
	v_mfma_f32_16x16x32_bf16 v[56:59], v[156:159], v[192:195], v[56:59]
	v_mfma_f32_16x16x32_bf16 v[44:47], v[148:151], v[200:203], v[44:47]
	v_mfma_f32_16x16x32_bf16 v[40:43], v[156:159], v[200:203], v[40:43]
	v_mfma_f32_16x16x32_bf16 v[28:31], v[148:151], v[208:211], v[28:31]
	v_mfma_f32_16x16x32_bf16 v[24:27], v[156:159], v[208:211], v[24:27]
	v_mfma_f32_16x16x32_bf16 v[12:15], v[148:151], v[216:219], v[12:15]
	v_mfma_f32_16x16x32_bf16 v[8:11], v[156:159], v[216:219], v[8:11]
	v_mfma_f32_16x16x32_bf16 v[60:63], v[152:155], v[196:199], v[60:63]
	v_mfma_f32_16x16x32_bf16 v[56:59], v[160:163], v[196:199], v[56:59]
	v_mfma_f32_16x16x32_bf16 v[44:47], v[152:155], v[204:207], v[44:47]
	v_mfma_f32_16x16x32_bf16 v[40:43], v[160:163], v[204:207], v[40:43]
	v_mfma_f32_16x16x32_bf16 v[28:31], v[152:155], v[212:215], v[28:31]
	v_mfma_f32_16x16x32_bf16 v[24:27], v[160:163], v[212:215], v[24:27]
	v_mfma_f32_16x16x32_bf16 v[12:15], v[152:155], v[220:223], v[12:15]
	v_mfma_f32_16x16x32_bf16 v[8:11], v[160:163], v[220:223], v[8:11]
	v_mfma_f32_16x16x32_bf16 v[52:55], v[164:167], v[192:195], v[52:55]
	v_mfma_f32_16x16x32_bf16 v[48:51], v[184:187], v[192:195], v[48:51]
	v_mfma_f32_16x16x32_bf16 v[36:39], v[164:167], v[200:203], v[36:39]
	v_mfma_f32_16x16x32_bf16 v[32:35], v[184:187], v[200:203], v[32:35]
	v_mfma_f32_16x16x32_bf16 v[20:23], v[164:167], v[208:211], v[20:23]
	v_mfma_f32_16x16x32_bf16 v[16:19], v[184:187], v[208:211], v[16:19]
	v_mfma_f32_16x16x32_bf16 v[4:7], v[164:167], v[216:219], v[4:7]
	v_mfma_f32_16x16x32_bf16 v[0:3], v[184:187], v[216:219], v[0:3]
	v_mfma_f32_16x16x32_bf16 v[52:55], v[168:171], v[196:199], v[52:55]
	v_mfma_f32_16x16x32_bf16 v[48:51], v[188:191], v[196:199], v[48:51]
	v_mfma_f32_16x16x32_bf16 v[36:39], v[168:171], v[204:207], v[36:39]
	v_mfma_f32_16x16x32_bf16 v[32:35], v[188:191], v[204:207], v[32:35]
	v_mfma_f32_16x16x32_bf16 v[20:23], v[168:171], v[212:215], v[20:23]
	v_mfma_f32_16x16x32_bf16 v[16:19], v[188:191], v[212:215], v[16:19]
	v_mfma_f32_16x16x32_bf16 v[4:7], v[168:171], v[220:223], v[4:7]
	v_mfma_f32_16x16x32_bf16 v[0:3], v[188:191], v[220:223], v[0:3]
	s_barrier
	s_setprio 0
	s_add_i32 s96, 0, 0x18000
	v_add_u32_e32 v136, s96, v175
	ds_read_b128 v[148:151], v136
	ds_read_b128 v[152:155], v136 offset:1024
	ds_read_b128 v[156:159], v136 offset:2048
	ds_read_b128 v[160:163], v136 offset:3072
	s_add_i32 s8, 0, 0x1c000
	v_add_u32_e32 v136, s8, v175
	ds_read_b128 v[164:167], v136
	ds_read_b128 v[168:171], v136 offset:1024
	ds_read_b128 v[184:187], v136 offset:2048
	ds_read_b128 v[188:191], v136 offset:3072
	ds_read_b128 v[192:195], v181 offset:32768
	ds_read_b128 v[196:199], v181 offset:33792
	ds_read_b128 v[200:203], v181 offset:34816
	ds_read_b128 v[204:207], v181 offset:35840
	ds_read_b128 v[208:211], v181 offset:36864
	ds_read_b128 v[212:215], v181 offset:37888
	ds_read_b128 v[216:219], v181 offset:38912
	ds_read_b128 v[220:223], v181 offset:39936
	s_add_u32 s60, s88, 0x80000
	s_addc_u32 s61, s89, 0
	s_mov_b32 m0, s34
	v_lshl_add_u64 v[230:231], s[60:61], 0, v[128:129]
	global_load_lds_dwordx4 v[230:231], off
	v_lshl_add_u64 v[230:231], s[60:61], 0, v[132:133]
	s_mov_b32 m0, s46
	s_nop 0
	global_load_lds_dwordx4 v[230:231], off
	s_waitcnt vmcnt(8)
	s_waitcnt lgkmcnt(0)
	s_barrier
	s_setprio 1
	v_mfma_f32_16x16x32_bf16 v[124:127], v[148:151], v[192:195], v[124:127]
	v_mfma_f32_16x16x32_bf16 v[120:123], v[156:159], v[192:195], v[120:123]
	v_mfma_f32_16x16x32_bf16 v[108:111], v[148:151], v[200:203], v[108:111]
	v_mfma_f32_16x16x32_bf16 v[104:107], v[156:159], v[200:203], v[104:107]
	v_mfma_f32_16x16x32_bf16 v[92:95], v[148:151], v[208:211], v[92:95]
	v_mfma_f32_16x16x32_bf16 v[88:91], v[156:159], v[208:211], v[88:91]
	v_mfma_f32_16x16x32_bf16 v[76:79], v[148:151], v[216:219], v[76:79]
	v_mfma_f32_16x16x32_bf16 v[72:75], v[156:159], v[216:219], v[72:75]
	v_mfma_f32_16x16x32_bf16 v[124:127], v[152:155], v[196:199], v[124:127]
	v_mfma_f32_16x16x32_bf16 v[120:123], v[160:163], v[196:199], v[120:123]
	v_mfma_f32_16x16x32_bf16 v[108:111], v[152:155], v[204:207], v[108:111]
	v_mfma_f32_16x16x32_bf16 v[104:107], v[160:163], v[204:207], v[104:107]
	v_mfma_f32_16x16x32_bf16 v[92:95], v[152:155], v[212:215], v[92:95]
	v_mfma_f32_16x16x32_bf16 v[88:91], v[160:163], v[212:215], v[88:91]
	v_mfma_f32_16x16x32_bf16 v[76:79], v[152:155], v[220:223], v[76:79]
	v_mfma_f32_16x16x32_bf16 v[72:75], v[160:163], v[220:223], v[72:75]
	v_mfma_f32_16x16x32_bf16 v[116:119], v[164:167], v[192:195], v[116:119]
	v_mfma_f32_16x16x32_bf16 v[112:115], v[184:187], v[192:195], v[112:115]
	v_mfma_f32_16x16x32_bf16 v[100:103], v[164:167], v[200:203], v[100:103]
	v_mfma_f32_16x16x32_bf16 v[96:99], v[184:187], v[200:203], v[96:99]
	v_mfma_f32_16x16x32_bf16 v[84:87], v[164:167], v[208:211], v[84:87]
	v_mfma_f32_16x16x32_bf16 v[80:83], v[184:187], v[208:211], v[80:83]
	v_mfma_f32_16x16x32_bf16 v[68:71], v[164:167], v[216:219], v[68:71]
	v_mfma_f32_16x16x32_bf16 v[64:67], v[184:187], v[216:219], v[64:67]
	v_mfma_f32_16x16x32_bf16 v[116:119], v[168:171], v[196:199], v[116:119]
	v_mfma_f32_16x16x32_bf16 v[112:115], v[188:191], v[196:199], v[112:115]
	v_mfma_f32_16x16x32_bf16 v[100:103], v[168:171], v[204:207], v[100:103]
	v_mfma_f32_16x16x32_bf16 v[96:99], v[188:191], v[204:207], v[96:99]
	v_mfma_f32_16x16x32_bf16 v[84:87], v[168:171], v[212:215], v[84:87]
	v_mfma_f32_16x16x32_bf16 v[80:83], v[188:191], v[212:215], v[80:83]
	v_mfma_f32_16x16x32_bf16 v[68:71], v[168:171], v[220:223], v[68:71]
	v_mfma_f32_16x16x32_bf16 v[64:67], v[188:191], v[220:223], v[64:67]
	s_barrier
	s_setprio 0
	ds_read_b128 v[192:195], v181 offset:49152
	ds_read_b128 v[196:199], v181 offset:50176
	ds_read_b128 v[200:203], v181 offset:51200
	ds_read_b128 v[204:207], v181 offset:52224
	ds_read_b128 v[208:211], v181 offset:53248
	ds_read_b128 v[212:215], v181 offset:54272
	ds_read_b128 v[216:219], v181 offset:55296
	ds_read_b128 v[220:223], v181 offset:56320
	s_add_i32 s9, s96, s94
	v_lshl_add_u64 v[172:173], v[172:173], 0, s[74:75]
	s_mov_b32 m0, s9
	s_nop 0
	global_load_lds_dwordx4 v[172:173], off
	s_add_i32 m0, s9, 0x2000
	s_add_u32 s60, s86, 0x80080
	v_lshl_add_u64 v[172:173], v[224:225], 0, s[74:75]
	s_addc_u32 s61, s87, 0
	s_add_i32 s8, s8, s94
	global_load_lds_dwordx4 v[172:173], off
	v_lshl_add_u64 v[172:173], s[60:61], 0, v[130:131]
	s_mov_b32 m0, s8
	s_nop 0
	global_load_lds_dwordx4 v[172:173], off
	v_lshl_add_u64 v[172:173], s[60:61], 0, v[134:135]
	s_add_i32 m0, s8, 0x2000
	s_nop 0
	global_load_lds_dwordx4 v[172:173], off
	v_lshl_add_u64 v[172:173], v[226:227], 0, s[74:75]
	s_mov_b32 m0, s56
	s_nop 0
	global_load_lds_dwordx4 v[172:173], off
	v_lshl_add_u64 v[172:173], v[228:229], 0, s[74:75]
	s_mov_b32 m0, s57
	s_nop 0
	global_load_lds_dwordx4 v[172:173], off
	s_waitcnt vmcnt(8)
	s_waitcnt lgkmcnt(0)
	s_barrier
	s_setprio 1
	v_mfma_f32_16x16x32_bf16 v[60:63], v[148:151], v[192:195], v[60:63]
	v_mfma_f32_16x16x32_bf16 v[56:59], v[156:159], v[192:195], v[56:59]
	v_mfma_f32_16x16x32_bf16 v[44:47], v[148:151], v[200:203], v[44:47]
	v_mfma_f32_16x16x32_bf16 v[40:43], v[156:159], v[200:203], v[40:43]
	v_mfma_f32_16x16x32_bf16 v[28:31], v[148:151], v[208:211], v[28:31]
	v_mfma_f32_16x16x32_bf16 v[24:27], v[156:159], v[208:211], v[24:27]
	v_mfma_f32_16x16x32_bf16 v[12:15], v[148:151], v[216:219], v[12:15]
	v_mfma_f32_16x16x32_bf16 v[8:11], v[156:159], v[216:219], v[8:11]
	v_mfma_f32_16x16x32_bf16 v[60:63], v[152:155], v[196:199], v[60:63]
	v_mfma_f32_16x16x32_bf16 v[56:59], v[160:163], v[196:199], v[56:59]
	v_mfma_f32_16x16x32_bf16 v[44:47], v[152:155], v[204:207], v[44:47]
	v_mfma_f32_16x16x32_bf16 v[40:43], v[160:163], v[204:207], v[40:43]
	v_mfma_f32_16x16x32_bf16 v[28:31], v[152:155], v[212:215], v[28:31]
	v_mfma_f32_16x16x32_bf16 v[24:27], v[160:163], v[212:215], v[24:27]
	v_mfma_f32_16x16x32_bf16 v[12:15], v[152:155], v[220:223], v[12:15]
	v_mfma_f32_16x16x32_bf16 v[8:11], v[160:163], v[220:223], v[8:11]
	v_mfma_f32_16x16x32_bf16 v[52:55], v[164:167], v[192:195], v[52:55]
	v_mfma_f32_16x16x32_bf16 v[48:51], v[184:187], v[192:195], v[48:51]
	v_mfma_f32_16x16x32_bf16 v[36:39], v[164:167], v[200:203], v[36:39]
	v_mfma_f32_16x16x32_bf16 v[32:35], v[184:187], v[200:203], v[32:35]
	v_mfma_f32_16x16x32_bf16 v[20:23], v[164:167], v[208:211], v[20:23]
	v_mfma_f32_16x16x32_bf16 v[16:19], v[184:187], v[208:211], v[16:19]
	v_mfma_f32_16x16x32_bf16 v[4:7], v[164:167], v[216:219], v[4:7]
	v_mfma_f32_16x16x32_bf16 v[0:3], v[184:187], v[216:219], v[0:3]
	v_mfma_f32_16x16x32_bf16 v[52:55], v[168:171], v[196:199], v[52:55]
	v_mfma_f32_16x16x32_bf16 v[48:51], v[188:191], v[196:199], v[48:51]
	v_mfma_f32_16x16x32_bf16 v[36:39], v[168:171], v[204:207], v[36:39]
	v_mfma_f32_16x16x32_bf16 v[32:35], v[188:191], v[204:207], v[32:35]
	v_mfma_f32_16x16x32_bf16 v[20:23], v[168:171], v[212:215], v[20:23]
	v_mfma_f32_16x16x32_bf16 v[16:19], v[188:191], v[212:215], v[16:19]
	v_mfma_f32_16x16x32_bf16 v[4:7], v[168:171], v[220:223], v[4:7]
	v_mfma_f32_16x16x32_bf16 v[0:3], v[188:191], v[220:223], v[0:3]
	s_barrier
	s_setprio 0
	s_add_i32 s95, s95, 2
	s_add_u32 s84, s84, 0x100
	s_addc_u32 s85, s85, 0
	s_add_u32 vcc_hi, vcc_hi, 0x100
	s_addc_u32 s97, s97, 0
	s_cmp_gt_u32 s95, 29
	s_cbranch_scc0 .LBB0_2128
	s_and_b64 vcc, exec, s[58:59]
	s_cbranch_vccz .LBB0_2131
	s_barrier

.LBB0_2459:
	ds_read_b128 v[148:151], v163
	ds_read_b128 v[152:155], v163 offset:1024
	ds_read_b128 v[168:171], v163 offset:2048
	ds_read_b128 v[172:175], v163 offset:3072
	ds_read_b128 v[176:179], v164
	ds_read_b128 v[180:183], v164 offset:1024
	ds_read_b128 v[184:187], v164 offset:2048
	ds_read_b128 v[188:191], v164 offset:3072
	ds_read_b128 v[192:195], v165
	ds_read_b128 v[196:199], v165 offset:1024
	ds_read_b128 v[200:203], v165 offset:2048
	ds_read_b128 v[204:207], v165 offset:3072
	ds_read_b128 v[208:211], v165 offset:4096
	ds_read_b128 v[212:215], v165 offset:5120
	ds_read_b128 v[216:219], v165 offset:6144
	ds_read_b128 v[220:223], v165 offset:7168
	s_add_u32 s16, s70, 0x100
	s_addc_u32 s17, s71, 0
	s_cmp_eq_u32 s86, 8
	s_cselect_b32 s75, s23, s17
	s_cselect_b32 s74, s22, s16
	s_cselect_b32 s73, s49, s85
	s_cselect_b32 s72, s48, s84
	v_lshl_add_u64 v[156:157], s[70:71], 0, v[140:141]
	s_add_i32 m0, s12, 0xc000
	s_nop 0
	global_load_lds_dwordx4 v[156:157], off
	v_lshl_add_u64 v[156:157], s[70:71], 0, v[142:143]
	s_add_i32 m0, s12, 0xe000
	s_nop 0
	global_load_lds_dwordx4 v[156:157], off
	s_waitcnt vmcnt(8)
	s_waitcnt lgkmcnt(0)
	s_barrier
	s_setprio 1
	v_mfma_f32_16x16x32_bf16 v[124:127], v[148:151], v[192:195], v[124:127]
	v_mfma_f32_16x16x32_bf16 v[120:123], v[168:171], v[192:195], v[120:123]
	v_mfma_f32_16x16x32_bf16 v[108:111], v[148:151], v[200:203], v[108:111]
	v_mfma_f32_16x16x32_bf16 v[104:107], v[168:171], v[200:203], v[104:107]
	v_mfma_f32_16x16x32_bf16 v[92:95], v[148:151], v[208:211], v[92:95]
	v_mfma_f32_16x16x32_bf16 v[88:91], v[168:171], v[208:211], v[88:91]
	v_mfma_f32_16x16x32_bf16 v[76:79], v[148:151], v[216:219], v[76:79]
	v_mfma_f32_16x16x32_bf16 v[72:75], v[168:171], v[216:219], v[72:75]
	v_mfma_f32_16x16x32_bf16 v[124:127], v[152:155], v[196:199], v[124:127]
	v_mfma_f32_16x16x32_bf16 v[120:123], v[172:175], v[196:199], v[120:123]
	v_mfma_f32_16x16x32_bf16 v[108:111], v[152:155], v[204:207], v[108:111]
	v_mfma_f32_16x16x32_bf16 v[104:107], v[172:175], v[204:207], v[104:107]
	v_mfma_f32_16x16x32_bf16 v[92:95], v[152:155], v[212:215], v[92:95]
	v_mfma_f32_16x16x32_bf16 v[88:91], v[172:175], v[212:215], v[88:91]
	v_mfma_f32_16x16x32_bf16 v[76:79], v[152:155], v[220:223], v[76:79]
	v_mfma_f32_16x16x32_bf16 v[72:75], v[172:175], v[220:223], v[72:75]
	v_mfma_f32_16x16x32_bf16 v[116:119], v[176:179], v[192:195], v[116:119]
	v_mfma_f32_16x16x32_bf16 v[112:115], v[184:187], v[192:195], v[112:115]
	v_mfma_f32_16x16x32_bf16 v[100:103], v[176:179], v[200:203], v[100:103]
	v_mfma_f32_16x16x32_bf16 v[96:99], v[184:187], v[200:203], v[96:99]
	v_mfma_f32_16x16x32_bf16 v[84:87], v[176:179], v[208:211], v[84:87]
	v_mfma_f32_16x16x32_bf16 v[80:83], v[184:187], v[208:211], v[80:83]
	v_mfma_f32_16x16x32_bf16 v[68:71], v[176:179], v[216:219], v[68:71]
	v_mfma_f32_16x16x32_bf16 v[64:67], v[184:187], v[216:219], v[64:67]
	v_mfma_f32_16x16x32_bf16 v[116:119], v[180:183], v[196:199], v[116:119]
	v_mfma_f32_16x16x32_bf16 v[112:115], v[188:191], v[196:199], v[112:115]
	v_mfma_f32_16x16x32_bf16 v[100:103], v[180:183], v[204:207], v[100:103]
	v_mfma_f32_16x16x32_bf16 v[96:99], v[188:191], v[204:207], v[96:99]
	v_mfma_f32_16x16x32_bf16 v[84:87], v[180:183], v[212:215], v[84:87]
	v_mfma_f32_16x16x32_bf16 v[80:83], v[188:191], v[212:215], v[80:83]
	v_mfma_f32_16x16x32_bf16 v[68:71], v[180:183], v[220:223], v[68:71]
	v_mfma_f32_16x16x32_bf16 v[64:67], v[188:191], v[220:223], v[64:67]
	s_barrier
	s_setprio 0
	ds_read_b128 v[192:195], v165 offset:16384
	ds_read_b128 v[196:199], v165 offset:17408
	ds_read_b128 v[200:203], v165 offset:18432
	ds_read_b128 v[204:207], v165 offset:19456
	ds_read_b128 v[208:211], v165 offset:20480
	ds_read_b128 v[212:215], v165 offset:21504
	ds_read_b128 v[216:219], v165 offset:22528
	ds_read_b128 v[220:223], v165 offset:23552
	s_add_i32 s8, s76, s94
	v_lshl_add_u64 v[156:157], s[72:73], 0, v[130:131]
	s_mov_b32 m0, s8
	s_nop 0
	global_load_lds_dwordx4 v[156:157], off
	s_add_i32 m0, s8, 0x2000
	s_add_u32 s60, s72, 0x30000
	v_lshl_add_u64 v[224:225], s[72:73], 0, v[134:135]
	s_addc_u32 s61, s73, 0
	s_add_i32 s8, s77, s94
	global_load_lds_dwordx4 v[224:225], off
	v_lshl_add_u64 v[226:227], s[60:61], 0, v[130:131]
	s_mov_b32 m0, s8
	v_lshl_add_u64 v[228:229], s[74:75], 0, v[132:133]
	global_load_lds_dwordx4 v[226:227], off
	v_lshl_add_u64 v[226:227], s[60:61], 0, v[134:135]
	s_add_i32 m0, s8, 0x2000
	s_nop 0
	global_load_lds_dwordx4 v[226:227], off
	v_lshl_add_u64 v[226:227], s[74:75], 0, v[128:129]
	s_mov_b32 m0, s12
	s_nop 0
	global_load_lds_dwordx4 v[226:227], off
	s_mov_b32 m0, s13
	s_nop 0
	global_load_lds_dwordx4 v[228:229], off
	s_waitcnt vmcnt(8)
	s_waitcnt lgkmcnt(0)
	s_barrier
	s_setprio 1
	v_mfma_f32_16x16x32_bf16 v[60:63], v[148:151], v[192:195], v[60:63]
	v_mfma_f32_16x16x32_bf16 v[56:59], v[168:171], v[192:195], v[56:59]
	v_mfma_f32_16x16x32_bf16 v[44:47], v[148:151], v[200:203], v[44:47]
	v_mfma_f32_16x16x32_bf16 v[40:43], v[168:171], v[200:203], v[40:43]
	v_mfma_f32_16x16x32_bf16 v[28:31], v[148:151], v[208:211], v[28:31]
	v_mfma_f32_16x16x32_bf16 v[24:27], v[168:171], v[208:211], v[24:27]
	v_mfma_f32_16x16x32_bf16 v[12:15], v[148:151], v[216:219], v[12:15]
	v_mfma_f32_16x16x32_bf16 v[8:11], v[168:171], v[216:219], v[8:11]
	v_mfma_f32_16x16x32_bf16 v[60:63], v[152:155], v[196:199], v[60:63]
	v_mfma_f32_16x16x32_bf16 v[56:59], v[172:175], v[196:199], v[56:59]
	v_mfma_f32_16x16x32_bf16 v[44:47], v[152:155], v[204:207], v[44:47]
	v_mfma_f32_16x16x32_bf16 v[40:43], v[172:175], v[204:207], v[40:43]
	v_mfma_f32_16x16x32_bf16 v[28:31], v[152:155], v[212:215], v[28:31]
	v_mfma_f32_16x16x32_bf16 v[24:27], v[172:175], v[212:215], v[24:27]
	v_mfma_f32_16x16x32_bf16 v[12:15], v[152:155], v[220:223], v[12:15]
	v_mfma_f32_16x16x32_bf16 v[8:11], v[172:175], v[220:223], v[8:11]
	v_mfma_f32_16x16x32_bf16 v[52:55], v[176:179], v[192:195], v[52:55]
	v_mfma_f32_16x16x32_bf16 v[48:51], v[184:187], v[192:195], v[48:51]
	v_mfma_f32_16x16x32_bf16 v[36:39], v[176:179], v[200:203], v[36:39]
	v_mfma_f32_16x16x32_bf16 v[32:35], v[184:187], v[200:203], v[32:35]
	v_mfma_f32_16x16x32_bf16 v[20:23], v[176:179], v[208:211], v[20:23]
	v_mfma_f32_16x16x32_bf16 v[16:19], v[184:187], v[208:211], v[16:19]
	v_mfma_f32_16x16x32_bf16 v[4:7], v[176:179], v[216:219], v[4:7]
	v_mfma_f32_16x16x32_bf16 v[0:3], v[184:187], v[216:219], v[0:3]
	v_mfma_f32_16x16x32_bf16 v[52:55], v[180:183], v[196:199], v[52:55]
	v_mfma_f32_16x16x32_bf16 v[48:51], v[188:191], v[196:199], v[48:51]
	v_mfma_f32_16x16x32_bf16 v[36:39], v[180:183], v[204:207], v[36:39]
	v_mfma_f32_16x16x32_bf16 v[32:35], v[188:191], v[204:207], v[32:35]
	v_mfma_f32_16x16x32_bf16 v[20:23], v[180:183], v[212:215], v[20:23]
	v_mfma_f32_16x16x32_bf16 v[16:19], v[188:191], v[212:215], v[16:19]
	v_mfma_f32_16x16x32_bf16 v[4:7], v[180:183], v[220:223], v[4:7]
	v_mfma_f32_16x16x32_bf16 v[0:3], v[188:191], v[220:223], v[0:3]
	s_barrier
	s_setprio 0
	s_add_i32 s8, 0, 0x18000
	v_add_u32_e32 v136, s8, v159
	ds_read_b128 v[148:151], v136
	ds_read_b128 v[152:155], v136 offset:1024
	ds_read_b128 v[168:171], v136 offset:2048
	ds_read_b128 v[172:175], v136 offset:3072
	s_add_i32 s9, 0, 0x1c000
	v_add_u32_e32 v136, s9, v159
	ds_read_b128 v[176:179], v136
	ds_read_b128 v[180:183], v136 offset:1024
	ds_read_b128 v[184:187], v136 offset:2048
	ds_read_b128 v[188:191], v136 offset:3072
	ds_read_b128 v[192:195], v165 offset:32768
	ds_read_b128 v[196:199], v165 offset:33792
	ds_read_b128 v[200:203], v165 offset:34816
	ds_read_b128 v[204:207], v165 offset:35840
	ds_read_b128 v[208:211], v165 offset:36864
	ds_read_b128 v[212:215], v165 offset:37888
	ds_read_b128 v[216:219], v165 offset:38912
	ds_read_b128 v[220:223], v165 offset:39936
	s_add_u32 s60, s74, 0x60000
	s_addc_u32 s61, s75, 0
	s_mov_b32 m0, s29
	v_lshl_add_u64 v[230:231], s[60:61], 0, v[128:129]
	global_load_lds_dwordx4 v[230:231], off
	v_lshl_add_u64 v[230:231], s[60:61], 0, v[132:133]
	s_mov_b32 m0, s30
	s_nop 0
	global_load_lds_dwordx4 v[230:231], off
	s_waitcnt vmcnt(8)
	s_waitcnt lgkmcnt(0)
	s_barrier
	s_setprio 1
	v_mfma_f32_16x16x32_bf16 v[124:127], v[148:151], v[192:195], v[124:127]
	v_mfma_f32_16x16x32_bf16 v[120:123], v[168:171], v[192:195], v[120:123]
	v_mfma_f32_16x16x32_bf16 v[108:111], v[148:151], v[200:203], v[108:111]
	v_mfma_f32_16x16x32_bf16 v[104:107], v[168:171], v[200:203], v[104:107]
	v_mfma_f32_16x16x32_bf16 v[92:95], v[148:151], v[208:211], v[92:95]
	v_mfma_f32_16x16x32_bf16 v[88:91], v[168:171], v[208:211], v[88:91]
	v_mfma_f32_16x16x32_bf16 v[76:79], v[148:151], v[216:219], v[76:79]
	v_mfma_f32_16x16x32_bf16 v[72:75], v[168:171], v[216:219], v[72:75]
	v_mfma_f32_16x16x32_bf16 v[124:127], v[152:155], v[196:199], v[124:127]
	v_mfma_f32_16x16x32_bf16 v[120:123], v[172:175], v[196:199], v[120:123]
	v_mfma_f32_16x16x32_bf16 v[108:111], v[152:155], v[204:207], v[108:111]
	v_mfma_f32_16x16x32_bf16 v[104:107], v[172:175], v[204:207], v[104:107]
	v_mfma_f32_16x16x32_bf16 v[92:95], v[152:155], v[212:215], v[92:95]
	v_mfma_f32_16x16x32_bf16 v[88:91], v[172:175], v[212:215], v[88:91]
	v_mfma_f32_16x16x32_bf16 v[76:79], v[152:155], v[220:223], v[76:79]
	v_mfma_f32_16x16x32_bf16 v[72:75], v[172:175], v[220:223], v[72:75]
	v_mfma_f32_16x16x32_bf16 v[116:119], v[176:179], v[192:195], v[116:119]
	v_mfma_f32_16x16x32_bf16 v[112:115], v[184:187], v[192:195], v[112:115]
	v_mfma_f32_16x16x32_bf16 v[100:103], v[176:179], v[200:203], v[100:103]
	v_mfma_f32_16x16x32_bf16 v[96:99], v[184:187], v[200:203], v[96:99]
	v_mfma_f32_16x16x32_bf16 v[84:87], v[176:179], v[208:211], v[84:87]
	v_mfma_f32_16x16x32_bf16 v[80:83], v[184:187], v[208:211], v[80:83]
	v_mfma_f32_16x16x32_bf16 v[68:71], v[176:179], v[216:219], v[68:71]
	v_mfma_f32_16x16x32_bf16 v[64:67], v[184:187], v[216:219], v[64:67]
	v_mfma_f32_16x16x32_bf16 v[116:119], v[180:183], v[196:199], v[116:119]
	v_mfma_f32_16x16x32_bf16 v[112:115], v[188:191], v[196:199], v[112:115]
	v_mfma_f32_16x16x32_bf16 v[100:103], v[180:183], v[204:207], v[100:103]
	v_mfma_f32_16x16x32_bf16 v[96:99], v[188:191], v[204:207], v[96:99]
	v_mfma_f32_16x16x32_bf16 v[84:87], v[180:183], v[212:215], v[84:87]
	v_mfma_f32_16x16x32_bf16 v[80:83], v[188:191], v[212:215], v[80:83]
	v_mfma_f32_16x16x32_bf16 v[68:71], v[180:183], v[220:223], v[68:71]
	v_mfma_f32_16x16x32_bf16 v[64:67], v[188:191], v[220:223], v[64:67]
	s_barrier
	s_setprio 0
	ds_read_b128 v[192:195], v165 offset:49152
	ds_read_b128 v[196:199], v165 offset:50176
	ds_read_b128 v[200:203], v165 offset:51200
	ds_read_b128 v[204:207], v165 offset:52224
	ds_read_b128 v[208:211], v165 offset:53248
	ds_read_b128 v[212:215], v165 offset:54272
	ds_read_b128 v[216:219], v165 offset:55296
	ds_read_b128 v[220:223], v165 offset:56320
	s_add_i32 s8, s8, s94
	v_lshl_add_u64 v[156:157], v[156:157], 0, s[20:21]
	s_mov_b32 m0, s8
	s_nop 0
	global_load_lds_dwordx4 v[156:157], off
	s_add_i32 m0, s8, 0x2000
	s_add_u32 s60, s72, 0x30080
	v_lshl_add_u64 v[156:157], v[224:225], 0, s[20:21]
	s_addc_u32 s61, s73, 0
	s_add_i32 s8, s9, s94
	global_load_lds_dwordx4 v[156:157], off
	v_lshl_add_u64 v[156:157], s[60:61], 0, v[130:131]
	s_mov_b32 m0, s8
	s_nop 0
	global_load_lds_dwordx4 v[156:157], off
	v_lshl_add_u64 v[156:157], s[60:61], 0, v[134:135]
	s_add_i32 m0, s8, 0x2000
	s_nop 0
	global_load_lds_dwordx4 v[156:157], off
	v_lshl_add_u64 v[156:157], v[226:227], 0, s[20:21]
	s_mov_b32 m0, s46
	s_nop 0
	global_load_lds_dwordx4 v[156:157], off
	v_lshl_add_u64 v[156:157], v[228:229], 0, s[20:21]
	s_mov_b32 m0, s56
	s_nop 0
	global_load_lds_dwordx4 v[156:157], off
	s_waitcnt vmcnt(8)
	s_waitcnt lgkmcnt(0)
	s_barrier
	s_setprio 1
	v_mfma_f32_16x16x32_bf16 v[60:63], v[148:151], v[192:195], v[60:63]
	v_mfma_f32_16x16x32_bf16 v[56:59], v[168:171], v[192:195], v[56:59]
	v_mfma_f32_16x16x32_bf16 v[44:47], v[148:151], v[200:203], v[44:47]
	v_mfma_f32_16x16x32_bf16 v[40:43], v[168:171], v[200:203], v[40:43]
	v_mfma_f32_16x16x32_bf16 v[28:31], v[148:151], v[208:211], v[28:31]
	v_mfma_f32_16x16x32_bf16 v[24:27], v[168:171], v[208:211], v[24:27]
	v_mfma_f32_16x16x32_bf16 v[12:15], v[148:151], v[216:219], v[12:15]
	v_mfma_f32_16x16x32_bf16 v[8:11], v[168:171], v[216:219], v[8:11]
	v_mfma_f32_16x16x32_bf16 v[60:63], v[152:155], v[196:199], v[60:63]
	v_mfma_f32_16x16x32_bf16 v[56:59], v[172:175], v[196:199], v[56:59]
	v_mfma_f32_16x16x32_bf16 v[44:47], v[152:155], v[204:207], v[44:47]
	v_mfma_f32_16x16x32_bf16 v[40:43], v[172:175], v[204:207], v[40:43]
	v_mfma_f32_16x16x32_bf16 v[28:31], v[152:155], v[212:215], v[28:31]
	v_mfma_f32_16x16x32_bf16 v[24:27], v[172:175], v[212:215], v[24:27]
	v_mfma_f32_16x16x32_bf16 v[12:15], v[152:155], v[220:223], v[12:15]
	v_mfma_f32_16x16x32_bf16 v[8:11], v[172:175], v[220:223], v[8:11]
	v_mfma_f32_16x16x32_bf16 v[52:55], v[176:179], v[192:195], v[52:55]
	v_mfma_f32_16x16x32_bf16 v[48:51], v[184:187], v[192:195], v[48:51]
	v_mfma_f32_16x16x32_bf16 v[36:39], v[176:179], v[200:203], v[36:39]
	v_mfma_f32_16x16x32_bf16 v[32:35], v[184:187], v[200:203], v[32:35]
	v_mfma_f32_16x16x32_bf16 v[20:23], v[176:179], v[208:211], v[20:23]
	v_mfma_f32_16x16x32_bf16 v[16:19], v[184:187], v[208:211], v[16:19]
	v_mfma_f32_16x16x32_bf16 v[4:7], v[176:179], v[216:219], v[4:7]
	v_mfma_f32_16x16x32_bf16 v[0:3], v[184:187], v[216:219], v[0:3]
	v_mfma_f32_16x16x32_bf16 v[52:55], v[180:183], v[196:199], v[52:55]
	v_mfma_f32_16x16x32_bf16 v[48:51], v[188:191], v[196:199], v[48:51]
	v_mfma_f32_16x16x32_bf16 v[36:39], v[180:183], v[204:207], v[36:39]
	v_mfma_f32_16x16x32_bf16 v[32:35], v[188:191], v[204:207], v[32:35]
	v_mfma_f32_16x16x32_bf16 v[20:23], v[180:183], v[212:215], v[20:23]
	v_mfma_f32_16x16x32_bf16 v[16:19], v[188:191], v[212:215], v[16:19]
	v_mfma_f32_16x16x32_bf16 v[4:7], v[180:183], v[220:223], v[4:7]
	v_mfma_f32_16x16x32_bf16 v[0:3], v[188:191], v[220:223], v[0:3]
	s_barrier
	s_setprio 0
	s_add_i32 s86, s86, 2
	s_add_u32 s84, s84, 0x100
	s_addc_u32 s85, s85, 0
	s_cmp_gt_u32 s86, 9
	s_mov_b64 s[70:71], s[16:17]
	s_cbranch_scc0 .LBB0_2459
	s_and_b64 vcc, exec, s[58:59]
	s_cbranch_vccz .LBB0_2462
	s_barrier

.LBB0_2535:
	ds_read_b128 v[146:149], v155
	ds_read_b128 v[160:163], v155 offset:1024
	ds_read_b128 v[164:167], v155 offset:2048
	ds_read_b128 v[168:171], v155 offset:3072
	ds_read_b128 v[172:175], v156
	ds_read_b128 v[176:179], v156 offset:1024
	ds_read_b128 v[180:183], v156 offset:2048
	ds_read_b128 v[184:187], v156 offset:3072
	ds_read_b128 v[188:191], v157
	ds_read_b128 v[192:195], v157 offset:1024
	ds_read_b128 v[196:199], v157 offset:2048
	ds_read_b128 v[200:203], v157 offset:3072
	ds_read_b128 v[204:207], v157 offset:4096
	ds_read_b128 v[208:211], v157 offset:5120
	ds_read_b128 v[212:215], v157 offset:6144
	ds_read_b128 v[216:219], v157 offset:7168
	s_add_u32 s16, s68, 0x100
	s_addc_u32 s17, s69, 0
	s_cmp_eq_u32 s80, 4
	s_cselect_b32 s73, s49, s17
	s_cselect_b32 s72, s48, s16
	s_cselect_b32 s71, s43, s79
	s_cselect_b32 s70, s77, s78
	v_lshl_add_u64 v[220:221], s[68:69], 0, v[138:139]
	s_add_i32 m0, s29, 0xc000
	s_nop 0
	global_load_lds_dwordx4 v[220:221], off
	v_lshl_add_u64 v[220:221], s[68:69], 0, v[140:141]
	s_add_i32 m0, s29, 0xe000
	s_nop 0
	global_load_lds_dwordx4 v[220:221], off
	s_waitcnt vmcnt(8)
	s_waitcnt lgkmcnt(0)
	s_barrier
	s_setprio 1
	v_mfma_f32_16x16x32_bf16 v[124:127], v[146:149], v[188:191], v[124:127]
	v_mfma_f32_16x16x32_bf16 v[120:123], v[164:167], v[188:191], v[120:123]
	v_mfma_f32_16x16x32_bf16 v[108:111], v[146:149], v[196:199], v[108:111]
	v_mfma_f32_16x16x32_bf16 v[104:107], v[164:167], v[196:199], v[104:107]
	v_mfma_f32_16x16x32_bf16 v[92:95], v[146:149], v[204:207], v[92:95]
	v_mfma_f32_16x16x32_bf16 v[88:91], v[164:167], v[204:207], v[88:91]
	v_mfma_f32_16x16x32_bf16 v[76:79], v[146:149], v[212:215], v[76:79]
	v_mfma_f32_16x16x32_bf16 v[72:75], v[164:167], v[212:215], v[72:75]
	v_mfma_f32_16x16x32_bf16 v[124:127], v[160:163], v[192:195], v[124:127]
	v_mfma_f32_16x16x32_bf16 v[120:123], v[168:171], v[192:195], v[120:123]
	v_mfma_f32_16x16x32_bf16 v[108:111], v[160:163], v[200:203], v[108:111]
	v_mfma_f32_16x16x32_bf16 v[104:107], v[168:171], v[200:203], v[104:107]
	v_mfma_f32_16x16x32_bf16 v[92:95], v[160:163], v[208:211], v[92:95]
	v_mfma_f32_16x16x32_bf16 v[88:91], v[168:171], v[208:211], v[88:91]
	v_mfma_f32_16x16x32_bf16 v[76:79], v[160:163], v[216:219], v[76:79]
	v_mfma_f32_16x16x32_bf16 v[72:75], v[168:171], v[216:219], v[72:75]
	v_mfma_f32_16x16x32_bf16 v[116:119], v[172:175], v[188:191], v[116:119]
	v_mfma_f32_16x16x32_bf16 v[112:115], v[180:183], v[188:191], v[112:115]
	v_mfma_f32_16x16x32_bf16 v[100:103], v[172:175], v[196:199], v[100:103]
	v_mfma_f32_16x16x32_bf16 v[96:99], v[180:183], v[196:199], v[96:99]
	v_mfma_f32_16x16x32_bf16 v[84:87], v[172:175], v[204:207], v[84:87]
	v_mfma_f32_16x16x32_bf16 v[80:83], v[180:183], v[204:207], v[80:83]
	v_mfma_f32_16x16x32_bf16 v[68:71], v[172:175], v[212:215], v[68:71]
	v_mfma_f32_16x16x32_bf16 v[64:67], v[180:183], v[212:215], v[64:67]
	v_mfma_f32_16x16x32_bf16 v[116:119], v[176:179], v[192:195], v[116:119]
	v_mfma_f32_16x16x32_bf16 v[112:115], v[184:187], v[192:195], v[112:115]
	v_mfma_f32_16x16x32_bf16 v[100:103], v[176:179], v[200:203], v[100:103]
	v_mfma_f32_16x16x32_bf16 v[96:99], v[184:187], v[200:203], v[96:99]
	v_mfma_f32_16x16x32_bf16 v[84:87], v[176:179], v[208:211], v[84:87]
	v_mfma_f32_16x16x32_bf16 v[80:83], v[184:187], v[208:211], v[80:83]
	v_mfma_f32_16x16x32_bf16 v[68:71], v[176:179], v[216:219], v[68:71]
	v_mfma_f32_16x16x32_bf16 v[64:67], v[184:187], v[216:219], v[64:67]
	s_barrier
	s_setprio 0
	ds_read_b128 v[188:191], v157 offset:16384
	ds_read_b128 v[192:195], v157 offset:17408
	ds_read_b128 v[196:199], v157 offset:18432
	ds_read_b128 v[200:203], v157 offset:19456
	ds_read_b128 v[204:207], v157 offset:20480
	ds_read_b128 v[208:211], v157 offset:21504
	ds_read_b128 v[212:215], v157 offset:22528
	ds_read_b128 v[216:219], v157 offset:23552
	s_add_i32 s8, s67, s94
	v_lshl_add_u64 v[220:221], s[70:71], 0, v[130:131]
	s_mov_b32 m0, s8
	s_nop 0
	global_load_lds_dwordx4 v[220:221], off
	s_add_i32 m0, s8, 0x2000
	s_add_u32 s60, s70, 0x20000
	v_lshl_add_u64 v[222:223], s[70:71], 0, v[134:135]
	s_addc_u32 s61, s71, 0
	s_add_i32 s8, s74, s94
	global_load_lds_dwordx4 v[222:223], off
	v_lshl_add_u64 v[224:225], s[60:61], 0, v[130:131]
	s_mov_b32 m0, s8
	v_lshl_add_u64 v[226:227], s[72:73], 0, v[132:133]
	global_load_lds_dwordx4 v[224:225], off
	v_lshl_add_u64 v[224:225], s[60:61], 0, v[134:135]
	s_add_i32 m0, s8, 0x2000
	s_nop 0
	global_load_lds_dwordx4 v[224:225], off
	v_lshl_add_u64 v[224:225], s[72:73], 0, v[128:129]
	s_mov_b32 m0, s29
	s_nop 0
	global_load_lds_dwordx4 v[224:225], off
	s_mov_b32 m0, s30
	s_nop 0
	global_load_lds_dwordx4 v[226:227], off
	s_waitcnt vmcnt(8)
	s_waitcnt lgkmcnt(0)
	s_barrier
	s_setprio 1
	v_mfma_f32_16x16x32_bf16 v[60:63], v[146:149], v[188:191], v[60:63]
	v_mfma_f32_16x16x32_bf16 v[56:59], v[164:167], v[188:191], v[56:59]
	v_mfma_f32_16x16x32_bf16 v[44:47], v[146:149], v[196:199], v[44:47]
	v_mfma_f32_16x16x32_bf16 v[40:43], v[164:167], v[196:199], v[40:43]
	v_mfma_f32_16x16x32_bf16 v[28:31], v[146:149], v[204:207], v[28:31]
	v_mfma_f32_16x16x32_bf16 v[24:27], v[164:167], v[204:207], v[24:27]
	v_mfma_f32_16x16x32_bf16 v[12:15], v[146:149], v[212:215], v[12:15]
	v_mfma_f32_16x16x32_bf16 v[8:11], v[164:167], v[212:215], v[8:11]
	v_mfma_f32_16x16x32_bf16 v[60:63], v[160:163], v[192:195], v[60:63]
	v_mfma_f32_16x16x32_bf16 v[56:59], v[168:171], v[192:195], v[56:59]
	v_mfma_f32_16x16x32_bf16 v[44:47], v[160:163], v[200:203], v[44:47]
	v_mfma_f32_16x16x32_bf16 v[40:43], v[168:171], v[200:203], v[40:43]
	v_mfma_f32_16x16x32_bf16 v[28:31], v[160:163], v[208:211], v[28:31]
	v_mfma_f32_16x16x32_bf16 v[24:27], v[168:171], v[208:211], v[24:27]
	v_mfma_f32_16x16x32_bf16 v[12:15], v[160:163], v[216:219], v[12:15]
	v_mfma_f32_16x16x32_bf16 v[8:11], v[168:171], v[216:219], v[8:11]
	v_mfma_f32_16x16x32_bf16 v[52:55], v[172:175], v[188:191], v[52:55]
	v_mfma_f32_16x16x32_bf16 v[48:51], v[180:183], v[188:191], v[48:51]
	v_mfma_f32_16x16x32_bf16 v[36:39], v[172:175], v[196:199], v[36:39]
	v_mfma_f32_16x16x32_bf16 v[32:35], v[180:183], v[196:199], v[32:35]
	v_mfma_f32_16x16x32_bf16 v[20:23], v[172:175], v[204:207], v[20:23]
	v_mfma_f32_16x16x32_bf16 v[16:19], v[180:183], v[204:207], v[16:19]
	v_mfma_f32_16x16x32_bf16 v[4:7], v[172:175], v[212:215], v[4:7]
	v_mfma_f32_16x16x32_bf16 v[0:3], v[180:183], v[212:215], v[0:3]
	v_mfma_f32_16x16x32_bf16 v[52:55], v[176:179], v[192:195], v[52:55]
	v_mfma_f32_16x16x32_bf16 v[48:51], v[184:187], v[192:195], v[48:51]
	v_mfma_f32_16x16x32_bf16 v[36:39], v[176:179], v[200:203], v[36:39]
	v_mfma_f32_16x16x32_bf16 v[32:35], v[184:187], v[200:203], v[32:35]
	v_mfma_f32_16x16x32_bf16 v[20:23], v[176:179], v[208:211], v[20:23]
	v_mfma_f32_16x16x32_bf16 v[16:19], v[184:187], v[208:211], v[16:19]
	v_mfma_f32_16x16x32_bf16 v[4:7], v[176:179], v[216:219], v[4:7]
	v_mfma_f32_16x16x32_bf16 v[0:3], v[184:187], v[216:219], v[0:3]
	s_barrier
	s_setprio 0
	s_add_i32 s8, 0, 0x18000
	v_add_u32_e32 v159, s8, v151
	ds_read_b128 v[146:149], v159
	ds_read_b128 v[160:163], v159 offset:1024
	ds_read_b128 v[164:167], v159 offset:2048
	ds_read_b128 v[168:171], v159 offset:3072
	s_add_i32 s9, 0, 0x1c000
	v_add_u32_e32 v159, s9, v151
	ds_read_b128 v[172:175], v159
	ds_read_b128 v[176:179], v159 offset:1024
	ds_read_b128 v[180:183], v159 offset:2048
	ds_read_b128 v[184:187], v159 offset:3072
	ds_read_b128 v[188:191], v157 offset:32768
	ds_read_b128 v[192:195], v157 offset:33792
	ds_read_b128 v[196:199], v157 offset:34816
	ds_read_b128 v[200:203], v157 offset:35840
	ds_read_b128 v[204:207], v157 offset:36864
	ds_read_b128 v[208:211], v157 offset:37888
	ds_read_b128 v[212:215], v157 offset:38912
	ds_read_b128 v[216:219], v157 offset:39936
	s_add_u32 s60, s72, 0x60000
	s_addc_u32 s61, s73, 0
	s_mov_b32 m0, s34
	v_lshl_add_u64 v[228:229], s[60:61], 0, v[128:129]
	global_load_lds_dwordx4 v[228:229], off
	v_lshl_add_u64 v[228:229], s[60:61], 0, v[132:133]
	s_mov_b32 m0, s35
	s_nop 0
	global_load_lds_dwordx4 v[228:229], off
	s_waitcnt vmcnt(8)
	s_waitcnt lgkmcnt(0)
	s_barrier
	s_setprio 1
	v_mfma_f32_16x16x32_bf16 v[124:127], v[146:149], v[188:191], v[124:127]
	v_mfma_f32_16x16x32_bf16 v[120:123], v[164:167], v[188:191], v[120:123]
	v_mfma_f32_16x16x32_bf16 v[108:111], v[146:149], v[196:199], v[108:111]
	v_mfma_f32_16x16x32_bf16 v[104:107], v[164:167], v[196:199], v[104:107]
	v_mfma_f32_16x16x32_bf16 v[92:95], v[146:149], v[204:207], v[92:95]
	v_mfma_f32_16x16x32_bf16 v[88:91], v[164:167], v[204:207], v[88:91]
	v_mfma_f32_16x16x32_bf16 v[76:79], v[146:149], v[212:215], v[76:79]
	v_mfma_f32_16x16x32_bf16 v[72:75], v[164:167], v[212:215], v[72:75]
	v_mfma_f32_16x16x32_bf16 v[124:127], v[160:163], v[192:195], v[124:127]
	v_mfma_f32_16x16x32_bf16 v[120:123], v[168:171], v[192:195], v[120:123]
	v_mfma_f32_16x16x32_bf16 v[108:111], v[160:163], v[200:203], v[108:111]
	v_mfma_f32_16x16x32_bf16 v[104:107], v[168:171], v[200:203], v[104:107]
	v_mfma_f32_16x16x32_bf16 v[92:95], v[160:163], v[208:211], v[92:95]
	v_mfma_f32_16x16x32_bf16 v[88:91], v[168:171], v[208:211], v[88:91]
	v_mfma_f32_16x16x32_bf16 v[76:79], v[160:163], v[216:219], v[76:79]
	v_mfma_f32_16x16x32_bf16 v[72:75], v[168:171], v[216:219], v[72:75]
	v_mfma_f32_16x16x32_bf16 v[116:119], v[172:175], v[188:191], v[116:119]
	v_mfma_f32_16x16x32_bf16 v[112:115], v[180:183], v[188:191], v[112:115]
	v_mfma_f32_16x16x32_bf16 v[100:103], v[172:175], v[196:199], v[100:103]
	v_mfma_f32_16x16x32_bf16 v[96:99], v[180:183], v[196:199], v[96:99]
	v_mfma_f32_16x16x32_bf16 v[84:87], v[172:175], v[204:207], v[84:87]
	v_mfma_f32_16x16x32_bf16 v[80:83], v[180:183], v[204:207], v[80:83]
	v_mfma_f32_16x16x32_bf16 v[68:71], v[172:175], v[212:215], v[68:71]
	v_mfma_f32_16x16x32_bf16 v[64:67], v[180:183], v[212:215], v[64:67]
	v_mfma_f32_16x16x32_bf16 v[116:119], v[176:179], v[192:195], v[116:119]
	v_mfma_f32_16x16x32_bf16 v[112:115], v[184:187], v[192:195], v[112:115]
	v_mfma_f32_16x16x32_bf16 v[100:103], v[176:179], v[200:203], v[100:103]
	v_mfma_f32_16x16x32_bf16 v[96:99], v[184:187], v[200:203], v[96:99]
	v_mfma_f32_16x16x32_bf16 v[84:87], v[176:179], v[208:211], v[84:87]
	v_mfma_f32_16x16x32_bf16 v[80:83], v[184:187], v[208:211], v[80:83]
	v_mfma_f32_16x16x32_bf16 v[68:71], v[176:179], v[216:219], v[68:71]
	v_mfma_f32_16x16x32_bf16 v[64:67], v[184:187], v[216:219], v[64:67]
	s_barrier
	s_setprio 0
	ds_read_b128 v[188:191], v157 offset:49152
	ds_read_b128 v[192:195], v157 offset:50176
	ds_read_b128 v[196:199], v157 offset:51200
	ds_read_b128 v[200:203], v157 offset:52224
	ds_read_b128 v[204:207], v157 offset:53248
	ds_read_b128 v[208:211], v157 offset:54272
	ds_read_b128 v[212:215], v157 offset:55296
	ds_read_b128 v[216:219], v157 offset:56320
	s_add_i32 s8, s8, s94
	v_lshl_add_u64 v[220:221], v[220:221], 0, s[22:23]
	s_mov_b32 m0, s8
	s_nop 0
	global_load_lds_dwordx4 v[220:221], off
	s_add_i32 m0, s8, 0x2000
	s_add_u32 s60, s70, 0x20080
	v_lshl_add_u64 v[220:221], v[222:223], 0, s[22:23]
	s_addc_u32 s61, s71, 0
	s_add_i32 s8, s9, s94
	global_load_lds_dwordx4 v[220:221], off
	v_lshl_add_u64 v[220:221], s[60:61], 0, v[130:131]
	s_mov_b32 m0, s8
	s_nop 0
	global_load_lds_dwordx4 v[220:221], off
	v_lshl_add_u64 v[220:221], s[60:61], 0, v[134:135]
	s_add_i32 m0, s8, 0x2000
	s_nop 0
	global_load_lds_dwordx4 v[220:221], off
	v_lshl_add_u64 v[220:221], v[224:225], 0, s[22:23]
	s_mov_b32 m0, s56
	s_nop 0
	global_load_lds_dwordx4 v[220:221], off
	v_lshl_add_u64 v[220:221], v[226:227], 0, s[22:23]
	s_mov_b32 m0, s57
	s_nop 0
	global_load_lds_dwordx4 v[220:221], off
	s_waitcnt vmcnt(8)
	s_waitcnt lgkmcnt(0)
	s_barrier
	s_setprio 1
	v_mfma_f32_16x16x32_bf16 v[60:63], v[146:149], v[188:191], v[60:63]
	v_mfma_f32_16x16x32_bf16 v[56:59], v[164:167], v[188:191], v[56:59]
	v_mfma_f32_16x16x32_bf16 v[44:47], v[146:149], v[196:199], v[44:47]
	v_mfma_f32_16x16x32_bf16 v[40:43], v[164:167], v[196:199], v[40:43]
	v_mfma_f32_16x16x32_bf16 v[28:31], v[146:149], v[204:207], v[28:31]
	v_mfma_f32_16x16x32_bf16 v[24:27], v[164:167], v[204:207], v[24:27]
	v_mfma_f32_16x16x32_bf16 v[12:15], v[146:149], v[212:215], v[12:15]
	v_mfma_f32_16x16x32_bf16 v[8:11], v[164:167], v[212:215], v[8:11]
	v_mfma_f32_16x16x32_bf16 v[60:63], v[160:163], v[192:195], v[60:63]
	v_mfma_f32_16x16x32_bf16 v[56:59], v[168:171], v[192:195], v[56:59]
	v_mfma_f32_16x16x32_bf16 v[44:47], v[160:163], v[200:203], v[44:47]
	v_mfma_f32_16x16x32_bf16 v[40:43], v[168:171], v[200:203], v[40:43]
	v_mfma_f32_16x16x32_bf16 v[28:31], v[160:163], v[208:211], v[28:31]
	v_mfma_f32_16x16x32_bf16 v[24:27], v[168:171], v[208:211], v[24:27]
	v_mfma_f32_16x16x32_bf16 v[12:15], v[160:163], v[216:219], v[12:15]
	v_mfma_f32_16x16x32_bf16 v[8:11], v[168:171], v[216:219], v[8:11]
	v_mfma_f32_16x16x32_bf16 v[52:55], v[172:175], v[188:191], v[52:55]
	v_mfma_f32_16x16x32_bf16 v[48:51], v[180:183], v[188:191], v[48:51]
	v_mfma_f32_16x16x32_bf16 v[36:39], v[172:175], v[196:199], v[36:39]
	v_mfma_f32_16x16x32_bf16 v[32:35], v[180:183], v[196:199], v[32:35]
	v_mfma_f32_16x16x32_bf16 v[20:23], v[172:175], v[204:207], v[20:23]
	v_mfma_f32_16x16x32_bf16 v[16:19], v[180:183], v[204:207], v[16:19]
	v_mfma_f32_16x16x32_bf16 v[4:7], v[172:175], v[212:215], v[4:7]
	v_mfma_f32_16x16x32_bf16 v[0:3], v[180:183], v[212:215], v[0:3]
	v_mfma_f32_16x16x32_bf16 v[52:55], v[176:179], v[192:195], v[52:55]
	v_mfma_f32_16x16x32_bf16 v[48:51], v[184:187], v[192:195], v[48:51]
	v_mfma_f32_16x16x32_bf16 v[36:39], v[176:179], v[200:203], v[36:39]
	v_mfma_f32_16x16x32_bf16 v[32:35], v[184:187], v[200:203], v[32:35]
	v_mfma_f32_16x16x32_bf16 v[20:23], v[176:179], v[208:211], v[20:23]
	v_mfma_f32_16x16x32_bf16 v[16:19], v[184:187], v[208:211], v[16:19]
	v_mfma_f32_16x16x32_bf16 v[4:7], v[176:179], v[216:219], v[4:7]
	v_mfma_f32_16x16x32_bf16 v[0:3], v[184:187], v[216:219], v[0:3]
	s_barrier
	s_setprio 0
	s_add_i32 s80, s80, 2
	s_add_u32 s78, s78, 0x100
	s_addc_u32 s79, s79, 0
	s_cmp_gt_u32 s80, 5
	s_mov_b64 s[68:69], s[16:17]
	s_cbranch_scc0 .LBB0_2535
	s_and_b64 vcc, exec, s[58:59]
	s_cbranch_vccz .LBB0_2538
	s_barrier

.LBB0_2713:
	ds_read_b128 v[140:143], v149
	ds_read_b128 v[152:155], v149 offset:1024
	ds_read_b128 v[156:159], v149 offset:2048
	ds_read_b128 v[160:163], v149 offset:3072
	ds_read_b128 v[164:167], v150
	ds_read_b128 v[168:171], v150 offset:1024
	ds_read_b128 v[172:175], v150 offset:2048
	ds_read_b128 v[176:179], v150 offset:3072
	ds_read_b128 v[180:183], v151
	ds_read_b128 v[184:187], v151 offset:1024
	ds_read_b128 v[188:191], v151 offset:2048
	ds_read_b128 v[192:195], v151 offset:3072
	ds_read_b128 v[196:199], v151 offset:4096
	ds_read_b128 v[200:203], v151 offset:5120
	ds_read_b128 v[204:207], v151 offset:6144
	ds_read_b128 v[208:211], v151 offset:7168
	s_add_u32 s8, s62, 0xfff80080
	s_addc_u32 s9, s63, -1
	s_cmp_eq_u32 s72, 28
	s_cselect_b32 s67, s43, s9
	s_cselect_b32 s66, s57, s8
	s_cselect_b32 s65, s23, s71
	s_cselect_b32 s64, s69, s70
	v_lshl_add_u64 v[212:213], s[62:63], 0, v[132:133]
	s_add_i32 m0, s12, 0xc000
	s_nop 0
	global_load_lds_dwordx4 v[212:213], off
	v_lshl_add_u64 v[212:213], s[62:63], 0, v[134:135]
	s_add_i32 m0, s12, 0xe000
	s_nop 0
	global_load_lds_dwordx4 v[212:213], off
	s_waitcnt vmcnt(8)
	s_waitcnt lgkmcnt(0)
	s_barrier
	s_setprio 1
	v_mfma_f32_16x16x32_bf16 v[124:127], v[140:143], v[180:183], v[124:127]
	v_mfma_f32_16x16x32_bf16 v[120:123], v[156:159], v[180:183], v[120:123]
	v_mfma_f32_16x16x32_bf16 v[108:111], v[140:143], v[188:191], v[108:111]
	v_mfma_f32_16x16x32_bf16 v[104:107], v[156:159], v[188:191], v[104:107]
	v_mfma_f32_16x16x32_bf16 v[92:95], v[140:143], v[196:199], v[92:95]
	v_mfma_f32_16x16x32_bf16 v[88:91], v[156:159], v[196:199], v[88:91]
	v_mfma_f32_16x16x32_bf16 v[76:79], v[140:143], v[204:207], v[76:79]
	v_mfma_f32_16x16x32_bf16 v[72:75], v[156:159], v[204:207], v[72:75]
	v_mfma_f32_16x16x32_bf16 v[124:127], v[152:155], v[184:187], v[124:127]
	v_mfma_f32_16x16x32_bf16 v[120:123], v[160:163], v[184:187], v[120:123]
	v_mfma_f32_16x16x32_bf16 v[108:111], v[152:155], v[192:195], v[108:111]
	v_mfma_f32_16x16x32_bf16 v[104:107], v[160:163], v[192:195], v[104:107]
	v_mfma_f32_16x16x32_bf16 v[92:95], v[152:155], v[200:203], v[92:95]
	v_mfma_f32_16x16x32_bf16 v[88:91], v[160:163], v[200:203], v[88:91]
	v_mfma_f32_16x16x32_bf16 v[76:79], v[152:155], v[208:211], v[76:79]
	v_mfma_f32_16x16x32_bf16 v[72:75], v[160:163], v[208:211], v[72:75]
	v_mfma_f32_16x16x32_bf16 v[116:119], v[164:167], v[180:183], v[116:119]
	v_mfma_f32_16x16x32_bf16 v[112:115], v[172:175], v[180:183], v[112:115]
	v_mfma_f32_16x16x32_bf16 v[100:103], v[164:167], v[188:191], v[100:103]
	v_mfma_f32_16x16x32_bf16 v[96:99], v[172:175], v[188:191], v[96:99]
	v_mfma_f32_16x16x32_bf16 v[84:87], v[164:167], v[196:199], v[84:87]
	v_mfma_f32_16x16x32_bf16 v[80:83], v[172:175], v[196:199], v[80:83]
	v_mfma_f32_16x16x32_bf16 v[68:71], v[164:167], v[204:207], v[68:71]
	v_mfma_f32_16x16x32_bf16 v[64:67], v[172:175], v[204:207], v[64:67]
	v_mfma_f32_16x16x32_bf16 v[116:119], v[168:171], v[184:187], v[116:119]
	v_mfma_f32_16x16x32_bf16 v[112:115], v[176:179], v[184:187], v[112:115]
	v_mfma_f32_16x16x32_bf16 v[100:103], v[168:171], v[192:195], v[100:103]
	v_mfma_f32_16x16x32_bf16 v[96:99], v[176:179], v[192:195], v[96:99]
	v_mfma_f32_16x16x32_bf16 v[84:87], v[168:171], v[200:203], v[84:87]
	v_mfma_f32_16x16x32_bf16 v[80:83], v[176:179], v[200:203], v[80:83]
	v_mfma_f32_16x16x32_bf16 v[68:71], v[168:171], v[208:211], v[68:71]
	v_mfma_f32_16x16x32_bf16 v[64:67], v[176:179], v[208:211], v[64:67]
	s_barrier
	s_setprio 0
	ds_read_b128 v[180:183], v151 offset:16384
	ds_read_b128 v[184:187], v151 offset:17408
	ds_read_b128 v[188:191], v151 offset:18432
	ds_read_b128 v[192:195], v151 offset:19456
	ds_read_b128 v[196:199], v151 offset:20480
	ds_read_b128 v[200:203], v151 offset:21504
	ds_read_b128 v[204:207], v151 offset:22528
	ds_read_b128 v[208:211], v151 offset:23552
	s_add_i32 s8, s46, s94
	v_lshl_add_u64 v[212:213], s[64:65], 0, v[128:129]
	s_mov_b32 m0, s8
	s_nop 0
	global_load_lds_dwordx4 v[212:213], off
	s_add_i32 m0, s8, 0x2000
	s_add_u32 s60, s64, 0x80000
	v_lshl_add_u64 v[214:215], s[64:65], 0, v[130:131]
	s_addc_u32 s61, s65, 0
	s_add_i32 s8, s47, s94
	global_load_lds_dwordx4 v[214:215], off
	v_lshl_add_u64 v[216:217], s[60:61], 0, v[128:129]
	s_mov_b32 m0, s8
	v_lshl_add_u64 v[218:219], s[66:67], 0, v[130:131]
	global_load_lds_dwordx4 v[216:217], off
	v_lshl_add_u64 v[216:217], s[60:61], 0, v[130:131]
	s_add_i32 m0, s8, 0x2000
	s_nop 0
	global_load_lds_dwordx4 v[216:217], off
	v_lshl_add_u64 v[216:217], s[66:67], 0, v[128:129]
	s_mov_b32 m0, s12
	s_nop 0
	global_load_lds_dwordx4 v[216:217], off
	s_mov_b32 m0, s13
	s_nop 0
	global_load_lds_dwordx4 v[218:219], off
	s_waitcnt vmcnt(8)
	s_waitcnt lgkmcnt(0)
	s_barrier
	s_setprio 1
	v_mfma_f32_16x16x32_bf16 v[60:63], v[140:143], v[180:183], v[60:63]
	v_mfma_f32_16x16x32_bf16 v[56:59], v[156:159], v[180:183], v[56:59]
	v_mfma_f32_16x16x32_bf16 v[44:47], v[140:143], v[188:191], v[44:47]
	v_mfma_f32_16x16x32_bf16 v[40:43], v[156:159], v[188:191], v[40:43]
	v_mfma_f32_16x16x32_bf16 v[28:31], v[140:143], v[196:199], v[28:31]
	v_mfma_f32_16x16x32_bf16 v[24:27], v[156:159], v[196:199], v[24:27]
	v_mfma_f32_16x16x32_bf16 v[12:15], v[140:143], v[204:207], v[12:15]
	v_mfma_f32_16x16x32_bf16 v[8:11], v[156:159], v[204:207], v[8:11]
	v_mfma_f32_16x16x32_bf16 v[60:63], v[152:155], v[184:187], v[60:63]
	v_mfma_f32_16x16x32_bf16 v[56:59], v[160:163], v[184:187], v[56:59]
	v_mfma_f32_16x16x32_bf16 v[44:47], v[152:155], v[192:195], v[44:47]
	v_mfma_f32_16x16x32_bf16 v[40:43], v[160:163], v[192:195], v[40:43]
	v_mfma_f32_16x16x32_bf16 v[28:31], v[152:155], v[200:203], v[28:31]
	v_mfma_f32_16x16x32_bf16 v[24:27], v[160:163], v[200:203], v[24:27]
	v_mfma_f32_16x16x32_bf16 v[12:15], v[152:155], v[208:211], v[12:15]
	v_mfma_f32_16x16x32_bf16 v[8:11], v[160:163], v[208:211], v[8:11]
	v_mfma_f32_16x16x32_bf16 v[52:55], v[164:167], v[180:183], v[52:55]
	v_mfma_f32_16x16x32_bf16 v[48:51], v[172:175], v[180:183], v[48:51]
	v_mfma_f32_16x16x32_bf16 v[36:39], v[164:167], v[188:191], v[36:39]
	v_mfma_f32_16x16x32_bf16 v[32:35], v[172:175], v[188:191], v[32:35]
	v_mfma_f32_16x16x32_bf16 v[20:23], v[164:167], v[196:199], v[20:23]
	v_mfma_f32_16x16x32_bf16 v[16:19], v[172:175], v[196:199], v[16:19]
	v_mfma_f32_16x16x32_bf16 v[4:7], v[164:167], v[204:207], v[4:7]
	v_mfma_f32_16x16x32_bf16 v[0:3], v[172:175], v[204:207], v[0:3]
	v_mfma_f32_16x16x32_bf16 v[52:55], v[168:171], v[184:187], v[52:55]
	v_mfma_f32_16x16x32_bf16 v[48:51], v[176:179], v[184:187], v[48:51]
	v_mfma_f32_16x16x32_bf16 v[36:39], v[168:171], v[192:195], v[36:39]
	v_mfma_f32_16x16x32_bf16 v[32:35], v[176:179], v[192:195], v[32:35]
	v_mfma_f32_16x16x32_bf16 v[20:23], v[168:171], v[200:203], v[20:23]
	v_mfma_f32_16x16x32_bf16 v[16:19], v[176:179], v[200:203], v[16:19]
	v_mfma_f32_16x16x32_bf16 v[4:7], v[168:171], v[208:211], v[4:7]
	v_mfma_f32_16x16x32_bf16 v[0:3], v[176:179], v[208:211], v[0:3]
	s_barrier
	s_setprio 0
	s_add_i32 s8, 0, 0x18000
	s_add_i32 s9, 0, 0x1c000
	v_add_u32_e32 v160, s8, v145
	ds_read_b128 v[140:143], v160
	ds_read_b128 v[152:155], v160 offset:1024
	ds_read_b128 v[156:159], v160 offset:2048
	ds_read_b128 v[160:163], v160 offset:3072
	v_add_u32_e32 v176, s9, v145
	ds_read_b128 v[164:167], v176
	ds_read_b128 v[168:171], v176 offset:1024
	ds_read_b128 v[172:175], v176 offset:2048
	ds_read_b128 v[176:179], v176 offset:3072
	ds_read_b128 v[180:183], v151 offset:32768
	ds_read_b128 v[184:187], v151 offset:33792
	ds_read_b128 v[188:191], v151 offset:34816
	ds_read_b128 v[192:195], v151 offset:35840
	ds_read_b128 v[196:199], v151 offset:36864
	ds_read_b128 v[200:203], v151 offset:37888
	ds_read_b128 v[204:207], v151 offset:38912
	ds_read_b128 v[208:211], v151 offset:39936
	s_add_u32 s60, s66, 0x80000
	s_addc_u32 s61, s67, 0
	s_mov_b32 m0, s29
	v_lshl_add_u64 v[220:221], s[60:61], 0, v[128:129]
	global_load_lds_dwordx4 v[220:221], off
	v_lshl_add_u64 v[220:221], s[60:61], 0, v[130:131]
	s_mov_b32 m0, s30
	s_nop 0
	global_load_lds_dwordx4 v[220:221], off
	s_waitcnt vmcnt(8)
	s_waitcnt lgkmcnt(0)
	s_barrier
	s_setprio 1
	v_mfma_f32_16x16x32_bf16 v[124:127], v[140:143], v[180:183], v[124:127]
	v_mfma_f32_16x16x32_bf16 v[120:123], v[156:159], v[180:183], v[120:123]
	v_mfma_f32_16x16x32_bf16 v[108:111], v[140:143], v[188:191], v[108:111]
	v_mfma_f32_16x16x32_bf16 v[104:107], v[156:159], v[188:191], v[104:107]
	v_mfma_f32_16x16x32_bf16 v[92:95], v[140:143], v[196:199], v[92:95]
	v_mfma_f32_16x16x32_bf16 v[88:91], v[156:159], v[196:199], v[88:91]
	v_mfma_f32_16x16x32_bf16 v[76:79], v[140:143], v[204:207], v[76:79]
	v_mfma_f32_16x16x32_bf16 v[72:75], v[156:159], v[204:207], v[72:75]
	v_mfma_f32_16x16x32_bf16 v[124:127], v[152:155], v[184:187], v[124:127]
	v_mfma_f32_16x16x32_bf16 v[120:123], v[160:163], v[184:187], v[120:123]
	v_mfma_f32_16x16x32_bf16 v[108:111], v[152:155], v[192:195], v[108:111]
	v_mfma_f32_16x16x32_bf16 v[104:107], v[160:163], v[192:195], v[104:107]
	v_mfma_f32_16x16x32_bf16 v[92:95], v[152:155], v[200:203], v[92:95]
	v_mfma_f32_16x16x32_bf16 v[88:91], v[160:163], v[200:203], v[88:91]
	v_mfma_f32_16x16x32_bf16 v[76:79], v[152:155], v[208:211], v[76:79]
	v_mfma_f32_16x16x32_bf16 v[72:75], v[160:163], v[208:211], v[72:75]
	v_mfma_f32_16x16x32_bf16 v[116:119], v[164:167], v[180:183], v[116:119]
	v_mfma_f32_16x16x32_bf16 v[112:115], v[172:175], v[180:183], v[112:115]
	v_mfma_f32_16x16x32_bf16 v[100:103], v[164:167], v[188:191], v[100:103]
	v_mfma_f32_16x16x32_bf16 v[96:99], v[172:175], v[188:191], v[96:99]
	v_mfma_f32_16x16x32_bf16 v[84:87], v[164:167], v[196:199], v[84:87]
	v_mfma_f32_16x16x32_bf16 v[80:83], v[172:175], v[196:199], v[80:83]
	v_mfma_f32_16x16x32_bf16 v[68:71], v[164:167], v[204:207], v[68:71]
	v_mfma_f32_16x16x32_bf16 v[64:67], v[172:175], v[204:207], v[64:67]
	v_mfma_f32_16x16x32_bf16 v[116:119], v[168:171], v[184:187], v[116:119]
	v_mfma_f32_16x16x32_bf16 v[112:115], v[176:179], v[184:187], v[112:115]
	v_mfma_f32_16x16x32_bf16 v[100:103], v[168:171], v[192:195], v[100:103]
	v_mfma_f32_16x16x32_bf16 v[96:99], v[176:179], v[192:195], v[96:99]
	v_mfma_f32_16x16x32_bf16 v[84:87], v[168:171], v[200:203], v[84:87]
	v_mfma_f32_16x16x32_bf16 v[80:83], v[176:179], v[200:203], v[80:83]
	v_mfma_f32_16x16x32_bf16 v[68:71], v[168:171], v[208:211], v[68:71]
	v_mfma_f32_16x16x32_bf16 v[64:67], v[176:179], v[208:211], v[64:67]
	s_barrier
	s_setprio 0
	ds_read_b128 v[180:183], v151 offset:49152
	ds_read_b128 v[184:187], v151 offset:50176
	ds_read_b128 v[188:191], v151 offset:51200
	ds_read_b128 v[192:195], v151 offset:52224
	ds_read_b128 v[196:199], v151 offset:53248
	ds_read_b128 v[200:203], v151 offset:54272
	ds_read_b128 v[204:207], v151 offset:55296
	ds_read_b128 v[208:211], v151 offset:56320
	s_add_i32 s8, s8, s94
	v_lshl_add_u64 v[212:213], v[212:213], 0, s[20:21]
	s_mov_b32 m0, s8
	s_nop 0
	global_load_lds_dwordx4 v[212:213], off
	s_add_i32 m0, s8, 0x2000
	s_add_u32 s60, s64, 0x80080
	v_lshl_add_u64 v[212:213], v[214:215], 0, s[20:21]
	s_addc_u32 s61, s65, 0
	s_add_i32 s8, s9, s94
	global_load_lds_dwordx4 v[212:213], off
	v_lshl_add_u64 v[212:213], s[60:61], 0, v[128:129]
	s_mov_b32 m0, s8
	s_nop 0
	global_load_lds_dwordx4 v[212:213], off
	v_lshl_add_u64 v[212:213], s[60:61], 0, v[130:131]
	s_add_i32 m0, s8, 0x2000
	s_nop 0
	global_load_lds_dwordx4 v[212:213], off
	v_lshl_add_u64 v[212:213], v[216:217], 0, s[20:21]
	s_mov_b32 m0, s34
	s_nop 0
	global_load_lds_dwordx4 v[212:213], off
	v_lshl_add_u64 v[212:213], v[218:219], 0, s[20:21]
	s_mov_b32 m0, s35
	s_nop 0
	global_load_lds_dwordx4 v[212:213], off
	s_waitcnt vmcnt(8)
	s_waitcnt lgkmcnt(0)
	s_barrier
	s_setprio 1
	v_mfma_f32_16x16x32_bf16 v[60:63], v[140:143], v[180:183], v[60:63]
	v_mfma_f32_16x16x32_bf16 v[56:59], v[156:159], v[180:183], v[56:59]
	v_mfma_f32_16x16x32_bf16 v[44:47], v[140:143], v[188:191], v[44:47]
	v_mfma_f32_16x16x32_bf16 v[40:43], v[156:159], v[188:191], v[40:43]
	v_mfma_f32_16x16x32_bf16 v[28:31], v[140:143], v[196:199], v[28:31]
	v_mfma_f32_16x16x32_bf16 v[24:27], v[156:159], v[196:199], v[24:27]
	v_mfma_f32_16x16x32_bf16 v[12:15], v[140:143], v[204:207], v[12:15]
	v_mfma_f32_16x16x32_bf16 v[8:11], v[156:159], v[204:207], v[8:11]
	v_mfma_f32_16x16x32_bf16 v[60:63], v[152:155], v[184:187], v[60:63]
	v_mfma_f32_16x16x32_bf16 v[56:59], v[160:163], v[184:187], v[56:59]
	v_mfma_f32_16x16x32_bf16 v[44:47], v[152:155], v[192:195], v[44:47]
	v_mfma_f32_16x16x32_bf16 v[40:43], v[160:163], v[192:195], v[40:43]
	v_mfma_f32_16x16x32_bf16 v[28:31], v[152:155], v[200:203], v[28:31]
	v_mfma_f32_16x16x32_bf16 v[24:27], v[160:163], v[200:203], v[24:27]
	v_mfma_f32_16x16x32_bf16 v[12:15], v[152:155], v[208:211], v[12:15]
	v_mfma_f32_16x16x32_bf16 v[8:11], v[160:163], v[208:211], v[8:11]
	v_mfma_f32_16x16x32_bf16 v[52:55], v[164:167], v[180:183], v[52:55]
	v_mfma_f32_16x16x32_bf16 v[48:51], v[172:175], v[180:183], v[48:51]
	v_mfma_f32_16x16x32_bf16 v[36:39], v[164:167], v[188:191], v[36:39]
	v_mfma_f32_16x16x32_bf16 v[32:35], v[172:175], v[188:191], v[32:35]
	v_mfma_f32_16x16x32_bf16 v[20:23], v[164:167], v[196:199], v[20:23]
	v_mfma_f32_16x16x32_bf16 v[16:19], v[172:175], v[196:199], v[16:19]
	v_mfma_f32_16x16x32_bf16 v[4:7], v[164:167], v[204:207], v[4:7]
	v_mfma_f32_16x16x32_bf16 v[0:3], v[172:175], v[204:207], v[0:3]
	v_mfma_f32_16x16x32_bf16 v[52:55], v[168:171], v[184:187], v[52:55]
	v_mfma_f32_16x16x32_bf16 v[48:51], v[176:179], v[184:187], v[48:51]
	v_mfma_f32_16x16x32_bf16 v[36:39], v[168:171], v[192:195], v[36:39]
	v_mfma_f32_16x16x32_bf16 v[32:35], v[176:179], v[192:195], v[32:35]
	v_mfma_f32_16x16x32_bf16 v[20:23], v[168:171], v[200:203], v[20:23]
	v_mfma_f32_16x16x32_bf16 v[16:19], v[176:179], v[200:203], v[16:19]
	v_mfma_f32_16x16x32_bf16 v[4:7], v[168:171], v[208:211], v[4:7]
	v_mfma_f32_16x16x32_bf16 v[0:3], v[176:179], v[208:211], v[0:3]
	s_barrier
	s_setprio 0
	s_add_i32 s72, s72, 2
	s_add_u32 s62, s62, 0x100
	s_addc_u32 s63, s63, 0
	s_add_u32 s70, s70, 0x100
	s_addc_u32 s71, s71, 0
	s_cmp_gt_u32 s72, 29
	s_cbranch_scc0 .LBB0_2713
	s_and_b64 vcc, exec, s[58:59]
	s_cbranch_vccz .LBB0_2716
	s_barrier

.LBB0_2805:
	ds_read_b128 v[146:149], v155
	ds_read_b128 v[160:163], v155 offset:1024
	ds_read_b128 v[164:167], v155 offset:2048
	ds_read_b128 v[168:171], v155 offset:3072
	ds_read_b128 v[172:175], v156
	ds_read_b128 v[176:179], v156 offset:1024
	ds_read_b128 v[180:183], v156 offset:2048
	ds_read_b128 v[184:187], v156 offset:3072
	ds_read_b128 v[188:191], v157
	ds_read_b128 v[192:195], v157 offset:1024
	ds_read_b128 v[196:199], v157 offset:2048
	ds_read_b128 v[200:203], v157 offset:3072
	ds_read_b128 v[204:207], v157 offset:4096
	ds_read_b128 v[208:211], v157 offset:5120
	ds_read_b128 v[212:215], v157 offset:6144
	ds_read_b128 v[216:219], v157 offset:7168
	s_add_u32 s8, s48, 0xfff80080
	s_addc_u32 s9, s49, -1
	s_cmp_eq_u32 s67, 28
	s_cselect_b32 s61, s21, s9
	s_cselect_b32 s60, s43, s8
	s_cselect_b32 s57, s19, s66
	s_cselect_b32 s56, s45, s65
	v_lshl_add_u64 v[220:221], s[48:49], 0, v[138:139]
	s_add_i32 m0, s29, 0xc000
	s_nop 0
	global_load_lds_dwordx4 v[220:221], off
	v_lshl_add_u64 v[220:221], s[48:49], 0, v[140:141]
	s_add_i32 m0, s29, 0xe000
	s_nop 0
	global_load_lds_dwordx4 v[220:221], off
	s_waitcnt vmcnt(8)
	s_waitcnt lgkmcnt(0)
	s_barrier
	s_setprio 1
	v_mfma_f32_16x16x32_bf16 v[124:127], v[146:149], v[188:191], v[124:127]
	v_mfma_f32_16x16x32_bf16 v[120:123], v[164:167], v[188:191], v[120:123]
	v_mfma_f32_16x16x32_bf16 v[108:111], v[146:149], v[196:199], v[108:111]
	v_mfma_f32_16x16x32_bf16 v[104:107], v[164:167], v[196:199], v[104:107]
	v_mfma_f32_16x16x32_bf16 v[92:95], v[146:149], v[204:207], v[92:95]
	v_mfma_f32_16x16x32_bf16 v[88:91], v[164:167], v[204:207], v[88:91]
	v_mfma_f32_16x16x32_bf16 v[76:79], v[146:149], v[212:215], v[76:79]
	v_mfma_f32_16x16x32_bf16 v[72:75], v[164:167], v[212:215], v[72:75]
	v_mfma_f32_16x16x32_bf16 v[124:127], v[160:163], v[192:195], v[124:127]
	v_mfma_f32_16x16x32_bf16 v[120:123], v[168:171], v[192:195], v[120:123]
	v_mfma_f32_16x16x32_bf16 v[108:111], v[160:163], v[200:203], v[108:111]
	v_mfma_f32_16x16x32_bf16 v[104:107], v[168:171], v[200:203], v[104:107]
	v_mfma_f32_16x16x32_bf16 v[92:95], v[160:163], v[208:211], v[92:95]
	v_mfma_f32_16x16x32_bf16 v[88:91], v[168:171], v[208:211], v[88:91]
	v_mfma_f32_16x16x32_bf16 v[76:79], v[160:163], v[216:219], v[76:79]
	v_mfma_f32_16x16x32_bf16 v[72:75], v[168:171], v[216:219], v[72:75]
	v_mfma_f32_16x16x32_bf16 v[116:119], v[172:175], v[188:191], v[116:119]
	v_mfma_f32_16x16x32_bf16 v[112:115], v[180:183], v[188:191], v[112:115]
	v_mfma_f32_16x16x32_bf16 v[100:103], v[172:175], v[196:199], v[100:103]
	v_mfma_f32_16x16x32_bf16 v[96:99], v[180:183], v[196:199], v[96:99]
	v_mfma_f32_16x16x32_bf16 v[84:87], v[172:175], v[204:207], v[84:87]
	v_mfma_f32_16x16x32_bf16 v[80:83], v[180:183], v[204:207], v[80:83]
	v_mfma_f32_16x16x32_bf16 v[68:71], v[172:175], v[212:215], v[68:71]
	v_mfma_f32_16x16x32_bf16 v[64:67], v[180:183], v[212:215], v[64:67]
	v_mfma_f32_16x16x32_bf16 v[116:119], v[176:179], v[192:195], v[116:119]
	v_mfma_f32_16x16x32_bf16 v[112:115], v[184:187], v[192:195], v[112:115]
	v_mfma_f32_16x16x32_bf16 v[100:103], v[176:179], v[200:203], v[100:103]
	v_mfma_f32_16x16x32_bf16 v[96:99], v[184:187], v[200:203], v[96:99]
	v_mfma_f32_16x16x32_bf16 v[84:87], v[176:179], v[208:211], v[84:87]
	v_mfma_f32_16x16x32_bf16 v[80:83], v[184:187], v[208:211], v[80:83]
	v_mfma_f32_16x16x32_bf16 v[68:71], v[176:179], v[216:219], v[68:71]
	v_mfma_f32_16x16x32_bf16 v[64:67], v[184:187], v[216:219], v[64:67]
	s_barrier
	s_setprio 0
	ds_read_b128 v[188:191], v157 offset:16384
	ds_read_b128 v[192:195], v157 offset:17408
	ds_read_b128 v[196:199], v157 offset:18432
	ds_read_b128 v[200:203], v157 offset:19456
	ds_read_b128 v[204:207], v157 offset:20480
	ds_read_b128 v[208:211], v157 offset:21504
	ds_read_b128 v[212:215], v157 offset:22528
	ds_read_b128 v[216:219], v157 offset:23552
	s_add_i32 s8, s63, s94
	v_lshl_add_u64 v[220:221], s[56:57], 0, v[130:131]
	s_mov_b32 m0, s8
	s_nop 0
	global_load_lds_dwordx4 v[220:221], off
	s_add_i32 m0, s8, 0x2000
	s_add_u32 s68, s56, 0x80000
	v_lshl_add_u64 v[222:223], s[56:57], 0, v[134:135]
	s_addc_u32 s69, s57, 0
	s_add_i32 s8, s64, s94
	global_load_lds_dwordx4 v[222:223], off
	v_lshl_add_u64 v[224:225], s[68:69], 0, v[130:131]
	s_mov_b32 m0, s8
	v_lshl_add_u64 v[226:227], s[60:61], 0, v[132:133]
	global_load_lds_dwordx4 v[224:225], off
	v_lshl_add_u64 v[224:225], s[68:69], 0, v[134:135]
	s_add_i32 m0, s8, 0x2000
	s_nop 0
	global_load_lds_dwordx4 v[224:225], off
	v_lshl_add_u64 v[224:225], s[60:61], 0, v[128:129]
	s_mov_b32 m0, s29
	s_nop 0
	global_load_lds_dwordx4 v[224:225], off
	s_mov_b32 m0, s30
	s_nop 0
	global_load_lds_dwordx4 v[226:227], off
	s_waitcnt vmcnt(8)
	s_waitcnt lgkmcnt(0)
	s_barrier
	s_setprio 1
	v_mfma_f32_16x16x32_bf16 v[60:63], v[146:149], v[188:191], v[60:63]
	v_mfma_f32_16x16x32_bf16 v[56:59], v[164:167], v[188:191], v[56:59]
	v_mfma_f32_16x16x32_bf16 v[44:47], v[146:149], v[196:199], v[44:47]
	v_mfma_f32_16x16x32_bf16 v[40:43], v[164:167], v[196:199], v[40:43]
	v_mfma_f32_16x16x32_bf16 v[28:31], v[146:149], v[204:207], v[28:31]
	v_mfma_f32_16x16x32_bf16 v[24:27], v[164:167], v[204:207], v[24:27]
	v_mfma_f32_16x16x32_bf16 v[12:15], v[146:149], v[212:215], v[12:15]
	v_mfma_f32_16x16x32_bf16 v[8:11], v[164:167], v[212:215], v[8:11]
	v_mfma_f32_16x16x32_bf16 v[60:63], v[160:163], v[192:195], v[60:63]
	v_mfma_f32_16x16x32_bf16 v[56:59], v[168:171], v[192:195], v[56:59]
	v_mfma_f32_16x16x32_bf16 v[44:47], v[160:163], v[200:203], v[44:47]
	v_mfma_f32_16x16x32_bf16 v[40:43], v[168:171], v[200:203], v[40:43]
	v_mfma_f32_16x16x32_bf16 v[28:31], v[160:163], v[208:211], v[28:31]
	v_mfma_f32_16x16x32_bf16 v[24:27], v[168:171], v[208:211], v[24:27]
	v_mfma_f32_16x16x32_bf16 v[12:15], v[160:163], v[216:219], v[12:15]
	v_mfma_f32_16x16x32_bf16 v[8:11], v[168:171], v[216:219], v[8:11]
	v_mfma_f32_16x16x32_bf16 v[52:55], v[172:175], v[188:191], v[52:55]
	v_mfma_f32_16x16x32_bf16 v[48:51], v[180:183], v[188:191], v[48:51]
	v_mfma_f32_16x16x32_bf16 v[36:39], v[172:175], v[196:199], v[36:39]
	v_mfma_f32_16x16x32_bf16 v[32:35], v[180:183], v[196:199], v[32:35]
	v_mfma_f32_16x16x32_bf16 v[20:23], v[172:175], v[204:207], v[20:23]
	v_mfma_f32_16x16x32_bf16 v[16:19], v[180:183], v[204:207], v[16:19]
	v_mfma_f32_16x16x32_bf16 v[4:7], v[172:175], v[212:215], v[4:7]
	v_mfma_f32_16x16x32_bf16 v[0:3], v[180:183], v[212:215], v[0:3]
	v_mfma_f32_16x16x32_bf16 v[52:55], v[176:179], v[192:195], v[52:55]
	v_mfma_f32_16x16x32_bf16 v[48:51], v[184:187], v[192:195], v[48:51]
	v_mfma_f32_16x16x32_bf16 v[36:39], v[176:179], v[200:203], v[36:39]
	v_mfma_f32_16x16x32_bf16 v[32:35], v[184:187], v[200:203], v[32:35]
	v_mfma_f32_16x16x32_bf16 v[20:23], v[176:179], v[208:211], v[20:23]
	v_mfma_f32_16x16x32_bf16 v[16:19], v[184:187], v[208:211], v[16:19]
	v_mfma_f32_16x16x32_bf16 v[4:7], v[176:179], v[216:219], v[4:7]
	v_mfma_f32_16x16x32_bf16 v[0:3], v[184:187], v[216:219], v[0:3]
	s_barrier
	s_setprio 0
	s_add_i32 s8, 0, 0x18000
	v_add_u32_e32 v159, s8, v151
	ds_read_b128 v[146:149], v159
	ds_read_b128 v[160:163], v159 offset:1024
	ds_read_b128 v[164:167], v159 offset:2048
	ds_read_b128 v[168:171], v159 offset:3072
	s_add_i32 s9, 0, 0x1c000
	v_add_u32_e32 v159, s9, v151
	ds_read_b128 v[172:175], v159
	ds_read_b128 v[176:179], v159 offset:1024
	ds_read_b128 v[180:183], v159 offset:2048
	ds_read_b128 v[184:187], v159 offset:3072
	ds_read_b128 v[188:191], v157 offset:32768
	ds_read_b128 v[192:195], v157 offset:33792
	ds_read_b128 v[196:199], v157 offset:34816
	ds_read_b128 v[200:203], v157 offset:35840
	ds_read_b128 v[204:207], v157 offset:36864
	ds_read_b128 v[208:211], v157 offset:37888
	ds_read_b128 v[212:215], v157 offset:38912
	ds_read_b128 v[216:219], v157 offset:39936
	s_add_u32 s60, s60, 0x80000
	s_addc_u32 s61, s61, 0
	s_mov_b32 m0, s34
	v_lshl_add_u64 v[228:229], s[60:61], 0, v[128:129]
	global_load_lds_dwordx4 v[228:229], off
	v_lshl_add_u64 v[228:229], s[60:61], 0, v[132:133]
	s_mov_b32 m0, s35
	s_nop 0
	global_load_lds_dwordx4 v[228:229], off
	s_waitcnt vmcnt(8)
	s_waitcnt lgkmcnt(0)
	s_barrier
	s_setprio 1
	v_mfma_f32_16x16x32_bf16 v[124:127], v[146:149], v[188:191], v[124:127]
	v_mfma_f32_16x16x32_bf16 v[120:123], v[164:167], v[188:191], v[120:123]
	v_mfma_f32_16x16x32_bf16 v[108:111], v[146:149], v[196:199], v[108:111]
	v_mfma_f32_16x16x32_bf16 v[104:107], v[164:167], v[196:199], v[104:107]
	v_mfma_f32_16x16x32_bf16 v[92:95], v[146:149], v[204:207], v[92:95]
	v_mfma_f32_16x16x32_bf16 v[88:91], v[164:167], v[204:207], v[88:91]
	v_mfma_f32_16x16x32_bf16 v[76:79], v[146:149], v[212:215], v[76:79]
	v_mfma_f32_16x16x32_bf16 v[72:75], v[164:167], v[212:215], v[72:75]
	v_mfma_f32_16x16x32_bf16 v[124:127], v[160:163], v[192:195], v[124:127]
	v_mfma_f32_16x16x32_bf16 v[120:123], v[168:171], v[192:195], v[120:123]
	v_mfma_f32_16x16x32_bf16 v[108:111], v[160:163], v[200:203], v[108:111]
	v_mfma_f32_16x16x32_bf16 v[104:107], v[168:171], v[200:203], v[104:107]
	v_mfma_f32_16x16x32_bf16 v[92:95], v[160:163], v[208:211], v[92:95]
	v_mfma_f32_16x16x32_bf16 v[88:91], v[168:171], v[208:211], v[88:91]
	v_mfma_f32_16x16x32_bf16 v[76:79], v[160:163], v[216:219], v[76:79]
	v_mfma_f32_16x16x32_bf16 v[72:75], v[168:171], v[216:219], v[72:75]
	v_mfma_f32_16x16x32_bf16 v[116:119], v[172:175], v[188:191], v[116:119]
	v_mfma_f32_16x16x32_bf16 v[112:115], v[180:183], v[188:191], v[112:115]
	v_mfma_f32_16x16x32_bf16 v[100:103], v[172:175], v[196:199], v[100:103]
	v_mfma_f32_16x16x32_bf16 v[96:99], v[180:183], v[196:199], v[96:99]
	v_mfma_f32_16x16x32_bf16 v[84:87], v[172:175], v[204:207], v[84:87]
	v_mfma_f32_16x16x32_bf16 v[80:83], v[180:183], v[204:207], v[80:83]
	v_mfma_f32_16x16x32_bf16 v[68:71], v[172:175], v[212:215], v[68:71]
	v_mfma_f32_16x16x32_bf16 v[64:67], v[180:183], v[212:215], v[64:67]
	v_mfma_f32_16x16x32_bf16 v[116:119], v[176:179], v[192:195], v[116:119]
	v_mfma_f32_16x16x32_bf16 v[112:115], v[184:187], v[192:195], v[112:115]
	v_mfma_f32_16x16x32_bf16 v[100:103], v[176:179], v[200:203], v[100:103]
	v_mfma_f32_16x16x32_bf16 v[96:99], v[184:187], v[200:203], v[96:99]
	v_mfma_f32_16x16x32_bf16 v[84:87], v[176:179], v[208:211], v[84:87]
	v_mfma_f32_16x16x32_bf16 v[80:83], v[184:187], v[208:211], v[80:83]
	v_mfma_f32_16x16x32_bf16 v[68:71], v[176:179], v[216:219], v[68:71]
	v_mfma_f32_16x16x32_bf16 v[64:67], v[184:187], v[216:219], v[64:67]
	s_barrier
	s_setprio 0
	ds_read_b128 v[188:191], v157 offset:49152
	ds_read_b128 v[192:195], v157 offset:50176
	ds_read_b128 v[196:199], v157 offset:51200
	ds_read_b128 v[200:203], v157 offset:52224
	ds_read_b128 v[204:207], v157 offset:53248
	ds_read_b128 v[208:211], v157 offset:54272
	ds_read_b128 v[212:215], v157 offset:55296
	ds_read_b128 v[216:219], v157 offset:56320
	s_add_i32 s8, s8, s94
	v_lshl_add_u64 v[220:221], v[220:221], 0, s[16:17]
	s_mov_b32 m0, s8
	s_nop 0
	global_load_lds_dwordx4 v[220:221], off
	s_add_i32 m0, s8, 0x2000
	s_add_u32 s56, s56, 0x80080
	v_lshl_add_u64 v[220:221], v[222:223], 0, s[16:17]
	s_addc_u32 s57, s57, 0
	s_add_i32 s8, s9, s94
	global_load_lds_dwordx4 v[220:221], off
	v_lshl_add_u64 v[220:221], s[56:57], 0, v[130:131]
	s_mov_b32 m0, s8
	s_nop 0
	global_load_lds_dwordx4 v[220:221], off
	v_lshl_add_u64 v[220:221], s[56:57], 0, v[134:135]
	s_add_i32 m0, s8, 0x2000
	s_nop 0
	global_load_lds_dwordx4 v[220:221], off
	v_lshl_add_u64 v[220:221], v[224:225], 0, s[16:17]
	s_mov_b32 m0, s47
	s_nop 0
	global_load_lds_dwordx4 v[220:221], off
	v_lshl_add_u64 v[220:221], v[226:227], 0, s[16:17]
	s_mov_b32 m0, s62
	s_nop 0
	global_load_lds_dwordx4 v[220:221], off
	s_waitcnt vmcnt(8)
	s_waitcnt lgkmcnt(0)
	s_barrier
	s_setprio 1
	v_mfma_f32_16x16x32_bf16 v[60:63], v[146:149], v[188:191], v[60:63]
	v_mfma_f32_16x16x32_bf16 v[56:59], v[164:167], v[188:191], v[56:59]
	v_mfma_f32_16x16x32_bf16 v[44:47], v[146:149], v[196:199], v[44:47]
	v_mfma_f32_16x16x32_bf16 v[40:43], v[164:167], v[196:199], v[40:43]
	v_mfma_f32_16x16x32_bf16 v[28:31], v[146:149], v[204:207], v[28:31]
	v_mfma_f32_16x16x32_bf16 v[24:27], v[164:167], v[204:207], v[24:27]
	v_mfma_f32_16x16x32_bf16 v[12:15], v[146:149], v[212:215], v[12:15]
	v_mfma_f32_16x16x32_bf16 v[8:11], v[164:167], v[212:215], v[8:11]
	v_mfma_f32_16x16x32_bf16 v[60:63], v[160:163], v[192:195], v[60:63]
	v_mfma_f32_16x16x32_bf16 v[56:59], v[168:171], v[192:195], v[56:59]
	v_mfma_f32_16x16x32_bf16 v[44:47], v[160:163], v[200:203], v[44:47]
	v_mfma_f32_16x16x32_bf16 v[40:43], v[168:171], v[200:203], v[40:43]
	v_mfma_f32_16x16x32_bf16 v[28:31], v[160:163], v[208:211], v[28:31]
	v_mfma_f32_16x16x32_bf16 v[24:27], v[168:171], v[208:211], v[24:27]
	v_mfma_f32_16x16x32_bf16 v[12:15], v[160:163], v[216:219], v[12:15]
	v_mfma_f32_16x16x32_bf16 v[8:11], v[168:171], v[216:219], v[8:11]
	v_mfma_f32_16x16x32_bf16 v[52:55], v[172:175], v[188:191], v[52:55]
	v_mfma_f32_16x16x32_bf16 v[48:51], v[180:183], v[188:191], v[48:51]
	v_mfma_f32_16x16x32_bf16 v[36:39], v[172:175], v[196:199], v[36:39]
	v_mfma_f32_16x16x32_bf16 v[32:35], v[180:183], v[196:199], v[32:35]
	v_mfma_f32_16x16x32_bf16 v[20:23], v[172:175], v[204:207], v[20:23]
	v_mfma_f32_16x16x32_bf16 v[16:19], v[180:183], v[204:207], v[16:19]
	v_mfma_f32_16x16x32_bf16 v[4:7], v[172:175], v[212:215], v[4:7]
	v_mfma_f32_16x16x32_bf16 v[0:3], v[180:183], v[212:215], v[0:3]
	v_mfma_f32_16x16x32_bf16 v[52:55], v[176:179], v[192:195], v[52:55]
	v_mfma_f32_16x16x32_bf16 v[48:51], v[184:187], v[192:195], v[48:51]
	v_mfma_f32_16x16x32_bf16 v[36:39], v[176:179], v[200:203], v[36:39]
	v_mfma_f32_16x16x32_bf16 v[32:35], v[184:187], v[200:203], v[32:35]
	v_mfma_f32_16x16x32_bf16 v[20:23], v[176:179], v[208:211], v[20:23]
	v_mfma_f32_16x16x32_bf16 v[16:19], v[184:187], v[208:211], v[16:19]
	v_mfma_f32_16x16x32_bf16 v[4:7], v[176:179], v[216:219], v[4:7]
	v_mfma_f32_16x16x32_bf16 v[0:3], v[184:187], v[216:219], v[0:3]
	s_barrier
	s_setprio 0
	s_add_i32 s67, s67, 2
	s_add_u32 s48, s48, 0x100
	s_addc_u32 s49, s49, 0
	s_add_u32 s65, s65, 0x100
	s_addc_u32 s66, s66, 0
	s_cmp_gt_u32 s67, 29
	s_cbranch_scc0 .LBB0_2805
	s_and_b64 vcc, exec, s[58:59]
	s_cbranch_vccz .LBB0_2808
	s_barrier

.LBB0_2917:
	ds_read_b128 v[140:143], v149
	ds_read_b128 v[152:155], v149 offset:1024
	ds_read_b128 v[156:159], v149 offset:2048
	ds_read_b128 v[160:163], v149 offset:3072
	ds_read_b128 v[164:167], v150
	ds_read_b128 v[168:171], v150 offset:1024
	ds_read_b128 v[172:175], v150 offset:2048
	ds_read_b128 v[176:179], v150 offset:3072
	ds_read_b128 v[180:183], v151
	ds_read_b128 v[184:187], v151 offset:1024
	ds_read_b128 v[188:191], v151 offset:2048
	ds_read_b128 v[192:195], v151 offset:3072
	ds_read_b128 v[196:199], v151 offset:4096
	ds_read_b128 v[200:203], v151 offset:5120
	ds_read_b128 v[204:207], v151 offset:6144
	ds_read_b128 v[208:211], v151 offset:7168
	s_add_u32 s42, s40, 0xffe00080
	s_addc_u32 s43, s41, -1
	s_cmpk_eq_i32 s64, 0x7c
	s_cselect_b32 s45, s21, s43
	s_cselect_b32 s44, s39, s42
	s_cselect_b32 s43, s19, s63
	s_cselect_b32 s42, s61, s62
	v_lshl_add_u64 v[212:213], s[40:41], 0, v[132:133]
	s_add_i32 m0, s29, 0xc000
	s_nop 0
	global_load_lds_dwordx4 v[212:213], off
	v_lshl_add_u64 v[212:213], s[40:41], 0, v[134:135]
	s_add_i32 m0, s29, 0xe000
	s_nop 0
	global_load_lds_dwordx4 v[212:213], off
	s_waitcnt vmcnt(8)
	s_waitcnt lgkmcnt(0)
	s_barrier
	s_setprio 1
	v_mfma_f32_16x16x32_bf16 v[124:127], v[140:143], v[180:183], v[124:127]
	v_mfma_f32_16x16x32_bf16 v[120:123], v[156:159], v[180:183], v[120:123]
	v_mfma_f32_16x16x32_bf16 v[108:111], v[140:143], v[188:191], v[108:111]
	v_mfma_f32_16x16x32_bf16 v[104:107], v[156:159], v[188:191], v[104:107]
	v_mfma_f32_16x16x32_bf16 v[92:95], v[140:143], v[196:199], v[92:95]
	v_mfma_f32_16x16x32_bf16 v[88:91], v[156:159], v[196:199], v[88:91]
	v_mfma_f32_16x16x32_bf16 v[76:79], v[140:143], v[204:207], v[76:79]
	v_mfma_f32_16x16x32_bf16 v[72:75], v[156:159], v[204:207], v[72:75]
	v_mfma_f32_16x16x32_bf16 v[124:127], v[152:155], v[184:187], v[124:127]
	v_mfma_f32_16x16x32_bf16 v[120:123], v[160:163], v[184:187], v[120:123]
	v_mfma_f32_16x16x32_bf16 v[108:111], v[152:155], v[192:195], v[108:111]
	v_mfma_f32_16x16x32_bf16 v[104:107], v[160:163], v[192:195], v[104:107]
	v_mfma_f32_16x16x32_bf16 v[92:95], v[152:155], v[200:203], v[92:95]
	v_mfma_f32_16x16x32_bf16 v[88:91], v[160:163], v[200:203], v[88:91]
	v_mfma_f32_16x16x32_bf16 v[76:79], v[152:155], v[208:211], v[76:79]
	v_mfma_f32_16x16x32_bf16 v[72:75], v[160:163], v[208:211], v[72:75]
	v_mfma_f32_16x16x32_bf16 v[116:119], v[164:167], v[180:183], v[116:119]
	v_mfma_f32_16x16x32_bf16 v[112:115], v[172:175], v[180:183], v[112:115]
	v_mfma_f32_16x16x32_bf16 v[100:103], v[164:167], v[188:191], v[100:103]
	v_mfma_f32_16x16x32_bf16 v[96:99], v[172:175], v[188:191], v[96:99]
	v_mfma_f32_16x16x32_bf16 v[84:87], v[164:167], v[196:199], v[84:87]
	v_mfma_f32_16x16x32_bf16 v[80:83], v[172:175], v[196:199], v[80:83]
	v_mfma_f32_16x16x32_bf16 v[68:71], v[164:167], v[204:207], v[68:71]
	v_mfma_f32_16x16x32_bf16 v[64:67], v[172:175], v[204:207], v[64:67]
	v_mfma_f32_16x16x32_bf16 v[116:119], v[168:171], v[184:187], v[116:119]
	v_mfma_f32_16x16x32_bf16 v[112:115], v[176:179], v[184:187], v[112:115]
	v_mfma_f32_16x16x32_bf16 v[100:103], v[168:171], v[192:195], v[100:103]
	v_mfma_f32_16x16x32_bf16 v[96:99], v[176:179], v[192:195], v[96:99]
	v_mfma_f32_16x16x32_bf16 v[84:87], v[168:171], v[200:203], v[84:87]
	v_mfma_f32_16x16x32_bf16 v[80:83], v[176:179], v[200:203], v[80:83]
	v_mfma_f32_16x16x32_bf16 v[68:71], v[168:171], v[208:211], v[68:71]
	v_mfma_f32_16x16x32_bf16 v[64:67], v[176:179], v[208:211], v[64:67]
	s_barrier
	s_setprio 0
	ds_read_b128 v[180:183], v151 offset:16384
	ds_read_b128 v[184:187], v151 offset:17408
	ds_read_b128 v[188:191], v151 offset:18432
	ds_read_b128 v[192:195], v151 offset:19456
	ds_read_b128 v[196:199], v151 offset:20480
	ds_read_b128 v[200:203], v151 offset:21504
	ds_read_b128 v[204:207], v151 offset:22528
	ds_read_b128 v[208:211], v151 offset:23552
	s_add_i32 s65, s56, s94
	v_lshl_add_u64 v[212:213], s[42:43], 0, v[128:129]
	s_mov_b32 m0, s65
	s_nop 0
	global_load_lds_dwordx4 v[212:213], off
	s_add_i32 m0, s65, 0x2000
	s_add_u32 s66, s42, 0x200000
	v_lshl_add_u64 v[214:215], s[42:43], 0, v[130:131]
	s_addc_u32 s67, s43, 0
	s_add_i32 s65, s57, s94
	global_load_lds_dwordx4 v[214:215], off
	v_lshl_add_u64 v[216:217], s[66:67], 0, v[128:129]
	s_mov_b32 m0, s65
	v_lshl_add_u64 v[218:219], s[44:45], 0, v[130:131]
	global_load_lds_dwordx4 v[216:217], off
	v_lshl_add_u64 v[216:217], s[66:67], 0, v[130:131]
	s_add_i32 m0, s65, 0x2000
	s_nop 0
	global_load_lds_dwordx4 v[216:217], off
	v_lshl_add_u64 v[216:217], s[44:45], 0, v[128:129]
	s_mov_b32 m0, s29
	s_nop 0
	global_load_lds_dwordx4 v[216:217], off
	s_mov_b32 m0, s30
	s_nop 0
	global_load_lds_dwordx4 v[218:219], off
	s_waitcnt vmcnt(8)
	s_waitcnt lgkmcnt(0)
	s_barrier
	s_setprio 1
	v_mfma_f32_16x16x32_bf16 v[60:63], v[140:143], v[180:183], v[60:63]
	v_mfma_f32_16x16x32_bf16 v[56:59], v[156:159], v[180:183], v[56:59]
	v_mfma_f32_16x16x32_bf16 v[44:47], v[140:143], v[188:191], v[44:47]
	v_mfma_f32_16x16x32_bf16 v[40:43], v[156:159], v[188:191], v[40:43]
	v_mfma_f32_16x16x32_bf16 v[28:31], v[140:143], v[196:199], v[28:31]
	v_mfma_f32_16x16x32_bf16 v[24:27], v[156:159], v[196:199], v[24:27]
	v_mfma_f32_16x16x32_bf16 v[12:15], v[140:143], v[204:207], v[12:15]
	v_mfma_f32_16x16x32_bf16 v[8:11], v[156:159], v[204:207], v[8:11]
	v_mfma_f32_16x16x32_bf16 v[60:63], v[152:155], v[184:187], v[60:63]
	v_mfma_f32_16x16x32_bf16 v[56:59], v[160:163], v[184:187], v[56:59]
	v_mfma_f32_16x16x32_bf16 v[44:47], v[152:155], v[192:195], v[44:47]
	v_mfma_f32_16x16x32_bf16 v[40:43], v[160:163], v[192:195], v[40:43]
	v_mfma_f32_16x16x32_bf16 v[28:31], v[152:155], v[200:203], v[28:31]
	v_mfma_f32_16x16x32_bf16 v[24:27], v[160:163], v[200:203], v[24:27]
	v_mfma_f32_16x16x32_bf16 v[12:15], v[152:155], v[208:211], v[12:15]
	v_mfma_f32_16x16x32_bf16 v[8:11], v[160:163], v[208:211], v[8:11]
	v_mfma_f32_16x16x32_bf16 v[52:55], v[164:167], v[180:183], v[52:55]
	v_mfma_f32_16x16x32_bf16 v[48:51], v[172:175], v[180:183], v[48:51]
	v_mfma_f32_16x16x32_bf16 v[36:39], v[164:167], v[188:191], v[36:39]
	v_mfma_f32_16x16x32_bf16 v[32:35], v[172:175], v[188:191], v[32:35]
	v_mfma_f32_16x16x32_bf16 v[20:23], v[164:167], v[196:199], v[20:23]
	v_mfma_f32_16x16x32_bf16 v[16:19], v[172:175], v[196:199], v[16:19]
	v_mfma_f32_16x16x32_bf16 v[4:7], v[164:167], v[204:207], v[4:7]
	v_mfma_f32_16x16x32_bf16 v[0:3], v[172:175], v[204:207], v[0:3]
	v_mfma_f32_16x16x32_bf16 v[52:55], v[168:171], v[184:187], v[52:55]
	v_mfma_f32_16x16x32_bf16 v[48:51], v[176:179], v[184:187], v[48:51]
	v_mfma_f32_16x16x32_bf16 v[36:39], v[168:171], v[192:195], v[36:39]
	v_mfma_f32_16x16x32_bf16 v[32:35], v[176:179], v[192:195], v[32:35]
	v_mfma_f32_16x16x32_bf16 v[20:23], v[168:171], v[200:203], v[20:23]
	v_mfma_f32_16x16x32_bf16 v[16:19], v[176:179], v[200:203], v[16:19]
	v_mfma_f32_16x16x32_bf16 v[4:7], v[168:171], v[208:211], v[4:7]
	v_mfma_f32_16x16x32_bf16 v[0:3], v[176:179], v[208:211], v[0:3]
	s_barrier
	s_setprio 0
	s_add_i32 s65, 0, 0x18000
	s_add_i32 s66, 0, 0x1c000
	v_add_u32_e32 v160, s65, v145
	ds_read_b128 v[140:143], v160
	ds_read_b128 v[152:155], v160 offset:1024
	ds_read_b128 v[156:159], v160 offset:2048
	ds_read_b128 v[160:163], v160 offset:3072
	v_add_u32_e32 v176, s66, v145
	ds_read_b128 v[164:167], v176
	ds_read_b128 v[168:171], v176 offset:1024
	ds_read_b128 v[172:175], v176 offset:2048
	ds_read_b128 v[176:179], v176 offset:3072
	ds_read_b128 v[180:183], v151 offset:32768
	ds_read_b128 v[184:187], v151 offset:33792
	ds_read_b128 v[188:191], v151 offset:34816
	ds_read_b128 v[192:195], v151 offset:35840
	ds_read_b128 v[196:199], v151 offset:36864
	ds_read_b128 v[200:203], v151 offset:37888
	ds_read_b128 v[204:207], v151 offset:38912
	ds_read_b128 v[208:211], v151 offset:39936
	s_add_u32 s44, s44, 0x200000
	s_addc_u32 s45, s45, 0
	s_mov_b32 m0, s46
	v_lshl_add_u64 v[220:221], s[44:45], 0, v[128:129]
	global_load_lds_dwordx4 v[220:221], off
	v_lshl_add_u64 v[220:221], s[44:45], 0, v[130:131]
	s_mov_b32 m0, s47
	s_nop 0
	global_load_lds_dwordx4 v[220:221], off
	s_waitcnt vmcnt(8)
	s_waitcnt lgkmcnt(0)
	s_barrier
	s_setprio 1
	v_mfma_f32_16x16x32_bf16 v[124:127], v[140:143], v[180:183], v[124:127]
	v_mfma_f32_16x16x32_bf16 v[120:123], v[156:159], v[180:183], v[120:123]
	v_mfma_f32_16x16x32_bf16 v[108:111], v[140:143], v[188:191], v[108:111]
	v_mfma_f32_16x16x32_bf16 v[104:107], v[156:159], v[188:191], v[104:107]
	v_mfma_f32_16x16x32_bf16 v[92:95], v[140:143], v[196:199], v[92:95]
	v_mfma_f32_16x16x32_bf16 v[88:91], v[156:159], v[196:199], v[88:91]
	v_mfma_f32_16x16x32_bf16 v[76:79], v[140:143], v[204:207], v[76:79]
	v_mfma_f32_16x16x32_bf16 v[72:75], v[156:159], v[204:207], v[72:75]
	v_mfma_f32_16x16x32_bf16 v[124:127], v[152:155], v[184:187], v[124:127]
	v_mfma_f32_16x16x32_bf16 v[120:123], v[160:163], v[184:187], v[120:123]
	v_mfma_f32_16x16x32_bf16 v[108:111], v[152:155], v[192:195], v[108:111]
	v_mfma_f32_16x16x32_bf16 v[104:107], v[160:163], v[192:195], v[104:107]
	v_mfma_f32_16x16x32_bf16 v[92:95], v[152:155], v[200:203], v[92:95]
	v_mfma_f32_16x16x32_bf16 v[88:91], v[160:163], v[200:203], v[88:91]
	v_mfma_f32_16x16x32_bf16 v[76:79], v[152:155], v[208:211], v[76:79]
	v_mfma_f32_16x16x32_bf16 v[72:75], v[160:163], v[208:211], v[72:75]
	v_mfma_f32_16x16x32_bf16 v[116:119], v[164:167], v[180:183], v[116:119]
	v_mfma_f32_16x16x32_bf16 v[112:115], v[172:175], v[180:183], v[112:115]
	v_mfma_f32_16x16x32_bf16 v[100:103], v[164:167], v[188:191], v[100:103]
	v_mfma_f32_16x16x32_bf16 v[96:99], v[172:175], v[188:191], v[96:99]
	v_mfma_f32_16x16x32_bf16 v[84:87], v[164:167], v[196:199], v[84:87]
	v_mfma_f32_16x16x32_bf16 v[80:83], v[172:175], v[196:199], v[80:83]
	v_mfma_f32_16x16x32_bf16 v[68:71], v[164:167], v[204:207], v[68:71]
	v_mfma_f32_16x16x32_bf16 v[64:67], v[172:175], v[204:207], v[64:67]
	v_mfma_f32_16x16x32_bf16 v[116:119], v[168:171], v[184:187], v[116:119]
	v_mfma_f32_16x16x32_bf16 v[112:115], v[176:179], v[184:187], v[112:115]
	v_mfma_f32_16x16x32_bf16 v[100:103], v[168:171], v[192:195], v[100:103]
	v_mfma_f32_16x16x32_bf16 v[96:99], v[176:179], v[192:195], v[96:99]
	v_mfma_f32_16x16x32_bf16 v[84:87], v[168:171], v[200:203], v[84:87]
	v_mfma_f32_16x16x32_bf16 v[80:83], v[176:179], v[200:203], v[80:83]
	v_mfma_f32_16x16x32_bf16 v[68:71], v[168:171], v[208:211], v[68:71]
	v_mfma_f32_16x16x32_bf16 v[64:67], v[176:179], v[208:211], v[64:67]
	s_barrier
	s_setprio 0
	ds_read_b128 v[180:183], v151 offset:49152
	ds_read_b128 v[184:187], v151 offset:50176
	ds_read_b128 v[188:191], v151 offset:51200
	ds_read_b128 v[192:195], v151 offset:52224
	ds_read_b128 v[196:199], v151 offset:53248
	ds_read_b128 v[200:203], v151 offset:54272
	ds_read_b128 v[204:207], v151 offset:55296
	ds_read_b128 v[208:211], v151 offset:56320
	s_add_i32 s44, s65, s94
	v_lshl_add_u64 v[212:213], v[212:213], 0, s[16:17]
	s_mov_b32 m0, s44
	s_nop 0
	global_load_lds_dwordx4 v[212:213], off
	s_add_i32 m0, s44, 0x2000
	s_add_u32 s42, s42, 0x200080
	v_lshl_add_u64 v[212:213], v[214:215], 0, s[16:17]
	s_addc_u32 s43, s43, 0
	s_add_i32 s44, s66, s94
	global_load_lds_dwordx4 v[212:213], off
	v_lshl_add_u64 v[212:213], s[42:43], 0, v[128:129]
	s_mov_b32 m0, s44
	s_nop 0
	global_load_lds_dwordx4 v[212:213], off
	v_lshl_add_u64 v[212:213], s[42:43], 0, v[130:131]
	s_add_i32 m0, s44, 0x2000
	s_nop 0
	global_load_lds_dwordx4 v[212:213], off
	v_lshl_add_u64 v[212:213], v[216:217], 0, s[16:17]
	s_mov_b32 m0, s48
	s_nop 0
	global_load_lds_dwordx4 v[212:213], off
	v_lshl_add_u64 v[212:213], v[218:219], 0, s[16:17]
	s_mov_b32 m0, s49
	s_nop 0
	global_load_lds_dwordx4 v[212:213], off
	s_waitcnt vmcnt(8)
	s_waitcnt lgkmcnt(0)
	s_barrier
	s_setprio 1
	v_mfma_f32_16x16x32_bf16 v[60:63], v[140:143], v[180:183], v[60:63]
	v_mfma_f32_16x16x32_bf16 v[56:59], v[156:159], v[180:183], v[56:59]
	v_mfma_f32_16x16x32_bf16 v[44:47], v[140:143], v[188:191], v[44:47]
	v_mfma_f32_16x16x32_bf16 v[40:43], v[156:159], v[188:191], v[40:43]
	v_mfma_f32_16x16x32_bf16 v[28:31], v[140:143], v[196:199], v[28:31]
	v_mfma_f32_16x16x32_bf16 v[24:27], v[156:159], v[196:199], v[24:27]
	v_mfma_f32_16x16x32_bf16 v[12:15], v[140:143], v[204:207], v[12:15]
	v_mfma_f32_16x16x32_bf16 v[8:11], v[156:159], v[204:207], v[8:11]
	v_mfma_f32_16x16x32_bf16 v[60:63], v[152:155], v[184:187], v[60:63]
	v_mfma_f32_16x16x32_bf16 v[56:59], v[160:163], v[184:187], v[56:59]
	v_mfma_f32_16x16x32_bf16 v[44:47], v[152:155], v[192:195], v[44:47]
	v_mfma_f32_16x16x32_bf16 v[40:43], v[160:163], v[192:195], v[40:43]
	v_mfma_f32_16x16x32_bf16 v[28:31], v[152:155], v[200:203], v[28:31]
	v_mfma_f32_16x16x32_bf16 v[24:27], v[160:163], v[200:203], v[24:27]
	v_mfma_f32_16x16x32_bf16 v[12:15], v[152:155], v[208:211], v[12:15]
	v_mfma_f32_16x16x32_bf16 v[8:11], v[160:163], v[208:211], v[8:11]
	v_mfma_f32_16x16x32_bf16 v[52:55], v[164:167], v[180:183], v[52:55]
	v_mfma_f32_16x16x32_bf16 v[48:51], v[172:175], v[180:183], v[48:51]
	v_mfma_f32_16x16x32_bf16 v[36:39], v[164:167], v[188:191], v[36:39]
	v_mfma_f32_16x16x32_bf16 v[32:35], v[172:175], v[188:191], v[32:35]
	v_mfma_f32_16x16x32_bf16 v[20:23], v[164:167], v[196:199], v[20:23]
	v_mfma_f32_16x16x32_bf16 v[16:19], v[172:175], v[196:199], v[16:19]
	v_mfma_f32_16x16x32_bf16 v[4:7], v[164:167], v[204:207], v[4:7]
	v_mfma_f32_16x16x32_bf16 v[0:3], v[172:175], v[204:207], v[0:3]
	v_mfma_f32_16x16x32_bf16 v[52:55], v[168:171], v[184:187], v[52:55]
	v_mfma_f32_16x16x32_bf16 v[48:51], v[176:179], v[184:187], v[48:51]
	v_mfma_f32_16x16x32_bf16 v[36:39], v[168:171], v[192:195], v[36:39]
	v_mfma_f32_16x16x32_bf16 v[32:35], v[176:179], v[192:195], v[32:35]
	v_mfma_f32_16x16x32_bf16 v[20:23], v[168:171], v[200:203], v[20:23]
	v_mfma_f32_16x16x32_bf16 v[16:19], v[176:179], v[200:203], v[16:19]
	v_mfma_f32_16x16x32_bf16 v[4:7], v[168:171], v[208:211], v[4:7]
	v_mfma_f32_16x16x32_bf16 v[0:3], v[176:179], v[208:211], v[0:3]
	s_barrier
	s_setprio 0
	s_add_i32 s64, s64, 2
	s_add_u32 s40, s40, 0x100
	s_addc_u32 s41, s41, 0
	s_add_u32 s62, s62, 0x100
	s_addc_u32 s63, s63, 0
	s_cmpk_gt_u32 s64, 0x7d
	s_cbranch_scc0 .LBB0_2917
	s_and_b64 vcc, exec, s[58:59]
	s_cbranch_vccz .LBB0_2920
	s_barrier
